# GLU epilogue de-serialised (bias once, z prefetched one block ahead); every hand-written counted vmcnt wait (attention first two tiles, GLU epilogue, final_norm pipeline) now counts only the loads iss
# speedup vs baseline: 1.0045x; 1.0041x over previous
; __device__ __forceinline__ unsigned cvt_pk_bf16(float lo, float hi) { const f32x2 v = {lo, hi}; return __builtin_bit_cast(unsigned, __builtin_convertvector(v, bf16x2_t)); }
; __device__ __forceinline__ float bf_lo(unsigned w) { return __uint_as_float(w << 16); }
; __device__ __forceinline__ float bf_hi(unsigned w) { return __uint_as_float(w & 0xffff0000u); }
; __device__ __forceinline__ float fast_sigmoid(float v) { return __builtin_amdgcn_rcpf(1.0f + __builtin_amdgcn_exp2f(-1.4426950408889634f * v)); }
; #define ssq2 ((float*)(WSPTR() + WS_SSQ2))
;     __device__ __forceinline__ void operator()(const f32x4 (&acc)[2][2][4][2], const Unit& u, int wr, int wc, int fr, int fq) const {
;     ...
;         for (int ai = 0; ai < 2; ++ai)
; #pragma unroll
;             for (int m = 0; m < 4; ++m) {
;                 const int row = row0 + ai * HALF + m * 16;
;                 float ss = 0.f;
; #pragma unroll
;                 for (int bj = 0; bj < 2; ++bj) {
;                     const int c0 = u.pn * BM + bj * HALF + wc * 32 + 8 * fq;
;                     const u32x4 zw = *(const u32x4*)(z + (size_t)row * 512 + c0);
;                     const f32x4 b0 = *(const f32x4*)(bglu + c0), b1 = *(const f32x4*)(bglu + c0 + 4);
;                     const f32x4 a0 = acc[ai][bj][m][0] + b0, a1 = acc[ai][bj][m][1] + b1;
;                     float o[8];
;                     o[0] = bf_lo(zw.x) * fast_sigmoid(a0[0]); o[1] = bf_hi(zw.x) * fast_sigmoid(a0[1]);
;                     o[2] = bf_lo(zw.y) * fast_sigmoid(a0[2]); o[3] = bf_hi(zw.y) * fast_sigmoid(a0[3]);
;                     o[4] = bf_lo(zw.z) * fast_sigmoid(a1[0]); o[5] = bf_hi(zw.z) * fast_sigmoid(a1[1]);
;                     o[6] = bf_lo(zw.w) * fast_sigmoid(a1[2]); o[7] = bf_hi(zw.w) * fast_sigmoid(a1[3]);
; #pragma unroll
;                     for (int j = 0; j < 8; ++j) ss += o[j] * o[j];
;                     u32x4 w; w.x = cvt_pk_bf16(o[0], o[1]); w.y = cvt_pk_bf16(o[2], o[3]); w.z = cvt_pk_bf16(o[4], o[5]); w.w = cvt_pk_bf16(o[6], o[7]);
;                     *(u32x4*)(s + (size_t)row * 1024 + 512 + c0) = w;
;                 }
;                 ss += __shfl_xor(ss, 16); ss += __shfl_xor(ss, 32); if (fq == 0) ssq2[((size_t)u.pn * 32768 + row) * 4 + wc] = ss;
;             }
.LBB0_592:
	s_or_b64 exec, exec, s[22:23]
	s_mov_b32 s100, 0x8000
	s_mov_b32 s101, 0
	v_lshl_add_u64 v[228:229], v[226:227], 0, s[100:101]
	global_load_dwordx4 v[200:203], v[228:229], off
	global_load_dwordx4 v[204:207], v[228:229], off offset:256
	s_waitcnt vmcnt(2)
	v_or_b32_e32 v114, 16, v144
	s_waitcnt lgkmcnt(0)
	v_ashrrev_i32_e32 v115, 31, v114
	v_lshlrev_b64 v[128:129], 10, v[114:115]
	v_lshl_add_u64 v[128:129], s[76:77], 0, v[128:129]
	v_lshl_add_u64 v[128:129], v[128:129], 0, v[142:143]
	v_lshlrev_b64 v[154:155], 11, v[114:115]
	v_lshl_add_u64 v[154:155], s[78:79], 0, v[154:155]
	v_lshl_add_u64 v[154:155], v[154:155], 0, v[142:143]
	v_mov_b32_e32 v118, v184
	v_mov_b32_e32 v119, v185
	v_mov_b32_e32 v120, v186
	v_mov_b32_e32 v121, v187
	v_mov_b32_e32 v124, v188
	v_mov_b32_e32 v125, v189
	v_mov_b32_e32 v126, v190
	v_mov_b32_e32 v127, v191
	v_mov_b32_e32 v150, v210
	v_mov_b32_e32 v151, v211
	v_mov_b32_e32 v152, v212
	v_mov_b32_e32 v153, v213
	v_pk_add_f32 v[112:113], v[112:113], v[120:121]
	v_pk_add_f32 v[110:111], v[110:111], v[118:119]
	v_pk_add_f32 v[108:109], v[108:109], v[126:127]
	v_pk_add_f32 v[106:107], v[106:107], v[124:125]
	v_mul_f32_e32 v110, 0xbfb8aa3b, v110
	v_mul_f32_e32 v111, 0xbfb8aa3b, v111
	v_mul_f32_e32 v112, 0xbfb8aa3b, v112
	v_mul_f32_e32 v113, 0xbfb8aa3b, v113
	v_mul_f32_e32 v106, 0xbfb8aa3b, v106
	v_mul_f32_e32 v107, 0xbfb8aa3b, v107
	v_mul_f32_e32 v108, 0xbfb8aa3b, v108
	v_mul_f32_e32 v109, 0xbfb8aa3b, v109
	v_exp_f32_e32 v117, v110
	v_exp_f32_e32 v118, v111
	v_exp_f32_e32 v119, v112
	v_exp_f32_e32 v120, v113
	v_exp_f32_e32 v121, v106
	v_exp_f32_e32 v123, v107
	v_exp_f32_e32 v124, v108
	v_exp_f32_e32 v125, v109
	v_lshlrev_b32_e32 v106, 16, v150
	v_and_b32_e32 v107, 0xffff0000, v150
	v_lshlrev_b32_e32 v108, 16, v151
	v_and_b32_e32 v109, 0xffff0000, v151
	v_lshlrev_b32_e32 v110, 16, v152
	v_and_b32_e32 v111, 0xffff0000, v152
	v_add_f32_e32 v117, 1.0, v117
	v_add_f32_e32 v126, 1.0, v118
	v_add_f32_e32 v127, 1.0, v119
	v_add_f32_e32 v145, 1.0, v120
	v_add_f32_e32 v150, 1.0, v121
	v_add_f32_e32 v123, 1.0, v123
	v_add_f32_e32 v151, 1.0, v124
	v_add_f32_e32 v152, 1.0, v125
	v_rcp_f32_e32 v118, v117
	v_rcp_f32_e32 v119, v126
	v_rcp_f32_e32 v120, v127
	v_rcp_f32_e32 v121, v145
	v_rcp_f32_e32 v124, v150
	v_rcp_f32_e32 v125, v123
	v_rcp_f32_e32 v126, v151
	v_rcp_f32_e32 v127, v152
	v_lshlrev_b32_e32 v112, 16, v153
	v_and_b32_e32 v113, 0xffff0000, v153
	v_pk_mul_f32 v[150:151], v[118:119], v[106:107]
	v_pk_mul_f32 v[152:153], v[120:121], v[108:109]
	v_pk_mul_f32 v[124:125], v[124:125], v[110:111]
	v_pk_mul_f32 v[126:127], v[126:127], v[112:113]
	v_cvt_pk_bf16_f32 v106, v150, v151
	v_cvt_pk_bf16_f32 v107, v152, v153
	v_cvt_pk_bf16_f32 v108, v124, v125
	v_cvt_pk_bf16_f32 v109, v126, v127
	global_store_dwordx4 v[154:155], v[106:109], off offset:1024
	s_nop 0
	v_pk_mul_f32 v[128:129], v[150:151], v[150:151]
	v_pk_mul_f32 v[150:151], v[152:153], v[152:153]
	v_add_f32_e32 v117, v128, v129
	v_add_f32_e32 v117, v150, v117
	v_pk_mul_f32 v[124:125], v[124:125], v[124:125]
	v_add_f32_e32 v117, v151, v117
	v_add_f32_e32 v117, v124, v117
	v_pk_mul_f32 v[126:127], v[126:127], v[126:127]
	v_add_f32_e32 v117, v125, v117
	v_add_f32_e32 v117, v126, v117
	v_add_f32_e32 v117, v127, v117
	v_mov_b32_e32 v106, v192
	v_mov_b32_e32 v107, v193
	v_mov_b32_e32 v108, v194
	v_mov_b32_e32 v109, v195
	v_mov_b32_e32 v110, v196
	v_mov_b32_e32 v111, v197
	v_mov_b32_e32 v112, v198
	v_mov_b32_e32 v113, v199
	v_mov_b32_e32 v118, v214
	v_mov_b32_e32 v119, v215
	v_mov_b32_e32 v120, v216
	v_mov_b32_e32 v121, v217
	v_pk_add_f32 v[102:103], v[102:103], v[106:107]
	v_pk_add_f32 v[104:105], v[104:105], v[108:109]
	v_pk_add_f32 v[98:99], v[98:99], v[110:111]
	v_mul_f32_e32 v102, 0xbfb8aa3b, v102
	v_mul_f32_e32 v103, 0xbfb8aa3b, v103
	v_pk_add_f32 v[100:101], v[100:101], v[112:113]
	v_mul_f32_e32 v104, 0xbfb8aa3b, v104
	v_mul_f32_e32 v105, 0xbfb8aa3b, v105
	v_mul_f32_e32 v98, 0xbfb8aa3b, v98
	v_mul_f32_e32 v99, 0xbfb8aa3b, v99
	v_exp_f32_e32 v102, v102
	v_exp_f32_e32 v103, v103
	v_mul_f32_e32 v100, 0xbfb8aa3b, v100
	v_mul_f32_e32 v101, 0xbfb8aa3b, v101
	v_exp_f32_e32 v104, v104
	v_exp_f32_e32 v105, v105
	v_exp_f32_e32 v98, v98
	v_exp_f32_e32 v99, v99
	v_exp_f32_e32 v100, v100
	v_exp_f32_e32 v101, v101
	v_add_f32_e32 v102, 1.0, v102
	v_add_f32_e32 v103, 1.0, v103
	v_lshlrev_b32_e32 v106, 16, v118
	v_and_b32_e32 v107, 0xffff0000, v118
	v_lshlrev_b32_e32 v108, 16, v119
	v_and_b32_e32 v109, 0xffff0000, v119
	v_add_f32_e32 v104, 1.0, v104
	v_add_f32_e32 v105, 1.0, v105
	v_add_f32_e32 v118, 1.0, v98
	v_add_f32_e32 v119, 1.0, v99
	v_rcp_f32_e32 v98, v102
	v_rcp_f32_e32 v99, v103
	v_lshlrev_b32_e32 v110, 16, v120
	v_and_b32_e32 v111, 0xffff0000, v120
	v_lshlrev_b32_e32 v112, 16, v121
	v_and_b32_e32 v113, 0xffff0000, v121
	v_add_f32_e32 v120, 1.0, v100
	v_add_f32_e32 v121, 1.0, v101
	v_rcp_f32_e32 v100, v104
	v_rcp_f32_e32 v101, v105
	v_rcp_f32_e32 v102, v118
	v_rcp_f32_e32 v103, v119
	v_pk_mul_f32 v[98:99], v[98:99], v[106:107]
	v_pk_mul_f32 v[106:107], v[100:101], v[108:109]
	v_pk_mul_f32 v[100:101], v[98:99], v[98:99]
	v_rcp_f32_e32 v104, v120
	v_rcp_f32_e32 v105, v121
	v_add_f32_e32 v100, v100, v117
	v_pk_mul_f32 v[108:109], v[106:107], v[106:107]
	v_add_f32_e32 v100, v101, v100
	v_pk_mul_f32 v[102:103], v[102:103], v[110:111]
	v_add_f32_e32 v100, v108, v100
	v_pk_mul_f32 v[110:111], v[102:103], v[102:103]
	v_add_f32_e32 v100, v109, v100
	v_pk_mul_f32 v[104:105], v[104:105], v[112:113]
	v_add_f32_e32 v100, v110, v100
	v_pk_mul_f32 v[112:113], v[104:105], v[104:105]
	v_add_f32_e32 v100, v111, v100
	v_add_f32_e32 v100, v112, v100
	v_add_f32_e32 v101, v113, v100
	ds_bpermute_b32 v108, v122, v101
	v_cvt_pk_bf16_f32 v100, v98, v99
	v_cvt_pk_bf16_f32 v102, v102, v103
	v_cvt_pk_bf16_f32 v103, v104, v105
	s_waitcnt lgkmcnt(0)
	v_add_f32_e32 v98, v101, v108
	ds_bpermute_b32 v99, v116, v98
	v_cvt_pk_bf16_f32 v101, v106, v107
	global_store_dwordx4 v[154:155], v[100:103], off offset:1280
	s_and_saveexec_b64 s[22:23], s[4:5]
	s_cbranch_execz .LBB0_594
	s_add_u32 s26, s36, s92
	s_addc_u32 s27, s37, s93
	v_lshl_add_u64 v[100:101], v[114:115], 4, s[26:27]
	s_lshl_b32 s52, s38, 2
	v_lshl_add_u64 v[100:101], v[100:101], 0, s[52:53]
	s_waitcnt lgkmcnt(0)
	v_add_f32_e32 v98, v98, v99
	global_store_dword v[100:101], v98, off
; __device__ __forceinline__ unsigned cvt_pk_bf16(float lo, float hi) { const f32x2 v = {lo, hi}; return __builtin_bit_cast(unsigned, __builtin_convertvector(v, bf16x2_t)); }
; __device__ __forceinline__ float bf_lo(unsigned w) { return __uint_as_float(w << 16); }
; __device__ __forceinline__ float bf_hi(unsigned w) { return __uint_as_float(w & 0xffff0000u); }
; __device__ __forceinline__ float fast_sigmoid(float v) { return __builtin_amdgcn_rcpf(1.0f + __builtin_amdgcn_exp2f(-1.4426950408889634f * v)); }
; #define ssq2 ((float*)(WSPTR() + WS_SSQ2))
;     __device__ __forceinline__ void operator()(const f32x4 (&acc)[2][2][4][2], const Unit& u, int wr, int wc, int fr, int fq) const {
;     ...
;         for (int ai = 0; ai < 2; ++ai)
; #pragma unroll
;             for (int m = 0; m < 4; ++m) {
;                 const int row = row0 + ai * HALF + m * 16;
;                 float ss = 0.f;
; #pragma unroll
;                 for (int bj = 0; bj < 2; ++bj) {
;                     const int c0 = u.pn * BM + bj * HALF + wc * 32 + 8 * fq;
;                     const u32x4 zw = *(const u32x4*)(z + (size_t)row * 512 + c0);
;                     const f32x4 b0 = *(const f32x4*)(bglu + c0), b1 = *(const f32x4*)(bglu + c0 + 4);
;                     const f32x4 a0 = acc[ai][bj][m][0] + b0, a1 = acc[ai][bj][m][1] + b1;
;                     float o[8];
;                     o[0] = bf_lo(zw.x) * fast_sigmoid(a0[0]); o[1] = bf_hi(zw.x) * fast_sigmoid(a0[1]);
;                     o[2] = bf_lo(zw.y) * fast_sigmoid(a0[2]); o[3] = bf_hi(zw.y) * fast_sigmoid(a0[3]);
;                     o[4] = bf_lo(zw.z) * fast_sigmoid(a1[0]); o[5] = bf_hi(zw.z) * fast_sigmoid(a1[1]);
;                     o[6] = bf_lo(zw.w) * fast_sigmoid(a1[2]); o[7] = bf_hi(zw.w) * fast_sigmoid(a1[3]);
; #pragma unroll
;                     for (int j = 0; j < 8; ++j) ss += o[j] * o[j];
;                     u32x4 w; w.x = cvt_pk_bf16(o[0], o[1]); w.y = cvt_pk_bf16(o[2], o[3]); w.z = cvt_pk_bf16(o[4], o[5]); w.w = cvt_pk_bf16(o[6], o[7]);
;                     *(u32x4*)(s + (size_t)row * 1024 + 512 + c0) = w;
;                 }
;                 ss += __shfl_xor(ss, 16); ss += __shfl_xor(ss, 32); if (fq == 0) ssq2[((size_t)u.pn * 32768 + row) * 4 + wc] = ss;
;             }
.LBB0_594:
	s_or_b64 exec, exec, s[22:23]
	s_mov_b32 s100, 0xc000
	s_mov_b32 s101, 0
	v_lshl_add_u64 v[228:229], v[226:227], 0, s[100:101]
	global_load_dwordx4 v[210:213], v[228:229], off
	global_load_dwordx4 v[214:217], v[228:229], off offset:256
	s_waitcnt vmcnt(2)
	v_or_b32_e32 v98, 32, v144
	s_waitcnt lgkmcnt(0)
	v_ashrrev_i32_e32 v99, 31, v98
	v_lshlrev_b64 v[108:109], 10, v[98:99]
	v_lshl_add_u64 v[108:109], s[76:77], 0, v[108:109]
	v_lshl_add_u64 v[112:113], v[108:109], 0, v[142:143]
	v_lshlrev_b64 v[114:115], 11, v[98:99]
	v_lshl_add_u64 v[114:115], s[78:79], 0, v[114:115]
	v_lshl_add_u64 v[114:115], v[114:115], 0, v[142:143]
	v_mov_b32_e32 v100, v184
	v_mov_b32_e32 v101, v185
	v_mov_b32_e32 v102, v186
	v_mov_b32_e32 v103, v187
	v_mov_b32_e32 v104, v188
	v_mov_b32_e32 v105, v189
	v_mov_b32_e32 v106, v190
	v_mov_b32_e32 v107, v191
	v_mov_b32_e32 v108, v200
	v_mov_b32_e32 v109, v201
	v_mov_b32_e32 v110, v202
	v_mov_b32_e32 v111, v203
	v_pk_add_f32 v[96:97], v[96:97], v[102:103]
	v_pk_add_f32 v[94:95], v[94:95], v[100:101]
	v_pk_add_f32 v[92:93], v[92:93], v[106:107]
	v_pk_add_f32 v[90:91], v[90:91], v[104:105]
	v_mul_f32_e32 v94, 0xbfb8aa3b, v94
	v_mul_f32_e32 v95, 0xbfb8aa3b, v95
	v_mul_f32_e32 v96, 0xbfb8aa3b, v96
	v_mul_f32_e32 v97, 0xbfb8aa3b, v97
	v_mul_f32_e32 v90, 0xbfb8aa3b, v90
	v_mul_f32_e32 v91, 0xbfb8aa3b, v91
	v_mul_f32_e32 v92, 0xbfb8aa3b, v92
	v_mul_f32_e32 v93, 0xbfb8aa3b, v93
	v_exp_f32_e32 v100, v94
	v_exp_f32_e32 v101, v95
	v_exp_f32_e32 v102, v96
	v_exp_f32_e32 v103, v97
	v_exp_f32_e32 v104, v90
	v_exp_f32_e32 v105, v91
	v_exp_f32_e32 v106, v92
	v_exp_f32_e32 v107, v93
	v_add_f32_e32 v100, 1.0, v100
	v_add_f32_e32 v101, 1.0, v101
	v_add_f32_e32 v102, 1.0, v102
	v_add_f32_e32 v103, 1.0, v103
	v_add_f32_e32 v104, 1.0, v104
	v_add_f32_e32 v105, 1.0, v105
	v_add_f32_e32 v106, 1.0, v106
	v_add_f32_e32 v107, 1.0, v107
	v_rcp_f32_e32 v100, v100
	v_rcp_f32_e32 v101, v101
	v_rcp_f32_e32 v102, v102
	v_rcp_f32_e32 v103, v103
	v_rcp_f32_e32 v104, v104
	v_rcp_f32_e32 v105, v105
	v_rcp_f32_e32 v106, v106
	v_rcp_f32_e32 v107, v107
	v_lshlrev_b32_e32 v90, 16, v108
	v_and_b32_e32 v91, 0xffff0000, v108
	v_lshlrev_b32_e32 v92, 16, v109
	v_and_b32_e32 v93, 0xffff0000, v109
	v_lshlrev_b32_e32 v94, 16, v110
	v_and_b32_e32 v95, 0xffff0000, v110
	v_lshlrev_b32_e32 v96, 16, v111
	v_and_b32_e32 v97, 0xffff0000, v111
	v_pk_mul_f32 v[108:109], v[100:101], v[90:91]
	v_pk_mul_f32 v[110:111], v[102:103], v[92:93]
	v_pk_mul_f32 v[104:105], v[104:105], v[94:95]
	v_pk_mul_f32 v[106:107], v[106:107], v[96:97]
	v_cvt_pk_bf16_f32 v90, v108, v109
	v_cvt_pk_bf16_f32 v91, v110, v111
	v_cvt_pk_bf16_f32 v92, v104, v105
	v_cvt_pk_bf16_f32 v93, v106, v107
	global_store_dwordx4 v[114:115], v[90:93], off offset:1024
	s_nop 0
	v_pk_mul_f32 v[108:109], v[108:109], v[108:109]
	v_pk_mul_f32 v[110:111], v[110:111], v[110:111]
	v_add_f32_e32 v108, v108, v109
	v_add_f32_e32 v108, v110, v108
	v_pk_mul_f32 v[104:105], v[104:105], v[104:105]
	v_add_f32_e32 v108, v111, v108
	v_add_f32_e32 v104, v104, v108
	v_pk_mul_f32 v[106:107], v[106:107], v[106:107]
	v_add_f32_e32 v104, v105, v104
	v_add_f32_e32 v104, v106, v104
	v_mov_b32_e32 v90, v192
	v_mov_b32_e32 v91, v193
	v_mov_b32_e32 v92, v194
	v_mov_b32_e32 v93, v195
	v_mov_b32_e32 v94, v196
	v_mov_b32_e32 v95, v197
	v_mov_b32_e32 v96, v198
	v_mov_b32_e32 v97, v199
	v_mov_b32_e32 v100, v204
	v_mov_b32_e32 v101, v205
	v_mov_b32_e32 v102, v206
	v_mov_b32_e32 v103, v207
	v_pk_add_f32 v[86:87], v[86:87], v[90:91]
	v_pk_add_f32 v[88:89], v[88:89], v[92:93]
	v_pk_add_f32 v[82:83], v[82:83], v[94:95]
	v_mul_f32_e32 v86, 0xbfb8aa3b, v86
	v_mul_f32_e32 v87, 0xbfb8aa3b, v87
	v_pk_add_f32 v[84:85], v[84:85], v[96:97]
	v_mul_f32_e32 v88, 0xbfb8aa3b, v88
	v_mul_f32_e32 v89, 0xbfb8aa3b, v89
	v_mul_f32_e32 v82, 0xbfb8aa3b, v82
	v_mul_f32_e32 v83, 0xbfb8aa3b, v83
	v_exp_f32_e32 v86, v86
	v_exp_f32_e32 v87, v87
	v_mul_f32_e32 v84, 0xbfb8aa3b, v84
	v_mul_f32_e32 v85, 0xbfb8aa3b, v85
	v_exp_f32_e32 v88, v88
	v_exp_f32_e32 v89, v89
	v_exp_f32_e32 v82, v82
	v_exp_f32_e32 v83, v83
	v_exp_f32_e32 v84, v84
	v_exp_f32_e32 v85, v85
	v_add_f32_e32 v86, 1.0, v86
	v_add_f32_e32 v87, 1.0, v87
	v_lshlrev_b32_e32 v90, 16, v100
	v_and_b32_e32 v91, 0xffff0000, v100
	v_lshlrev_b32_e32 v92, 16, v101
	v_and_b32_e32 v93, 0xffff0000, v101
	v_add_f32_e32 v88, 1.0, v88
	v_add_f32_e32 v89, 1.0, v89
	v_add_f32_e32 v100, 1.0, v82
	v_add_f32_e32 v101, 1.0, v83
	v_rcp_f32_e32 v82, v86
	v_rcp_f32_e32 v83, v87
	v_lshlrev_b32_e32 v94, 16, v102
	v_and_b32_e32 v95, 0xffff0000, v102
	v_lshlrev_b32_e32 v96, 16, v103
	v_and_b32_e32 v97, 0xffff0000, v103
	v_add_f32_e32 v102, 1.0, v84
	v_add_f32_e32 v103, 1.0, v85
	v_rcp_f32_e32 v84, v88
	v_rcp_f32_e32 v85, v89
	v_rcp_f32_e32 v86, v100
	v_rcp_f32_e32 v87, v101
	v_pk_mul_f32 v[82:83], v[82:83], v[90:91]
	v_pk_mul_f32 v[90:91], v[84:85], v[92:93]
	v_pk_mul_f32 v[84:85], v[82:83], v[82:83]
	v_add_f32_e32 v100, v107, v104
	v_rcp_f32_e32 v88, v102
	v_rcp_f32_e32 v89, v103
	v_add_f32_e32 v84, v84, v100
	v_pk_mul_f32 v[92:93], v[90:91], v[90:91]
	v_add_f32_e32 v84, v85, v84
	v_pk_mul_f32 v[86:87], v[86:87], v[94:95]
	v_add_f32_e32 v84, v92, v84
	v_pk_mul_f32 v[94:95], v[86:87], v[86:87]
	v_add_f32_e32 v84, v93, v84
	v_pk_mul_f32 v[88:89], v[88:89], v[96:97]
	v_add_f32_e32 v84, v94, v84
	v_pk_mul_f32 v[96:97], v[88:89], v[88:89]
	v_add_f32_e32 v84, v95, v84
	v_add_f32_e32 v84, v96, v84
	v_add_f32_e32 v85, v97, v84
	ds_bpermute_b32 v92, v122, v85
	v_cvt_pk_bf16_f32 v84, v82, v83
	v_cvt_pk_bf16_f32 v86, v86, v87
	v_cvt_pk_bf16_f32 v87, v88, v89
	s_waitcnt lgkmcnt(0)
	v_add_f32_e32 v82, v85, v92
	ds_bpermute_b32 v83, v116, v82
	v_cvt_pk_bf16_f32 v85, v90, v91
	global_store_dwordx4 v[114:115], v[84:87], off offset:1280
	s_and_saveexec_b64 s[22:23], s[4:5]
	s_cbranch_execz .LBB0_596
	s_add_u32 s26, s36, s92
	s_addc_u32 s27, s37, s93
	v_lshl_add_u64 v[84:85], v[98:99], 4, s[26:27]
	s_lshl_b32 s52, s38, 2
	v_lshl_add_u64 v[84:85], v[84:85], 0, s[52:53]
	s_waitcnt lgkmcnt(0)
	v_add_f32_e32 v82, v82, v83
	global_store_dword v[84:85], v82, off
; __device__ __forceinline__ unsigned cvt_pk_bf16(float lo, float hi) { const f32x2 v = {lo, hi}; return __builtin_bit_cast(unsigned, __builtin_convertvector(v, bf16x2_t)); }
; __device__ __forceinline__ float bf_lo(unsigned w) { return __uint_as_float(w << 16); }
; __device__ __forceinline__ float bf_hi(unsigned w) { return __uint_as_float(w & 0xffff0000u); }
; __device__ __forceinline__ float fast_sigmoid(float v) { return __builtin_amdgcn_rcpf(1.0f + __builtin_amdgcn_exp2f(-1.4426950408889634f * v)); }
; #define ssq2 ((float*)(WSPTR() + WS_SSQ2))
;     __device__ __forceinline__ void operator()(const f32x4 (&acc)[2][2][4][2], const Unit& u, int wr, int wc, int fr, int fq) const {
;     ...
;         for (int ai = 0; ai < 2; ++ai)
; #pragma unroll
;             for (int m = 0; m < 4; ++m) {
;                 const int row = row0 + ai * HALF + m * 16;
;                 float ss = 0.f;
; #pragma unroll
;                 for (int bj = 0; bj < 2; ++bj) {
;                     const int c0 = u.pn * BM + bj * HALF + wc * 32 + 8 * fq;
;                     const u32x4 zw = *(const u32x4*)(z + (size_t)row * 512 + c0);
;                     const f32x4 b0 = *(const f32x4*)(bglu + c0), b1 = *(const f32x4*)(bglu + c0 + 4);
;                     const f32x4 a0 = acc[ai][bj][m][0] + b0, a1 = acc[ai][bj][m][1] + b1;
;                     float o[8];
;                     o[0] = bf_lo(zw.x) * fast_sigmoid(a0[0]); o[1] = bf_hi(zw.x) * fast_sigmoid(a0[1]);
;                     o[2] = bf_lo(zw.y) * fast_sigmoid(a0[2]); o[3] = bf_hi(zw.y) * fast_sigmoid(a0[3]);
;                     o[4] = bf_lo(zw.z) * fast_sigmoid(a1[0]); o[5] = bf_hi(zw.z) * fast_sigmoid(a1[1]);
;                     o[6] = bf_lo(zw.w) * fast_sigmoid(a1[2]); o[7] = bf_hi(zw.w) * fast_sigmoid(a1[3]);
; #pragma unroll
;                     for (int j = 0; j < 8; ++j) ss += o[j] * o[j];
;                     u32x4 w; w.x = cvt_pk_bf16(o[0], o[1]); w.y = cvt_pk_bf16(o[2], o[3]); w.z = cvt_pk_bf16(o[4], o[5]); w.w = cvt_pk_bf16(o[6], o[7]);
;                     *(u32x4*)(s + (size_t)row * 1024 + 512 + c0) = w;
;                 }
;                 ss += __shfl_xor(ss, 16); ss += __shfl_xor(ss, 32); if (fq == 0) ssq2[((size_t)u.pn * 32768 + row) * 4 + wc] = ss;
;             }
.LBB0_596:
	s_or_b64 exec, exec, s[22:23]
	s_mov_b32 s100, 0x20000
	s_mov_b32 s101, 0
	v_lshl_add_u64 v[228:229], v[226:227], 0, s[100:101]
	global_load_dwordx4 v[200:203], v[228:229], off
	global_load_dwordx4 v[204:207], v[228:229], off offset:256
	s_waitcnt vmcnt(2)
	v_or_b32_e32 v82, 48, v144
	s_waitcnt lgkmcnt(0)
	v_ashrrev_i32_e32 v83, 31, v82
	v_lshlrev_b64 v[92:93], 10, v[82:83]
	v_lshl_add_u64 v[92:93], s[76:77], 0, v[92:93]
	v_lshl_add_u64 v[96:97], v[92:93], 0, v[142:143]
	v_lshlrev_b64 v[98:99], 11, v[82:83]
	v_lshl_add_u64 v[98:99], s[78:79], 0, v[98:99]
	v_lshl_add_u64 v[98:99], v[98:99], 0, v[142:143]
	v_mov_b32_e32 v84, v184
	v_mov_b32_e32 v85, v185
	v_mov_b32_e32 v86, v186
	v_mov_b32_e32 v87, v187
	v_mov_b32_e32 v88, v188
	v_mov_b32_e32 v89, v189
	v_mov_b32_e32 v90, v190
	v_mov_b32_e32 v91, v191
	v_mov_b32_e32 v92, v210
	v_mov_b32_e32 v93, v211
	v_mov_b32_e32 v94, v212
	v_mov_b32_e32 v95, v213
	v_pk_add_f32 v[80:81], v[80:81], v[86:87]
	v_pk_add_f32 v[78:79], v[78:79], v[84:85]
	v_pk_add_f32 v[76:77], v[76:77], v[90:91]
	v_pk_add_f32 v[74:75], v[74:75], v[88:89]
	v_mul_f32_e32 v78, 0xbfb8aa3b, v78
	v_mul_f32_e32 v79, 0xbfb8aa3b, v79
	v_mul_f32_e32 v80, 0xbfb8aa3b, v80
	v_mul_f32_e32 v81, 0xbfb8aa3b, v81
	v_mul_f32_e32 v74, 0xbfb8aa3b, v74
	v_mul_f32_e32 v75, 0xbfb8aa3b, v75
	v_mul_f32_e32 v76, 0xbfb8aa3b, v76
	v_mul_f32_e32 v77, 0xbfb8aa3b, v77
	v_exp_f32_e32 v84, v78
	v_exp_f32_e32 v85, v79
	v_exp_f32_e32 v86, v80
	v_exp_f32_e32 v87, v81
	v_exp_f32_e32 v88, v74
	v_exp_f32_e32 v89, v75
	v_exp_f32_e32 v90, v76
	v_exp_f32_e32 v91, v77
	v_add_f32_e32 v84, 1.0, v84
	v_add_f32_e32 v85, 1.0, v85
	v_add_f32_e32 v86, 1.0, v86
	v_add_f32_e32 v87, 1.0, v87
	v_add_f32_e32 v88, 1.0, v88
	v_add_f32_e32 v89, 1.0, v89
	v_add_f32_e32 v90, 1.0, v90
	v_add_f32_e32 v91, 1.0, v91
	v_rcp_f32_e32 v84, v84
	v_rcp_f32_e32 v85, v85
	v_rcp_f32_e32 v86, v86
	v_rcp_f32_e32 v87, v87
	v_rcp_f32_e32 v88, v88
	v_rcp_f32_e32 v89, v89
	v_rcp_f32_e32 v90, v90
	v_rcp_f32_e32 v91, v91
	v_lshlrev_b32_e32 v74, 16, v92
	v_and_b32_e32 v75, 0xffff0000, v92
	v_lshlrev_b32_e32 v76, 16, v93
	v_and_b32_e32 v77, 0xffff0000, v93
	v_lshlrev_b32_e32 v78, 16, v94
	v_and_b32_e32 v79, 0xffff0000, v94
	v_lshlrev_b32_e32 v80, 16, v95
	v_and_b32_e32 v81, 0xffff0000, v95
	v_pk_mul_f32 v[92:93], v[84:85], v[74:75]
	v_pk_mul_f32 v[94:95], v[86:87], v[76:77]
	v_pk_mul_f32 v[88:89], v[88:89], v[78:79]
	v_pk_mul_f32 v[90:91], v[90:91], v[80:81]
	v_cvt_pk_bf16_f32 v74, v92, v93
	v_cvt_pk_bf16_f32 v75, v94, v95
	v_cvt_pk_bf16_f32 v76, v88, v89
	v_cvt_pk_bf16_f32 v77, v90, v91
	global_store_dwordx4 v[98:99], v[74:77], off offset:1024
	s_nop 0
	v_pk_mul_f32 v[92:93], v[92:93], v[92:93]
	v_pk_mul_f32 v[94:95], v[94:95], v[94:95]
	v_add_f32_e32 v92, v92, v93
	v_add_f32_e32 v92, v94, v92
	v_pk_mul_f32 v[88:89], v[88:89], v[88:89]
	v_add_f32_e32 v92, v95, v92
	v_add_f32_e32 v88, v88, v92
	v_pk_mul_f32 v[90:91], v[90:91], v[90:91]
	v_add_f32_e32 v88, v89, v88
	v_add_f32_e32 v88, v90, v88
	v_mov_b32_e32 v74, v192
	v_mov_b32_e32 v75, v193
	v_mov_b32_e32 v76, v194
	v_mov_b32_e32 v77, v195
	v_mov_b32_e32 v78, v196
	v_mov_b32_e32 v79, v197
	v_mov_b32_e32 v80, v198
	v_mov_b32_e32 v81, v199
	v_mov_b32_e32 v84, v214
	v_mov_b32_e32 v85, v215
	v_mov_b32_e32 v86, v216
	v_mov_b32_e32 v87, v217
	v_pk_add_f32 v[70:71], v[70:71], v[74:75]
	v_pk_add_f32 v[72:73], v[72:73], v[76:77]
	v_pk_add_f32 v[66:67], v[66:67], v[78:79]
	v_mul_f32_e32 v70, 0xbfb8aa3b, v70
	v_mul_f32_e32 v71, 0xbfb8aa3b, v71
	v_pk_add_f32 v[68:69], v[68:69], v[80:81]
	v_mul_f32_e32 v72, 0xbfb8aa3b, v72
	v_mul_f32_e32 v73, 0xbfb8aa3b, v73
	v_mul_f32_e32 v66, 0xbfb8aa3b, v66
	v_mul_f32_e32 v67, 0xbfb8aa3b, v67
	v_exp_f32_e32 v70, v70
	v_exp_f32_e32 v71, v71
	v_mul_f32_e32 v68, 0xbfb8aa3b, v68
	v_mul_f32_e32 v69, 0xbfb8aa3b, v69
	v_exp_f32_e32 v72, v72
	v_exp_f32_e32 v73, v73
	v_exp_f32_e32 v66, v66
	v_exp_f32_e32 v67, v67
	v_exp_f32_e32 v68, v68
	v_exp_f32_e32 v69, v69
	v_add_f32_e32 v70, 1.0, v70
	v_add_f32_e32 v71, 1.0, v71
	v_lshlrev_b32_e32 v74, 16, v84
	v_and_b32_e32 v75, 0xffff0000, v84
	v_lshlrev_b32_e32 v76, 16, v85
	v_and_b32_e32 v77, 0xffff0000, v85
	v_add_f32_e32 v72, 1.0, v72
	v_add_f32_e32 v73, 1.0, v73
	v_add_f32_e32 v84, 1.0, v66
	v_add_f32_e32 v85, 1.0, v67
	v_rcp_f32_e32 v66, v70
	v_rcp_f32_e32 v67, v71
	v_lshlrev_b32_e32 v78, 16, v86
	v_and_b32_e32 v79, 0xffff0000, v86
	v_lshlrev_b32_e32 v80, 16, v87
	v_and_b32_e32 v81, 0xffff0000, v87
	v_add_f32_e32 v86, 1.0, v68
	v_add_f32_e32 v87, 1.0, v69
	v_rcp_f32_e32 v68, v72
	v_rcp_f32_e32 v69, v73
	v_rcp_f32_e32 v70, v84
	v_rcp_f32_e32 v71, v85
	v_pk_mul_f32 v[66:67], v[66:67], v[74:75]
	v_pk_mul_f32 v[74:75], v[68:69], v[76:77]
	v_pk_mul_f32 v[68:69], v[66:67], v[66:67]
	v_add_f32_e32 v84, v91, v88
	v_rcp_f32_e32 v72, v86
	v_rcp_f32_e32 v73, v87
	v_add_f32_e32 v68, v68, v84
	v_pk_mul_f32 v[76:77], v[74:75], v[74:75]
	v_add_f32_e32 v68, v69, v68
	v_pk_mul_f32 v[70:71], v[70:71], v[78:79]
	v_add_f32_e32 v68, v76, v68
	v_pk_mul_f32 v[78:79], v[70:71], v[70:71]
	v_add_f32_e32 v68, v77, v68
	v_pk_mul_f32 v[72:73], v[72:73], v[80:81]
	v_add_f32_e32 v68, v78, v68
	v_pk_mul_f32 v[80:81], v[72:73], v[72:73]
	v_add_f32_e32 v68, v79, v68
	v_add_f32_e32 v68, v80, v68
	v_add_f32_e32 v69, v81, v68
	ds_bpermute_b32 v76, v122, v69
	v_cvt_pk_bf16_f32 v68, v66, v67
	v_cvt_pk_bf16_f32 v70, v70, v71
	v_cvt_pk_bf16_f32 v71, v72, v73
	s_waitcnt lgkmcnt(0)
	v_add_f32_e32 v66, v69, v76
	ds_bpermute_b32 v67, v116, v66
	v_cvt_pk_bf16_f32 v69, v74, v75
	global_store_dwordx4 v[98:99], v[68:71], off offset:1280
	s_and_saveexec_b64 s[22:23], s[4:5]
	s_cbranch_execz .LBB0_598
	s_add_u32 s26, s36, s92
	s_addc_u32 s27, s37, s93
	v_lshl_add_u64 v[68:69], v[82:83], 4, s[26:27]
	s_lshl_b32 s52, s38, 2
	v_lshl_add_u64 v[68:69], v[68:69], 0, s[52:53]
	s_waitcnt lgkmcnt(0)
	v_add_f32_e32 v66, v66, v67
	global_store_dword v[68:69], v66, off
; __device__ __forceinline__ unsigned cvt_pk_bf16(float lo, float hi) { const f32x2 v = {lo, hi}; return __builtin_bit_cast(unsigned, __builtin_convertvector(v, bf16x2_t)); }
; __device__ __forceinline__ float bf_lo(unsigned w) { return __uint_as_float(w << 16); }
; __device__ __forceinline__ float bf_hi(unsigned w) { return __uint_as_float(w & 0xffff0000u); }
; __device__ __forceinline__ float fast_sigmoid(float v) { return __builtin_amdgcn_rcpf(1.0f + __builtin_amdgcn_exp2f(-1.4426950408889634f * v)); }
; #define ssq2 ((float*)(WSPTR() + WS_SSQ2))
;     __device__ __forceinline__ void operator()(const f32x4 (&acc)[2][2][4][2], const Unit& u, int wr, int wc, int fr, int fq) const {
;     ...
;         for (int ai = 0; ai < 2; ++ai)
; #pragma unroll
;             for (int m = 0; m < 4; ++m) {
;                 const int row = row0 + ai * HALF + m * 16;
;                 float ss = 0.f;
; #pragma unroll
;                 for (int bj = 0; bj < 2; ++bj) {
;                     const int c0 = u.pn * BM + bj * HALF + wc * 32 + 8 * fq;
;                     const u32x4 zw = *(const u32x4*)(z + (size_t)row * 512 + c0);
;                     const f32x4 b0 = *(const f32x4*)(bglu + c0), b1 = *(const f32x4*)(bglu + c0 + 4);
;                     const f32x4 a0 = acc[ai][bj][m][0] + b0, a1 = acc[ai][bj][m][1] + b1;
;                     float o[8];
;                     o[0] = bf_lo(zw.x) * fast_sigmoid(a0[0]); o[1] = bf_hi(zw.x) * fast_sigmoid(a0[1]);
;                     o[2] = bf_lo(zw.y) * fast_sigmoid(a0[2]); o[3] = bf_hi(zw.y) * fast_sigmoid(a0[3]);
;                     o[4] = bf_lo(zw.z) * fast_sigmoid(a1[0]); o[5] = bf_hi(zw.z) * fast_sigmoid(a1[1]);
;                     o[6] = bf_lo(zw.w) * fast_sigmoid(a1[2]); o[7] = bf_hi(zw.w) * fast_sigmoid(a1[3]);
; #pragma unroll
;                     for (int j = 0; j < 8; ++j) ss += o[j] * o[j];
;                     u32x4 w; w.x = cvt_pk_bf16(o[0], o[1]); w.y = cvt_pk_bf16(o[2], o[3]); w.z = cvt_pk_bf16(o[4], o[5]); w.w = cvt_pk_bf16(o[6], o[7]);
;                     *(u32x4*)(s + (size_t)row * 1024 + 512 + c0) = w;
;                 }
;                 ss += __shfl_xor(ss, 16); ss += __shfl_xor(ss, 32); if (fq == 0) ssq2[((size_t)u.pn * 32768 + row) * 4 + wc] = ss;
;             }
.LBB0_598:
	s_or_b64 exec, exec, s[22:23]
	s_mov_b32 s100, 0x24000
	s_mov_b32 s101, 0
	v_lshl_add_u64 v[228:229], v[226:227], 0, s[100:101]
	global_load_dwordx4 v[210:213], v[228:229], off
	global_load_dwordx4 v[214:217], v[228:229], off offset:256
	s_waitcnt vmcnt(2)
	v_add_u32_e32 v66, 0x80, v144
	s_waitcnt lgkmcnt(0)
	v_ashrrev_i32_e32 v67, 31, v66
	v_lshlrev_b64 v[76:77], 10, v[66:67]
	v_lshl_add_u64 v[76:77], s[76:77], 0, v[76:77]
	v_lshl_add_u64 v[80:81], v[76:77], 0, v[142:143]
	v_lshlrev_b64 v[82:83], 11, v[66:67]
	v_lshl_add_u64 v[82:83], s[78:79], 0, v[82:83]
	v_lshl_add_u64 v[82:83], v[82:83], 0, v[142:143]
	v_mov_b32_e32 v68, v184
	v_mov_b32_e32 v69, v185
	v_mov_b32_e32 v70, v186
	v_mov_b32_e32 v71, v187
	v_mov_b32_e32 v72, v188
	v_mov_b32_e32 v73, v189
	v_mov_b32_e32 v74, v190
	v_mov_b32_e32 v75, v191
	v_mov_b32_e32 v76, v200
	v_mov_b32_e32 v77, v201
	v_mov_b32_e32 v78, v202
	v_mov_b32_e32 v79, v203
	v_pk_add_f32 v[64:65], v[64:65], v[70:71]
	v_pk_add_f32 v[62:63], v[62:63], v[68:69]
	v_pk_add_f32 v[60:61], v[60:61], v[74:75]
	v_pk_add_f32 v[58:59], v[58:59], v[72:73]
	v_mul_f32_e32 v62, 0xbfb8aa3b, v62
	v_mul_f32_e32 v63, 0xbfb8aa3b, v63
	v_mul_f32_e32 v64, 0xbfb8aa3b, v64
	v_mul_f32_e32 v65, 0xbfb8aa3b, v65
	v_mul_f32_e32 v58, 0xbfb8aa3b, v58
	v_mul_f32_e32 v59, 0xbfb8aa3b, v59
	v_mul_f32_e32 v60, 0xbfb8aa3b, v60
	v_mul_f32_e32 v61, 0xbfb8aa3b, v61
	v_exp_f32_e32 v68, v62
	v_exp_f32_e32 v69, v63
	v_exp_f32_e32 v70, v64
	v_exp_f32_e32 v71, v65
	v_exp_f32_e32 v72, v58
	v_exp_f32_e32 v73, v59
	v_exp_f32_e32 v74, v60
	v_exp_f32_e32 v75, v61
	v_add_f32_e32 v68, 1.0, v68
	v_add_f32_e32 v69, 1.0, v69
	v_add_f32_e32 v70, 1.0, v70
	v_add_f32_e32 v71, 1.0, v71
	v_add_f32_e32 v72, 1.0, v72
	v_add_f32_e32 v73, 1.0, v73
	v_add_f32_e32 v74, 1.0, v74
	v_add_f32_e32 v75, 1.0, v75
	v_rcp_f32_e32 v68, v68
	v_rcp_f32_e32 v69, v69
	v_rcp_f32_e32 v70, v70
	v_rcp_f32_e32 v71, v71
	v_rcp_f32_e32 v72, v72
	v_rcp_f32_e32 v73, v73
	v_rcp_f32_e32 v74, v74
	v_rcp_f32_e32 v75, v75
	v_lshlrev_b32_e32 v58, 16, v76
	v_and_b32_e32 v59, 0xffff0000, v76
	v_lshlrev_b32_e32 v60, 16, v77
	v_and_b32_e32 v61, 0xffff0000, v77
	v_lshlrev_b32_e32 v62, 16, v78
	v_and_b32_e32 v63, 0xffff0000, v78
	v_lshlrev_b32_e32 v64, 16, v79
	v_and_b32_e32 v65, 0xffff0000, v79
	v_pk_mul_f32 v[76:77], v[68:69], v[58:59]
	v_pk_mul_f32 v[78:79], v[70:71], v[60:61]
	v_pk_mul_f32 v[72:73], v[72:73], v[62:63]
	v_pk_mul_f32 v[74:75], v[74:75], v[64:65]
	v_cvt_pk_bf16_f32 v58, v76, v77
	v_cvt_pk_bf16_f32 v59, v78, v79
	v_cvt_pk_bf16_f32 v60, v72, v73
	v_cvt_pk_bf16_f32 v61, v74, v75
	global_store_dwordx4 v[82:83], v[58:61], off offset:1024
	s_nop 0
	v_pk_mul_f32 v[76:77], v[76:77], v[76:77]
	v_pk_mul_f32 v[78:79], v[78:79], v[78:79]
	v_add_f32_e32 v76, v76, v77
	v_add_f32_e32 v76, v78, v76
	v_pk_mul_f32 v[72:73], v[72:73], v[72:73]
	v_add_f32_e32 v76, v79, v76
	v_add_f32_e32 v72, v72, v76
	v_pk_mul_f32 v[74:75], v[74:75], v[74:75]
	v_add_f32_e32 v72, v73, v72
	v_add_f32_e32 v72, v74, v72
	v_mov_b32_e32 v58, v192
	v_mov_b32_e32 v59, v193
	v_mov_b32_e32 v60, v194
	v_mov_b32_e32 v61, v195
	v_mov_b32_e32 v62, v196
	v_mov_b32_e32 v63, v197
	v_mov_b32_e32 v64, v198
	v_mov_b32_e32 v65, v199
	v_mov_b32_e32 v68, v204
	v_mov_b32_e32 v69, v205
	v_mov_b32_e32 v70, v206
	v_mov_b32_e32 v71, v207
	v_pk_add_f32 v[54:55], v[54:55], v[58:59]
	v_pk_add_f32 v[56:57], v[56:57], v[60:61]
	v_pk_add_f32 v[50:51], v[50:51], v[62:63]
	v_mul_f32_e32 v54, 0xbfb8aa3b, v54
	v_mul_f32_e32 v55, 0xbfb8aa3b, v55
	v_pk_add_f32 v[52:53], v[52:53], v[64:65]
	v_mul_f32_e32 v56, 0xbfb8aa3b, v56
	v_mul_f32_e32 v57, 0xbfb8aa3b, v57
	v_mul_f32_e32 v50, 0xbfb8aa3b, v50
	v_mul_f32_e32 v51, 0xbfb8aa3b, v51
	v_exp_f32_e32 v54, v54
	v_exp_f32_e32 v55, v55
	v_mul_f32_e32 v52, 0xbfb8aa3b, v52
	v_mul_f32_e32 v53, 0xbfb8aa3b, v53
	v_exp_f32_e32 v56, v56
	v_exp_f32_e32 v57, v57
	v_exp_f32_e32 v50, v50
	v_exp_f32_e32 v51, v51
	v_exp_f32_e32 v52, v52
	v_exp_f32_e32 v53, v53
	v_add_f32_e32 v54, 1.0, v54
	v_add_f32_e32 v55, 1.0, v55
	v_lshlrev_b32_e32 v58, 16, v68
	v_and_b32_e32 v59, 0xffff0000, v68
	v_lshlrev_b32_e32 v60, 16, v69
	v_and_b32_e32 v61, 0xffff0000, v69
	v_add_f32_e32 v56, 1.0, v56
	v_add_f32_e32 v57, 1.0, v57
	v_add_f32_e32 v68, 1.0, v50
	v_add_f32_e32 v69, 1.0, v51
	v_rcp_f32_e32 v50, v54
	v_rcp_f32_e32 v51, v55
	v_lshlrev_b32_e32 v62, 16, v70
	v_and_b32_e32 v63, 0xffff0000, v70
	v_lshlrev_b32_e32 v64, 16, v71
	v_and_b32_e32 v65, 0xffff0000, v71
	v_add_f32_e32 v70, 1.0, v52
	v_add_f32_e32 v71, 1.0, v53
	v_rcp_f32_e32 v52, v56
	v_rcp_f32_e32 v53, v57
	v_rcp_f32_e32 v54, v68
	v_rcp_f32_e32 v55, v69
	v_pk_mul_f32 v[50:51], v[50:51], v[58:59]
	v_pk_mul_f32 v[58:59], v[52:53], v[60:61]
	v_pk_mul_f32 v[52:53], v[50:51], v[50:51]
	v_add_f32_e32 v68, v75, v72
	v_rcp_f32_e32 v56, v70
	v_rcp_f32_e32 v57, v71
	v_add_f32_e32 v52, v52, v68
	v_pk_mul_f32 v[60:61], v[58:59], v[58:59]
	v_add_f32_e32 v52, v53, v52
	v_pk_mul_f32 v[54:55], v[54:55], v[62:63]
	v_add_f32_e32 v52, v60, v52
	v_pk_mul_f32 v[62:63], v[54:55], v[54:55]
	v_add_f32_e32 v52, v61, v52
	v_pk_mul_f32 v[56:57], v[56:57], v[64:65]
	v_add_f32_e32 v52, v62, v52
	v_pk_mul_f32 v[64:65], v[56:57], v[56:57]
	v_add_f32_e32 v52, v63, v52
	v_add_f32_e32 v52, v64, v52
	v_add_f32_e32 v53, v65, v52
	ds_bpermute_b32 v60, v122, v53
	v_cvt_pk_bf16_f32 v52, v50, v51
	v_cvt_pk_bf16_f32 v54, v54, v55
	v_cvt_pk_bf16_f32 v55, v56, v57
	s_waitcnt lgkmcnt(0)
	v_add_f32_e32 v50, v53, v60
	ds_bpermute_b32 v51, v116, v50
	v_cvt_pk_bf16_f32 v53, v58, v59
	global_store_dwordx4 v[82:83], v[52:55], off offset:1280
	s_and_saveexec_b64 s[22:23], s[4:5]
	s_cbranch_execz .LBB0_600
	s_add_u32 s26, s36, s92
	s_addc_u32 s27, s37, s93
	v_lshl_add_u64 v[52:53], v[66:67], 4, s[26:27]
	s_lshl_b32 s52, s38, 2
	v_lshl_add_u64 v[52:53], v[52:53], 0, s[52:53]
	s_waitcnt lgkmcnt(0)
	v_add_f32_e32 v50, v50, v51
	global_store_dword v[52:53], v50, off
; __device__ __forceinline__ unsigned cvt_pk_bf16(float lo, float hi) { const f32x2 v = {lo, hi}; return __builtin_bit_cast(unsigned, __builtin_convertvector(v, bf16x2_t)); }
; __device__ __forceinline__ float bf_lo(unsigned w) { return __uint_as_float(w << 16); }
; __device__ __forceinline__ float bf_hi(unsigned w) { return __uint_as_float(w & 0xffff0000u); }
; __device__ __forceinline__ float fast_sigmoid(float v) { return __builtin_amdgcn_rcpf(1.0f + __builtin_amdgcn_exp2f(-1.4426950408889634f * v)); }
; #define ssq2 ((float*)(WSPTR() + WS_SSQ2))
;     __device__ __forceinline__ void operator()(const f32x4 (&acc)[2][2][4][2], const Unit& u, int wr, int wc, int fr, int fq) const {
;     ...
;         for (int ai = 0; ai < 2; ++ai)
; #pragma unroll
;             for (int m = 0; m < 4; ++m) {
;                 const int row = row0 + ai * HALF + m * 16;
;                 float ss = 0.f;
; #pragma unroll
;                 for (int bj = 0; bj < 2; ++bj) {
;                     const int c0 = u.pn * BM + bj * HALF + wc * 32 + 8 * fq;
;                     const u32x4 zw = *(const u32x4*)(z + (size_t)row * 512 + c0);
;                     const f32x4 b0 = *(const f32x4*)(bglu + c0), b1 = *(const f32x4*)(bglu + c0 + 4);
;                     const f32x4 a0 = acc[ai][bj][m][0] + b0, a1 = acc[ai][bj][m][1] + b1;
;                     float o[8];
;                     o[0] = bf_lo(zw.x) * fast_sigmoid(a0[0]); o[1] = bf_hi(zw.x) * fast_sigmoid(a0[1]);
;                     o[2] = bf_lo(zw.y) * fast_sigmoid(a0[2]); o[3] = bf_hi(zw.y) * fast_sigmoid(a0[3]);
;                     o[4] = bf_lo(zw.z) * fast_sigmoid(a1[0]); o[5] = bf_hi(zw.z) * fast_sigmoid(a1[1]);
;                     o[6] = bf_lo(zw.w) * fast_sigmoid(a1[2]); o[7] = bf_hi(zw.w) * fast_sigmoid(a1[3]);
; #pragma unroll
;                     for (int j = 0; j < 8; ++j) ss += o[j] * o[j];
;                     u32x4 w; w.x = cvt_pk_bf16(o[0], o[1]); w.y = cvt_pk_bf16(o[2], o[3]); w.z = cvt_pk_bf16(o[4], o[5]); w.w = cvt_pk_bf16(o[6], o[7]);
;                     *(u32x4*)(s + (size_t)row * 1024 + 512 + c0) = w;
;                 }
;                 ss += __shfl_xor(ss, 16); ss += __shfl_xor(ss, 32); if (fq == 0) ssq2[((size_t)u.pn * 32768 + row) * 4 + wc] = ss;
;             }
.LBB0_600:
	s_or_b64 exec, exec, s[22:23]
	s_mov_b32 s100, 0x28000
	s_mov_b32 s101, 0
	v_lshl_add_u64 v[228:229], v[226:227], 0, s[100:101]
	global_load_dwordx4 v[200:203], v[228:229], off
	global_load_dwordx4 v[204:207], v[228:229], off offset:256
	s_waitcnt vmcnt(2)
	v_add_u32_e32 v50, 0x90, v144
	s_waitcnt lgkmcnt(0)
	v_ashrrev_i32_e32 v51, 31, v50
	v_lshlrev_b64 v[60:61], 10, v[50:51]
	v_lshl_add_u64 v[60:61], s[76:77], 0, v[60:61]
	v_lshl_add_u64 v[64:65], v[60:61], 0, v[142:143]
	v_lshlrev_b64 v[66:67], 11, v[50:51]
	v_lshl_add_u64 v[66:67], s[78:79], 0, v[66:67]
	v_lshl_add_u64 v[66:67], v[66:67], 0, v[142:143]
	v_mov_b32_e32 v52, v184
	v_mov_b32_e32 v53, v185
	v_mov_b32_e32 v54, v186
	v_mov_b32_e32 v55, v187
	v_mov_b32_e32 v56, v188
	v_mov_b32_e32 v57, v189
	v_mov_b32_e32 v58, v190
	v_mov_b32_e32 v59, v191
	v_mov_b32_e32 v60, v210
	v_mov_b32_e32 v61, v211
	v_mov_b32_e32 v62, v212
	v_mov_b32_e32 v63, v213
	v_pk_add_f32 v[48:49], v[48:49], v[54:55]
	v_pk_add_f32 v[46:47], v[46:47], v[52:53]
	v_pk_add_f32 v[44:45], v[44:45], v[58:59]
	v_pk_add_f32 v[42:43], v[42:43], v[56:57]
	v_mul_f32_e32 v46, 0xbfb8aa3b, v46
	v_mul_f32_e32 v47, 0xbfb8aa3b, v47
	v_mul_f32_e32 v48, 0xbfb8aa3b, v48
	v_mul_f32_e32 v49, 0xbfb8aa3b, v49
	v_mul_f32_e32 v42, 0xbfb8aa3b, v42
	v_mul_f32_e32 v43, 0xbfb8aa3b, v43
	v_mul_f32_e32 v44, 0xbfb8aa3b, v44
	v_mul_f32_e32 v45, 0xbfb8aa3b, v45
	v_exp_f32_e32 v52, v46
	v_exp_f32_e32 v53, v47
	v_exp_f32_e32 v54, v48
	v_exp_f32_e32 v55, v49
	v_exp_f32_e32 v56, v42
	v_exp_f32_e32 v57, v43
	v_exp_f32_e32 v58, v44
	v_exp_f32_e32 v59, v45
	v_add_f32_e32 v52, 1.0, v52
	v_add_f32_e32 v53, 1.0, v53
	v_add_f32_e32 v54, 1.0, v54
	v_add_f32_e32 v55, 1.0, v55
	v_add_f32_e32 v56, 1.0, v56
	v_add_f32_e32 v57, 1.0, v57
	v_add_f32_e32 v58, 1.0, v58
	v_add_f32_e32 v59, 1.0, v59
	v_rcp_f32_e32 v52, v52
	v_rcp_f32_e32 v53, v53
	v_rcp_f32_e32 v54, v54
	v_rcp_f32_e32 v55, v55
	v_rcp_f32_e32 v56, v56
	v_rcp_f32_e32 v57, v57
	v_rcp_f32_e32 v58, v58
	v_rcp_f32_e32 v59, v59
	v_lshlrev_b32_e32 v42, 16, v60
	v_and_b32_e32 v43, 0xffff0000, v60
	v_lshlrev_b32_e32 v44, 16, v61
	v_and_b32_e32 v45, 0xffff0000, v61
	v_lshlrev_b32_e32 v46, 16, v62
	v_and_b32_e32 v47, 0xffff0000, v62
	v_lshlrev_b32_e32 v48, 16, v63
	v_and_b32_e32 v49, 0xffff0000, v63
	v_pk_mul_f32 v[60:61], v[52:53], v[42:43]
	v_pk_mul_f32 v[62:63], v[54:55], v[44:45]
	v_pk_mul_f32 v[56:57], v[56:57], v[46:47]
	v_pk_mul_f32 v[58:59], v[58:59], v[48:49]
	v_cvt_pk_bf16_f32 v42, v60, v61
	v_cvt_pk_bf16_f32 v43, v62, v63
	v_cvt_pk_bf16_f32 v44, v56, v57
	v_cvt_pk_bf16_f32 v45, v58, v59
	global_store_dwordx4 v[66:67], v[42:45], off offset:1024
	s_nop 0
	v_pk_mul_f32 v[60:61], v[60:61], v[60:61]
	v_pk_mul_f32 v[62:63], v[62:63], v[62:63]
	v_add_f32_e32 v60, v60, v61
	v_add_f32_e32 v60, v62, v60
	v_pk_mul_f32 v[56:57], v[56:57], v[56:57]
	v_add_f32_e32 v60, v63, v60
	v_add_f32_e32 v56, v56, v60
	v_pk_mul_f32 v[58:59], v[58:59], v[58:59]
	v_add_f32_e32 v56, v57, v56
	v_add_f32_e32 v56, v58, v56
	v_mov_b32_e32 v42, v192
	v_mov_b32_e32 v43, v193
	v_mov_b32_e32 v44, v194
	v_mov_b32_e32 v45, v195
	v_mov_b32_e32 v46, v196
	v_mov_b32_e32 v47, v197
	v_mov_b32_e32 v48, v198
	v_mov_b32_e32 v49, v199
	v_mov_b32_e32 v52, v214
	v_mov_b32_e32 v53, v215
	v_mov_b32_e32 v54, v216
	v_mov_b32_e32 v55, v217
	v_pk_add_f32 v[38:39], v[38:39], v[42:43]
	v_pk_add_f32 v[40:41], v[40:41], v[44:45]
	v_pk_add_f32 v[34:35], v[34:35], v[46:47]
	v_mul_f32_e32 v38, 0xbfb8aa3b, v38
	v_mul_f32_e32 v39, 0xbfb8aa3b, v39
	v_pk_add_f32 v[36:37], v[36:37], v[48:49]
	v_mul_f32_e32 v40, 0xbfb8aa3b, v40
	v_mul_f32_e32 v41, 0xbfb8aa3b, v41
	v_mul_f32_e32 v34, 0xbfb8aa3b, v34
	v_mul_f32_e32 v35, 0xbfb8aa3b, v35
	v_exp_f32_e32 v38, v38
	v_exp_f32_e32 v39, v39
	v_mul_f32_e32 v36, 0xbfb8aa3b, v36
	v_mul_f32_e32 v37, 0xbfb8aa3b, v37
	v_exp_f32_e32 v40, v40
	v_exp_f32_e32 v41, v41
	v_exp_f32_e32 v34, v34
	v_exp_f32_e32 v35, v35
	v_exp_f32_e32 v36, v36
	v_exp_f32_e32 v37, v37
	v_add_f32_e32 v38, 1.0, v38
	v_add_f32_e32 v39, 1.0, v39
	v_lshlrev_b32_e32 v42, 16, v52
	v_and_b32_e32 v43, 0xffff0000, v52
	v_lshlrev_b32_e32 v44, 16, v53
	v_and_b32_e32 v45, 0xffff0000, v53
	v_add_f32_e32 v40, 1.0, v40
	v_add_f32_e32 v41, 1.0, v41
	v_add_f32_e32 v52, 1.0, v34
	v_add_f32_e32 v53, 1.0, v35
	v_rcp_f32_e32 v34, v38
	v_rcp_f32_e32 v35, v39
	v_lshlrev_b32_e32 v46, 16, v54
	v_and_b32_e32 v47, 0xffff0000, v54
	v_lshlrev_b32_e32 v48, 16, v55
	v_and_b32_e32 v49, 0xffff0000, v55
	v_add_f32_e32 v54, 1.0, v36
	v_add_f32_e32 v55, 1.0, v37
	v_rcp_f32_e32 v36, v40
	v_rcp_f32_e32 v37, v41
	v_rcp_f32_e32 v38, v52
	v_rcp_f32_e32 v39, v53
	v_pk_mul_f32 v[34:35], v[34:35], v[42:43]
	v_pk_mul_f32 v[42:43], v[36:37], v[44:45]
	v_pk_mul_f32 v[36:37], v[34:35], v[34:35]
	v_add_f32_e32 v52, v59, v56
	v_rcp_f32_e32 v40, v54
	v_rcp_f32_e32 v41, v55
	v_add_f32_e32 v36, v36, v52
	v_pk_mul_f32 v[44:45], v[42:43], v[42:43]
	v_add_f32_e32 v36, v37, v36
	v_pk_mul_f32 v[38:39], v[38:39], v[46:47]
	v_add_f32_e32 v36, v44, v36
	v_pk_mul_f32 v[46:47], v[38:39], v[38:39]
	v_add_f32_e32 v36, v45, v36
	v_pk_mul_f32 v[40:41], v[40:41], v[48:49]
	v_add_f32_e32 v36, v46, v36
	v_pk_mul_f32 v[48:49], v[40:41], v[40:41]
	v_add_f32_e32 v36, v47, v36
	v_add_f32_e32 v36, v48, v36
	v_add_f32_e32 v37, v49, v36
	ds_bpermute_b32 v44, v122, v37
	v_cvt_pk_bf16_f32 v36, v34, v35
	v_cvt_pk_bf16_f32 v38, v38, v39
	v_cvt_pk_bf16_f32 v39, v40, v41
	s_waitcnt lgkmcnt(0)
	v_add_f32_e32 v34, v37, v44
	ds_bpermute_b32 v35, v116, v34
	v_cvt_pk_bf16_f32 v37, v42, v43
	global_store_dwordx4 v[66:67], v[36:39], off offset:1280
	s_and_saveexec_b64 s[22:23], s[4:5]
	s_cbranch_execz .LBB0_602
	s_add_u32 s26, s36, s92
	s_addc_u32 s27, s37, s93
	v_lshl_add_u64 v[36:37], v[50:51], 4, s[26:27]
	s_lshl_b32 s52, s38, 2
	v_lshl_add_u64 v[36:37], v[36:37], 0, s[52:53]
	s_waitcnt lgkmcnt(0)
	v_add_f32_e32 v34, v34, v35
	global_store_dword v[36:37], v34, off
; __device__ __forceinline__ unsigned cvt_pk_bf16(float lo, float hi) { const f32x2 v = {lo, hi}; return __builtin_bit_cast(unsigned, __builtin_convertvector(v, bf16x2_t)); }
; __device__ __forceinline__ float bf_lo(unsigned w) { return __uint_as_float(w << 16); }
; __device__ __forceinline__ float bf_hi(unsigned w) { return __uint_as_float(w & 0xffff0000u); }
; __device__ __forceinline__ float fast_sigmoid(float v) { return __builtin_amdgcn_rcpf(1.0f + __builtin_amdgcn_exp2f(-1.4426950408889634f * v)); }
; #define ssq2 ((float*)(WSPTR() + WS_SSQ2))
;     __device__ __forceinline__ void operator()(const f32x4 (&acc)[2][2][4][2], const Unit& u, int wr, int wc, int fr, int fq) const {
;     ...
;         for (int ai = 0; ai < 2; ++ai)
; #pragma unroll
;             for (int m = 0; m < 4; ++m) {
;                 const int row = row0 + ai * HALF + m * 16;
;                 float ss = 0.f;
; #pragma unroll
;                 for (int bj = 0; bj < 2; ++bj) {
;                     const int c0 = u.pn * BM + bj * HALF + wc * 32 + 8 * fq;
;                     const u32x4 zw = *(const u32x4*)(z + (size_t)row * 512 + c0);
;                     const f32x4 b0 = *(const f32x4*)(bglu + c0), b1 = *(const f32x4*)(bglu + c0 + 4);
;                     const f32x4 a0 = acc[ai][bj][m][0] + b0, a1 = acc[ai][bj][m][1] + b1;
;                     float o[8];
;                     o[0] = bf_lo(zw.x) * fast_sigmoid(a0[0]); o[1] = bf_hi(zw.x) * fast_sigmoid(a0[1]);
;                     o[2] = bf_lo(zw.y) * fast_sigmoid(a0[2]); o[3] = bf_hi(zw.y) * fast_sigmoid(a0[3]);
;                     o[4] = bf_lo(zw.z) * fast_sigmoid(a1[0]); o[5] = bf_hi(zw.z) * fast_sigmoid(a1[1]);
;                     o[6] = bf_lo(zw.w) * fast_sigmoid(a1[2]); o[7] = bf_hi(zw.w) * fast_sigmoid(a1[3]);
; #pragma unroll
;                     for (int j = 0; j < 8; ++j) ss += o[j] * o[j];
;                     u32x4 w; w.x = cvt_pk_bf16(o[0], o[1]); w.y = cvt_pk_bf16(o[2], o[3]); w.z = cvt_pk_bf16(o[4], o[5]); w.w = cvt_pk_bf16(o[6], o[7]);
;                     *(u32x4*)(s + (size_t)row * 1024 + 512 + c0) = w;
;                 }
;                 ss += __shfl_xor(ss, 16); ss += __shfl_xor(ss, 32); if (fq == 0) ssq2[((size_t)u.pn * 32768 + row) * 4 + wc] = ss;
;             }
.LBB0_602:
	s_or_b64 exec, exec, s[22:23]
	s_mov_b32 s100, 0x2c000
	s_mov_b32 s101, 0
	v_lshl_add_u64 v[228:229], v[226:227], 0, s[100:101]
	global_load_dwordx4 v[210:213], v[228:229], off
	global_load_dwordx4 v[214:217], v[228:229], off offset:256
	s_waitcnt vmcnt(2)
	v_add_u32_e32 v34, 0xa0, v144
	s_waitcnt lgkmcnt(0)
	v_ashrrev_i32_e32 v35, 31, v34
	v_lshlrev_b64 v[44:45], 10, v[34:35]
	v_lshl_add_u64 v[44:45], s[76:77], 0, v[44:45]
	v_lshl_add_u64 v[48:49], v[44:45], 0, v[142:143]
	v_lshlrev_b64 v[50:51], 11, v[34:35]
	v_lshl_add_u64 v[50:51], s[78:79], 0, v[50:51]
	v_lshl_add_u64 v[50:51], v[50:51], 0, v[142:143]
	v_mov_b32_e32 v36, v184
	v_mov_b32_e32 v37, v185
	v_mov_b32_e32 v38, v186
	v_mov_b32_e32 v39, v187
	v_mov_b32_e32 v40, v188
	v_mov_b32_e32 v41, v189
	v_mov_b32_e32 v42, v190
	v_mov_b32_e32 v43, v191
	v_mov_b32_e32 v44, v200
	v_mov_b32_e32 v45, v201
	v_mov_b32_e32 v46, v202
	v_mov_b32_e32 v47, v203
	v_pk_add_f32 v[32:33], v[32:33], v[38:39]
	v_pk_add_f32 v[30:31], v[30:31], v[36:37]
	v_pk_add_f32 v[28:29], v[28:29], v[42:43]
	v_pk_add_f32 v[26:27], v[26:27], v[40:41]
	v_mul_f32_e32 v30, 0xbfb8aa3b, v30
	v_mul_f32_e32 v31, 0xbfb8aa3b, v31
	v_mul_f32_e32 v32, 0xbfb8aa3b, v32
	v_mul_f32_e32 v33, 0xbfb8aa3b, v33
	v_mul_f32_e32 v26, 0xbfb8aa3b, v26
	v_mul_f32_e32 v27, 0xbfb8aa3b, v27
	v_mul_f32_e32 v28, 0xbfb8aa3b, v28
	v_mul_f32_e32 v29, 0xbfb8aa3b, v29
	v_exp_f32_e32 v36, v30
	v_exp_f32_e32 v37, v31
	v_exp_f32_e32 v38, v32
	v_exp_f32_e32 v39, v33
	v_exp_f32_e32 v40, v26
	v_exp_f32_e32 v41, v27
	v_exp_f32_e32 v42, v28
	v_exp_f32_e32 v43, v29
	v_add_f32_e32 v36, 1.0, v36
	v_add_f32_e32 v37, 1.0, v37
	v_add_f32_e32 v38, 1.0, v38
	v_add_f32_e32 v39, 1.0, v39
	v_add_f32_e32 v40, 1.0, v40
	v_add_f32_e32 v41, 1.0, v41
	v_add_f32_e32 v42, 1.0, v42
	v_add_f32_e32 v43, 1.0, v43
	v_rcp_f32_e32 v36, v36
	v_rcp_f32_e32 v37, v37
	v_rcp_f32_e32 v38, v38
	v_rcp_f32_e32 v39, v39
	v_rcp_f32_e32 v40, v40
	v_rcp_f32_e32 v41, v41
	v_rcp_f32_e32 v42, v42
	v_rcp_f32_e32 v43, v43
	v_lshlrev_b32_e32 v26, 16, v44
	v_and_b32_e32 v27, 0xffff0000, v44
	v_lshlrev_b32_e32 v28, 16, v45
	v_and_b32_e32 v29, 0xffff0000, v45
	v_lshlrev_b32_e32 v30, 16, v46
	v_and_b32_e32 v31, 0xffff0000, v46
	v_lshlrev_b32_e32 v32, 16, v47
	v_and_b32_e32 v33, 0xffff0000, v47
	v_pk_mul_f32 v[44:45], v[36:37], v[26:27]
	v_pk_mul_f32 v[46:47], v[38:39], v[28:29]
	v_pk_mul_f32 v[40:41], v[40:41], v[30:31]
	v_pk_mul_f32 v[42:43], v[42:43], v[32:33]
	v_cvt_pk_bf16_f32 v26, v44, v45
	v_cvt_pk_bf16_f32 v27, v46, v47
	v_cvt_pk_bf16_f32 v28, v40, v41
	v_cvt_pk_bf16_f32 v29, v42, v43
	global_store_dwordx4 v[50:51], v[26:29], off offset:1024
	s_nop 0
	v_pk_mul_f32 v[44:45], v[44:45], v[44:45]
	v_pk_mul_f32 v[46:47], v[46:47], v[46:47]
	v_add_f32_e32 v44, v44, v45
	v_add_f32_e32 v44, v46, v44
	v_pk_mul_f32 v[40:41], v[40:41], v[40:41]
	v_add_f32_e32 v44, v47, v44
	v_add_f32_e32 v40, v40, v44
	v_pk_mul_f32 v[42:43], v[42:43], v[42:43]
	v_add_f32_e32 v40, v41, v40
	v_add_f32_e32 v40, v42, v40
	v_mov_b32_e32 v26, v192
	v_mov_b32_e32 v27, v193
	v_mov_b32_e32 v28, v194
	v_mov_b32_e32 v29, v195
	v_mov_b32_e32 v30, v196
	v_mov_b32_e32 v31, v197
	v_mov_b32_e32 v32, v198
	v_mov_b32_e32 v33, v199
	v_mov_b32_e32 v36, v204
	v_mov_b32_e32 v37, v205
	v_mov_b32_e32 v38, v206
	v_mov_b32_e32 v39, v207
	v_pk_add_f32 v[22:23], v[22:23], v[26:27]
	v_pk_add_f32 v[24:25], v[24:25], v[28:29]
	v_pk_add_f32 v[18:19], v[18:19], v[30:31]
	v_mul_f32_e32 v22, 0xbfb8aa3b, v22
	v_mul_f32_e32 v23, 0xbfb8aa3b, v23
	v_pk_add_f32 v[20:21], v[20:21], v[32:33]
	v_mul_f32_e32 v24, 0xbfb8aa3b, v24
	v_mul_f32_e32 v25, 0xbfb8aa3b, v25
	v_mul_f32_e32 v18, 0xbfb8aa3b, v18
	v_mul_f32_e32 v19, 0xbfb8aa3b, v19
	v_exp_f32_e32 v22, v22
	v_exp_f32_e32 v23, v23
	v_mul_f32_e32 v20, 0xbfb8aa3b, v20
	v_mul_f32_e32 v21, 0xbfb8aa3b, v21
	v_exp_f32_e32 v24, v24
	v_exp_f32_e32 v25, v25
	v_exp_f32_e32 v18, v18
	v_exp_f32_e32 v19, v19
	v_exp_f32_e32 v20, v20
	v_exp_f32_e32 v21, v21
	v_add_f32_e32 v22, 1.0, v22
	v_add_f32_e32 v23, 1.0, v23
	v_lshlrev_b32_e32 v26, 16, v36
	v_and_b32_e32 v27, 0xffff0000, v36
	v_lshlrev_b32_e32 v28, 16, v37
	v_and_b32_e32 v29, 0xffff0000, v37
	v_add_f32_e32 v24, 1.0, v24
	v_add_f32_e32 v25, 1.0, v25
	v_add_f32_e32 v36, 1.0, v18
	v_add_f32_e32 v37, 1.0, v19
	v_rcp_f32_e32 v18, v22
	v_rcp_f32_e32 v19, v23
	v_lshlrev_b32_e32 v30, 16, v38
	v_and_b32_e32 v31, 0xffff0000, v38
	v_lshlrev_b32_e32 v32, 16, v39
	v_and_b32_e32 v33, 0xffff0000, v39
	v_add_f32_e32 v38, 1.0, v20
	v_add_f32_e32 v39, 1.0, v21
	v_rcp_f32_e32 v20, v24
	v_rcp_f32_e32 v21, v25
	v_rcp_f32_e32 v22, v36
	v_rcp_f32_e32 v23, v37
	v_pk_mul_f32 v[18:19], v[18:19], v[26:27]
	v_pk_mul_f32 v[26:27], v[20:21], v[28:29]
	v_pk_mul_f32 v[20:21], v[18:19], v[18:19]
	v_add_f32_e32 v36, v43, v40
	v_rcp_f32_e32 v24, v38
	v_rcp_f32_e32 v25, v39
	v_add_f32_e32 v20, v20, v36
	v_pk_mul_f32 v[28:29], v[26:27], v[26:27]
	v_add_f32_e32 v20, v21, v20
	v_pk_mul_f32 v[22:23], v[22:23], v[30:31]
	v_add_f32_e32 v20, v28, v20
	v_pk_mul_f32 v[30:31], v[22:23], v[22:23]
	v_add_f32_e32 v20, v29, v20
	v_pk_mul_f32 v[24:25], v[24:25], v[32:33]
	v_add_f32_e32 v20, v30, v20
	v_pk_mul_f32 v[32:33], v[24:25], v[24:25]
	v_add_f32_e32 v20, v31, v20
	v_add_f32_e32 v20, v32, v20
	v_add_f32_e32 v21, v33, v20
	ds_bpermute_b32 v28, v122, v21
	v_cvt_pk_bf16_f32 v20, v18, v19
	v_cvt_pk_bf16_f32 v22, v22, v23
	v_cvt_pk_bf16_f32 v23, v24, v25
	s_waitcnt lgkmcnt(0)
	v_add_f32_e32 v18, v21, v28
	ds_bpermute_b32 v19, v116, v18
	v_cvt_pk_bf16_f32 v21, v26, v27
	global_store_dwordx4 v[50:51], v[20:23], off offset:1280
	s_and_saveexec_b64 s[22:23], s[4:5]
	s_cbranch_execz .LBB0_604
	s_add_u32 s26, s36, s92
	s_addc_u32 s27, s37, s93
	v_lshl_add_u64 v[20:21], v[34:35], 4, s[26:27]
	s_lshl_b32 s52, s38, 2
	v_lshl_add_u64 v[20:21], v[20:21], 0, s[52:53]
	s_waitcnt lgkmcnt(0)
	v_add_f32_e32 v18, v18, v19
	global_store_dword v[20:21], v18, off
; __device__ __forceinline__ unsigned cvt_pk_bf16(float lo, float hi) { const f32x2 v = {lo, hi}; return __builtin_bit_cast(unsigned, __builtin_convertvector(v, bf16x2_t)); }
; __device__ __forceinline__ float bf_lo(unsigned w) { return __uint_as_float(w << 16); }
; __device__ __forceinline__ float bf_hi(unsigned w) { return __uint_as_float(w & 0xffff0000u); }
; __device__ __forceinline__ float fast_sigmoid(float v) { return __builtin_amdgcn_rcpf(1.0f + __builtin_amdgcn_exp2f(-1.4426950408889634f * v)); }
; #define ssq2 ((float*)(WSPTR() + WS_SSQ2))
;     __device__ __forceinline__ void operator()(const f32x4 (&acc)[2][2][4][2], const Unit& u, int wr, int wc, int fr, int fq) const {
;     ...
;         for (int ai = 0; ai < 2; ++ai)
; #pragma unroll
;             for (int m = 0; m < 4; ++m) {
;                 const int row = row0 + ai * HALF + m * 16;
;                 float ss = 0.f;
; #pragma unroll
;                 for (int bj = 0; bj < 2; ++bj) {
;                     const int c0 = u.pn * BM + bj * HALF + wc * 32 + 8 * fq;
;                     const u32x4 zw = *(const u32x4*)(z + (size_t)row * 512 + c0);
;                     const f32x4 b0 = *(const f32x4*)(bglu + c0), b1 = *(const f32x4*)(bglu + c0 + 4);
;                     const f32x4 a0 = acc[ai][bj][m][0] + b0, a1 = acc[ai][bj][m][1] + b1;
;                     float o[8];
;                     o[0] = bf_lo(zw.x) * fast_sigmoid(a0[0]); o[1] = bf_hi(zw.x) * fast_sigmoid(a0[1]);
;                     o[2] = bf_lo(zw.y) * fast_sigmoid(a0[2]); o[3] = bf_hi(zw.y) * fast_sigmoid(a0[3]);
;                     o[4] = bf_lo(zw.z) * fast_sigmoid(a1[0]); o[5] = bf_hi(zw.z) * fast_sigmoid(a1[1]);
;                     o[6] = bf_lo(zw.w) * fast_sigmoid(a1[2]); o[7] = bf_hi(zw.w) * fast_sigmoid(a1[3]);
; #pragma unroll
;                     for (int j = 0; j < 8; ++j) ss += o[j] * o[j];
;                     u32x4 w; w.x = cvt_pk_bf16(o[0], o[1]); w.y = cvt_pk_bf16(o[2], o[3]); w.z = cvt_pk_bf16(o[4], o[5]); w.w = cvt_pk_bf16(o[6], o[7]);
;                     *(u32x4*)(s + (size_t)row * 1024 + 512 + c0) = w;
;                 }
;                 ss += __shfl_xor(ss, 16); ss += __shfl_xor(ss, 32); if (fq == 0) ssq2[((size_t)u.pn * 32768 + row) * 4 + wc] = ss;
;             }
.LBB0_604:
	s_or_b64 exec, exec, s[22:23]
	s_waitcnt vmcnt(0)
	v_add_u32_e32 v18, 0xb0, v144
	s_waitcnt lgkmcnt(0)
	v_ashrrev_i32_e32 v19, 31, v18
	v_lshlrev_b64 v[28:29], 10, v[18:19]
	v_lshl_add_u64 v[28:29], s[76:77], 0, v[28:29]
	v_lshl_add_u64 v[32:33], v[28:29], 0, v[142:143]
	v_lshlrev_b64 v[34:35], 11, v[18:19]
	v_lshl_add_u64 v[34:35], s[78:79], 0, v[34:35]
	v_lshl_add_u64 v[34:35], v[34:35], 0, v[142:143]
	v_mov_b32_e32 v20, v184
	v_mov_b32_e32 v21, v185
	v_mov_b32_e32 v22, v186
	v_mov_b32_e32 v23, v187
	v_mov_b32_e32 v24, v188
	v_mov_b32_e32 v25, v189
	v_mov_b32_e32 v26, v190
	v_mov_b32_e32 v27, v191
	v_mov_b32_e32 v28, v210
	v_mov_b32_e32 v29, v211
	v_mov_b32_e32 v30, v212
	v_mov_b32_e32 v31, v213
	v_pk_add_f32 v[16:17], v[16:17], v[22:23]
	v_pk_add_f32 v[14:15], v[14:15], v[20:21]
	v_pk_add_f32 v[12:13], v[12:13], v[26:27]
	v_pk_add_f32 v[10:11], v[10:11], v[24:25]
	v_mul_f32_e32 v14, 0xbfb8aa3b, v14
	v_mul_f32_e32 v15, 0xbfb8aa3b, v15
	v_mul_f32_e32 v16, 0xbfb8aa3b, v16
	v_mul_f32_e32 v17, 0xbfb8aa3b, v17
	v_mul_f32_e32 v10, 0xbfb8aa3b, v10
	v_mul_f32_e32 v11, 0xbfb8aa3b, v11
	v_mul_f32_e32 v12, 0xbfb8aa3b, v12
	v_mul_f32_e32 v13, 0xbfb8aa3b, v13
	v_exp_f32_e32 v20, v14
	v_exp_f32_e32 v21, v15
	v_exp_f32_e32 v22, v16
	v_exp_f32_e32 v23, v17
	v_exp_f32_e32 v24, v10
	v_exp_f32_e32 v25, v11
	v_exp_f32_e32 v26, v12
	v_exp_f32_e32 v27, v13
	v_add_f32_e32 v20, 1.0, v20
	v_add_f32_e32 v21, 1.0, v21
	v_add_f32_e32 v22, 1.0, v22
	v_add_f32_e32 v23, 1.0, v23
	v_add_f32_e32 v24, 1.0, v24
	v_add_f32_e32 v25, 1.0, v25
	v_add_f32_e32 v26, 1.0, v26
	v_add_f32_e32 v27, 1.0, v27
	v_rcp_f32_e32 v20, v20
	v_rcp_f32_e32 v21, v21
	v_rcp_f32_e32 v22, v22
	v_rcp_f32_e32 v23, v23
	v_rcp_f32_e32 v24, v24
	v_rcp_f32_e32 v25, v25
	v_rcp_f32_e32 v26, v26
	v_rcp_f32_e32 v27, v27
	v_lshlrev_b32_e32 v10, 16, v28
	v_and_b32_e32 v11, 0xffff0000, v28
	v_lshlrev_b32_e32 v12, 16, v29
	v_and_b32_e32 v13, 0xffff0000, v29
	v_lshlrev_b32_e32 v14, 16, v30
	v_and_b32_e32 v15, 0xffff0000, v30
	v_lshlrev_b32_e32 v16, 16, v31
	v_and_b32_e32 v17, 0xffff0000, v31
	v_pk_mul_f32 v[28:29], v[20:21], v[10:11]
	v_pk_mul_f32 v[30:31], v[22:23], v[12:13]
	v_pk_mul_f32 v[24:25], v[24:25], v[14:15]
	v_pk_mul_f32 v[26:27], v[26:27], v[16:17]
	v_cvt_pk_bf16_f32 v10, v28, v29
	v_cvt_pk_bf16_f32 v11, v30, v31
	v_cvt_pk_bf16_f32 v12, v24, v25
	v_cvt_pk_bf16_f32 v13, v26, v27
	global_store_dwordx4 v[34:35], v[10:13], off offset:1024
	s_nop 0
	v_pk_mul_f32 v[28:29], v[28:29], v[28:29]
	v_pk_mul_f32 v[30:31], v[30:31], v[30:31]
	v_add_f32_e32 v28, v28, v29
	v_add_f32_e32 v28, v30, v28
	v_pk_mul_f32 v[24:25], v[24:25], v[24:25]
	v_add_f32_e32 v28, v31, v28
	v_add_f32_e32 v24, v24, v28
	v_pk_mul_f32 v[26:27], v[26:27], v[26:27]
	v_add_f32_e32 v24, v25, v24
	v_add_f32_e32 v24, v26, v24
	v_mov_b32_e32 v10, v192
	v_mov_b32_e32 v11, v193
	v_mov_b32_e32 v12, v194
	v_mov_b32_e32 v13, v195
	v_mov_b32_e32 v14, v196
	v_mov_b32_e32 v15, v197
	v_mov_b32_e32 v16, v198
	v_mov_b32_e32 v17, v199
	v_mov_b32_e32 v20, v214
	v_mov_b32_e32 v21, v215
	v_mov_b32_e32 v22, v216
	v_mov_b32_e32 v23, v217
	v_pk_add_f32 v[6:7], v[6:7], v[10:11]
	v_pk_add_f32 v[8:9], v[8:9], v[12:13]
	v_pk_add_f32 v[2:3], v[2:3], v[14:15]
	v_mul_f32_e32 v6, 0xbfb8aa3b, v6
	v_mul_f32_e32 v7, 0xbfb8aa3b, v7
	v_pk_add_f32 v[4:5], v[4:5], v[16:17]
	v_mul_f32_e32 v8, 0xbfb8aa3b, v8
	v_mul_f32_e32 v9, 0xbfb8aa3b, v9
	v_mul_f32_e32 v2, 0xbfb8aa3b, v2
	v_mul_f32_e32 v3, 0xbfb8aa3b, v3
	v_exp_f32_e32 v6, v6
	v_exp_f32_e32 v7, v7
	v_mul_f32_e32 v4, 0xbfb8aa3b, v4
	v_mul_f32_e32 v5, 0xbfb8aa3b, v5
	v_exp_f32_e32 v8, v8
	v_exp_f32_e32 v9, v9
	v_exp_f32_e32 v2, v2
	v_exp_f32_e32 v3, v3
	v_exp_f32_e32 v4, v4
	v_exp_f32_e32 v5, v5
	v_add_f32_e32 v6, 1.0, v6
	v_add_f32_e32 v7, 1.0, v7
	v_lshlrev_b32_e32 v10, 16, v20
	v_and_b32_e32 v11, 0xffff0000, v20
	v_lshlrev_b32_e32 v12, 16, v21
	v_and_b32_e32 v13, 0xffff0000, v21
	v_add_f32_e32 v8, 1.0, v8
	v_add_f32_e32 v9, 1.0, v9
	v_add_f32_e32 v20, 1.0, v2
	v_add_f32_e32 v21, 1.0, v3
	v_rcp_f32_e32 v2, v6
	v_rcp_f32_e32 v3, v7
	v_lshlrev_b32_e32 v14, 16, v22
	v_and_b32_e32 v15, 0xffff0000, v22
	v_lshlrev_b32_e32 v16, 16, v23
	v_and_b32_e32 v17, 0xffff0000, v23
	v_add_f32_e32 v22, 1.0, v4
	v_add_f32_e32 v23, 1.0, v5
	v_rcp_f32_e32 v4, v8
	v_rcp_f32_e32 v5, v9
	v_rcp_f32_e32 v6, v20
	v_rcp_f32_e32 v7, v21
	v_pk_mul_f32 v[2:3], v[2:3], v[10:11]
	v_pk_mul_f32 v[10:11], v[4:5], v[12:13]
	v_pk_mul_f32 v[4:5], v[2:3], v[2:3]
	v_add_f32_e32 v20, v27, v24
	v_rcp_f32_e32 v8, v22
	v_rcp_f32_e32 v9, v23
	v_add_f32_e32 v4, v4, v20
	v_pk_mul_f32 v[12:13], v[10:11], v[10:11]
	v_add_f32_e32 v4, v5, v4
	v_pk_mul_f32 v[6:7], v[6:7], v[14:15]
	v_add_f32_e32 v4, v12, v4
	v_pk_mul_f32 v[14:15], v[6:7], v[6:7]
	v_add_f32_e32 v4, v13, v4
	v_pk_mul_f32 v[8:9], v[8:9], v[16:17]
	v_add_f32_e32 v4, v14, v4
	v_pk_mul_f32 v[16:17], v[8:9], v[8:9]
	v_add_f32_e32 v4, v15, v4
	v_add_f32_e32 v4, v16, v4
	v_add_f32_e32 v5, v17, v4
	ds_bpermute_b32 v12, v122, v5
	v_cvt_pk_bf16_f32 v4, v2, v3
	v_cvt_pk_bf16_f32 v6, v6, v7
	v_cvt_pk_bf16_f32 v7, v8, v9
	s_waitcnt lgkmcnt(0)
	v_add_f32_e32 v2, v5, v12
	ds_bpermute_b32 v3, v116, v2
	v_cvt_pk_bf16_f32 v5, v10, v11
	global_store_dwordx4 v[34:35], v[4:7], off offset:1280
	s_and_saveexec_b64 s[22:23], s[4:5]
	s_cbranch_execz .LBB0_606
	s_add_u32 s26, s36, s92
	s_addc_u32 s27, s37, s93
	v_lshl_add_u64 v[4:5], v[18:19], 4, s[26:27]
	s_lshl_b32 s52, s38, 2
	v_lshl_add_u64 v[4:5], v[4:5], 0, s[52:53]
	s_waitcnt lgkmcnt(0)
	v_add_f32_e32 v2, v2, v3
	global_store_dword v[4:5], v2, off

; __device__ __forceinline__ void attn_phase(const Args& a, LAS unsigned char* lds, int layer, int G, int vb) {
;     ...
;         float m = sinkv, lsum = 1.0f;
;         f32x16 o0, o1;
; #pragma unroll
;         for (int r = 0; r < 16; ++r) { o0[r] = 0.f; o1[r] = 0.f; }
;         const bf16* vbase = vT + ((size_t)(b * 2 + kvh) * 64 + ql) * SEQ + 4 * hi;
;         const bf16* kbase = proj + (size_t)(b * SEQ + ql) * DIN + 512 + kvh * 64 + 8 * hi;
;         const int rb = ui >> 3, kt_lo = (4 - rb) > 0 ? (4 - rb) : 0, kt_hi = (132 - rb) < 9 ? (132 - rb) : 9;
;         bf16x8 kf[4]; s16x4 vf[2][2][2];
;     ...
;         bf16x8 kg[4]; s16x4 vg[2][2][2];
.Latt_unit:
	v_mov_b32_e32 v140, v183
	v_mov_b32_e32 v141, 1.0
	v_mov_b32_e32 v24, 0
	v_mov_b32_e32 v25, 0
	v_mov_b32_e32 v26, 0
	v_mov_b32_e32 v27, 0
	v_mov_b32_e32 v28, 0
	v_mov_b32_e32 v29, 0
	v_mov_b32_e32 v30, 0
	v_mov_b32_e32 v31, 0
	v_mov_b32_e32 v32, 0
	v_mov_b32_e32 v33, 0
	v_mov_b32_e32 v34, 0
	v_mov_b32_e32 v35, 0
	v_mov_b32_e32 v36, 0
	v_mov_b32_e32 v37, 0
	v_mov_b32_e32 v38, 0
	v_mov_b32_e32 v39, 0
	v_mov_b32_e32 v46, 0
	v_mov_b32_e32 v47, 0
	v_mov_b32_e32 v48, 0
	v_mov_b32_e32 v49, 0
	v_mov_b32_e32 v50, 0
	v_mov_b32_e32 v51, 0
	v_mov_b32_e32 v52, 0
	v_mov_b32_e32 v53, 0
	v_mov_b32_e32 v54, 0
	v_mov_b32_e32 v55, 0
	v_mov_b32_e32 v56, 0
	v_mov_b32_e32 v57, 0
	v_mov_b32_e32 v58, 0
	v_mov_b32_e32 v59, 0
	v_mov_b32_e32 v60, 0
	v_mov_b32_e32 v61, 0
	s_mov_b32 s28, 0
	s_add_i32 s29, s28, 2
	s_and_b32 s29, s29, 3
	s_lshl_b32 s29, s29, 14
	s_add_i32 s29, s29, s92
	s_mov_b32 m0, s29
	s_and_b32 s32, s28, 3
	global_load_lds_dwordx4 v5, s[6:7]
	s_add_i32 m0, s29, 0x1000
	s_add_u32 s6, s6, 0x14000
	s_addc_u32 s7, s7, 0
	global_load_lds_dwordx4 v6, s[8:9]
	s_add_u32 s8, s8, 64
	s_addc_u32 s9, s9, 0
	s_lshl_b32 s32, s32, 14
	s_add_i32 s32, s32, s93
	v_add_u32_e32 v150, s32, v142
	v_add_u32_e32 v151, s32, v143
	v_add_u32_e32 v152, s32, v144
	v_add_u32_e32 v153, s32, v145
	v_add_u32_e32 v154, s32, v146
	v_add_u32_e32 v155, s32, v147
	v_add_u32_e32 v156, s32, v148
	v_add_u32_e32 v158, s32, v149
	v_add_u32_e32 v159, s36, v7
	s_waitcnt vmcnt(5)
	s_barrier
	ds_read2_b32 v[64:65], v159 offset0:0 offset1:1
	ds_read2_b32 v[66:67], v159 offset0:2 offset1:3
	ds_read2_b32 v[68:69], v159 offset0:8 offset1:9
	ds_read2_b32 v[70:71], v159 offset0:10 offset1:11
	ds_read2_b32 v[72:73], v159 offset0:16 offset1:17
	ds_read2_b32 v[74:75], v159 offset0:18 offset1:19
	ds_read2_b32 v[76:77], v159 offset0:24 offset1:25
	ds_read2_b32 v[78:79], v159 offset0:26 offset1:27
	ds_read_b128 v[80:83], v150
	ds_read_b128 v[84:87], v151
	ds_read_b128 v[88:91], v152
	ds_read_b128 v[92:95], v153
	s_add_i32 s36, s36, 0x80
	s_waitcnt lgkmcnt(0)
	v_mfma_f32_32x32x16_bf16 v[64:79], v[80:83], v[8:11], v[64:79]
	v_mfma_f32_32x32x16_bf16 v[64:79], v[84:87], v[12:15], v[64:79]
	v_mfma_f32_32x32x16_bf16 v[64:79], v[88:91], v[16:19], v[64:79]
	v_mfma_f32_32x32x16_bf16 v[64:79], v[92:95], v[20:23], v[64:79]
	ds_read_b64 v[112:113], v154
	ds_read_b64 v[114:115], v155
	ds_read_b64 v[116:117], v156
	ds_read_b64 v[118:119], v158
	ds_read_b64 v[120:121], v154 offset:2048
	ds_read_b64 v[122:123], v155 offset:2048
	ds_read_b64 v[124:125], v156 offset:2048
	ds_read_b64 v[126:127], v158 offset:2048
	s_nop 3
	v_max3_f32 v184, v64, v65, v66
	v_max3_f32 v184, v184, v67, v68
	v_max3_f32 v184, v184, v69, v70
	v_max3_f32 v184, v184, v71, v72
	v_max3_f32 v184, v184, v73, v74
	v_max3_f32 v184, v184, v75, v76
	v_max3_f32 v184, v184, v77, v78
	v_max_f32_e32 v184, v184, v79
	v_mov_b32_e32 v185, v184
	s_nop 1
	v_permlane32_swap_b32_e32 v184, v185
	v_max_f32_e32 v184, v184, v185
	v_cmp_gt_f32_e32 vcc, v184, v140
	s_cbranch_vccz .Latt_norescalep0
	v_max_f32_e32 v185, v140, v184
	v_sub_f32_e32 v186, v140, v185
	v_exp_f32_e32 v186, v186
	v_mov_b32_e32 v140, v185
	v_mov_b32_e32 v187, v1
	v_mul_f32_e32 v141, v141, v186
	v_pk_mul_f32 v[24:25], v[24:25], v[186:187] op_sel_hi:[1,0]
	v_pk_mul_f32 v[26:27], v[26:27], v[186:187] op_sel_hi:[1,0]
	v_pk_mul_f32 v[28:29], v[28:29], v[186:187] op_sel_hi:[1,0]
	v_pk_mul_f32 v[30:31], v[30:31], v[186:187] op_sel_hi:[1,0]
	v_pk_mul_f32 v[32:33], v[32:33], v[186:187] op_sel_hi:[1,0]
	v_pk_mul_f32 v[34:35], v[34:35], v[186:187] op_sel_hi:[1,0]
	v_pk_mul_f32 v[36:37], v[36:37], v[186:187] op_sel_hi:[1,0]
	v_pk_mul_f32 v[38:39], v[38:39], v[186:187] op_sel_hi:[1,0]
	v_pk_mul_f32 v[46:47], v[46:47], v[186:187] op_sel_hi:[1,0]
	v_pk_mul_f32 v[48:49], v[48:49], v[186:187] op_sel_hi:[1,0]
	v_pk_mul_f32 v[50:51], v[50:51], v[186:187] op_sel_hi:[1,0]
	v_pk_mul_f32 v[52:53], v[52:53], v[186:187] op_sel_hi:[1,0]
	v_pk_mul_f32 v[54:55], v[54:55], v[186:187] op_sel_hi:[1,0]
	v_pk_mul_f32 v[56:57], v[56:57], v[186:187] op_sel_hi:[1,0]
	v_pk_mul_f32 v[58:59], v[58:59], v[186:187] op_sel_hi:[1,0]
	v_pk_mul_f32 v[60:61], v[60:61], v[186:187] op_sel_hi:[1,0]
.Latt_norescalep0:
	v_sub_f32_e32 v64, v64, v140
	v_sub_f32_e32 v65, v65, v140
	v_sub_f32_e32 v66, v66, v140
	v_sub_f32_e32 v67, v67, v140
	v_sub_f32_e32 v68, v68, v140
	v_sub_f32_e32 v69, v69, v140
	v_sub_f32_e32 v70, v70, v140
	v_sub_f32_e32 v71, v71, v140
	v_sub_f32_e32 v72, v72, v140
	v_sub_f32_e32 v73, v73, v140
	v_sub_f32_e32 v74, v74, v140
	v_sub_f32_e32 v75, v75, v140
	v_sub_f32_e32 v76, v76, v140
	v_sub_f32_e32 v77, v77, v140
	v_sub_f32_e32 v78, v78, v140
	v_sub_f32_e32 v79, v79, v140
	v_exp_f32_e32 v64, v64
	v_exp_f32_e32 v65, v65
	v_exp_f32_e32 v66, v66
	v_exp_f32_e32 v67, v67
	v_exp_f32_e32 v68, v68
	v_exp_f32_e32 v69, v69
	v_exp_f32_e32 v70, v70
	v_exp_f32_e32 v71, v71
	v_exp_f32_e32 v72, v72
	v_exp_f32_e32 v73, v73
	v_exp_f32_e32 v74, v74
	v_exp_f32_e32 v75, v75
	v_exp_f32_e32 v76, v76
	v_exp_f32_e32 v77, v77
	v_exp_f32_e32 v78, v78
	v_exp_f32_e32 v79, v79
	v_add_f32_e32 v188, v64, v65
	v_add_f32_e32 v189, v66, v67
	v_add_f32_e32 v190, v68, v69
	v_add_f32_e32 v191, v70, v71
	v_add_f32_e32 v192, v72, v73
	v_add_f32_e32 v193, v74, v75
	v_add_f32_e32 v194, v76, v77
	v_add_f32_e32 v195, v78, v79
	v_add_f32_e32 v188, v188, v189
	v_add_f32_e32 v189, v190, v191
	v_add_f32_e32 v190, v192, v193
	v_add_f32_e32 v191, v194, v195
	v_add_f32_e32 v188, v188, v189
	v_add_f32_e32 v190, v190, v191
	v_add_f32_e32 v188, v188, v190
	v_mov_b32_e32 v189, v188
	v_cvt_pk_bf16_f32 v128, v64, v65
	v_cvt_pk_bf16_f32 v129, v66, v67
	v_cvt_pk_bf16_f32 v130, v68, v69
	v_cvt_pk_bf16_f32 v131, v70, v71
	v_permlane32_swap_b32_e32 v188, v189
	v_cvt_pk_bf16_f32 v136, v72, v73
	v_cvt_pk_bf16_f32 v137, v74, v75
	v_cvt_pk_bf16_f32 v138, v76, v77
	v_cvt_pk_bf16_f32 v139, v78, v79
	v_add_f32_e32 v188, v188, v189
	v_add_f32_e32 v141, v141, v188
	s_waitcnt lgkmcnt(0)
	v_mfma_f32_32x32x16_bf16 v[24:39], v[112:115], v[128:131], v[24:39]
	v_mfma_f32_32x32x16_bf16 v[46:61], v[120:123], v[128:131], v[46:61]
	v_mfma_f32_32x32x16_bf16 v[24:39], v[116:119], v[136:139], v[24:39]
	v_mfma_f32_32x32x16_bf16 v[46:61], v[124:127], v[136:139], v[46:61]
	s_add_i32 s28, s28, 1
	s_add_i32 s29, s28, 2
	s_and_b32 s29, s29, 3
	s_lshl_b32 s29, s29, 14
	s_add_i32 s29, s29, s92
	s_mov_b32 m0, s29
	s_and_b32 s32, s28, 3
	global_load_lds_dwordx4 v5, s[6:7]
	s_add_i32 m0, s29, 0x1000
	s_add_u32 s6, s6, 0x14000
	s_addc_u32 s7, s7, 0
	global_load_lds_dwordx4 v6, s[8:9]
	s_add_u32 s8, s8, 64
	s_addc_u32 s9, s9, 0
	s_lshl_b32 s32, s32, 14
	s_add_i32 s32, s32, s93
	v_add_u32_e32 v150, s32, v142
	v_add_u32_e32 v151, s32, v143
	v_add_u32_e32 v152, s32, v144
	v_add_u32_e32 v153, s32, v145
	v_add_u32_e32 v154, s32, v146
	v_add_u32_e32 v155, s32, v147
	v_add_u32_e32 v156, s32, v148
	v_add_u32_e32 v158, s32, v149
	v_add_u32_e32 v159, s36, v7
	s_waitcnt vmcnt(5)
	s_barrier
	ds_read2_b32 v[64:65], v159 offset0:0 offset1:1
	ds_read2_b32 v[66:67], v159 offset0:2 offset1:3
	ds_read2_b32 v[68:69], v159 offset0:8 offset1:9
	ds_read2_b32 v[70:71], v159 offset0:10 offset1:11
	ds_read2_b32 v[72:73], v159 offset0:16 offset1:17
	ds_read2_b32 v[74:75], v159 offset0:18 offset1:19
	ds_read2_b32 v[76:77], v159 offset0:24 offset1:25
	ds_read2_b32 v[78:79], v159 offset0:26 offset1:27
	ds_read_b128 v[80:83], v150
	ds_read_b128 v[84:87], v151
	ds_read_b128 v[88:91], v152
	ds_read_b128 v[92:95], v153
	s_add_i32 s36, s36, 0x80
	s_waitcnt lgkmcnt(0)
	v_mfma_f32_32x32x16_bf16 v[64:79], v[80:83], v[8:11], v[64:79]
	v_mfma_f32_32x32x16_bf16 v[64:79], v[84:87], v[12:15], v[64:79]
	v_mfma_f32_32x32x16_bf16 v[64:79], v[88:91], v[16:19], v[64:79]
	v_mfma_f32_32x32x16_bf16 v[64:79], v[92:95], v[20:23], v[64:79]
	ds_read_b64 v[112:113], v154
	ds_read_b64 v[114:115], v155
	ds_read_b64 v[116:117], v156
	ds_read_b64 v[118:119], v158
	ds_read_b64 v[120:121], v154 offset:2048
	ds_read_b64 v[122:123], v155 offset:2048
	ds_read_b64 v[124:125], v156 offset:2048
	ds_read_b64 v[126:127], v158 offset:2048
	s_nop 3
	v_max3_f32 v184, v64, v65, v66
	v_max3_f32 v184, v184, v67, v68
	v_max3_f32 v184, v184, v69, v70
	v_max3_f32 v184, v184, v71, v72
	v_max3_f32 v184, v184, v73, v74
	v_max3_f32 v184, v184, v75, v76
	v_max3_f32 v184, v184, v77, v78
	v_max_f32_e32 v184, v184, v79
	v_mov_b32_e32 v185, v184
	s_nop 1
	v_permlane32_swap_b32_e32 v184, v185
	v_max_f32_e32 v184, v184, v185
	v_cmp_gt_f32_e32 vcc, v184, v140
	s_cbranch_vccz .Latt_norescalep1
	v_max_f32_e32 v185, v140, v184
	v_sub_f32_e32 v186, v140, v185
	v_exp_f32_e32 v186, v186
	v_mov_b32_e32 v140, v185
	v_mov_b32_e32 v187, v1
	v_mul_f32_e32 v141, v141, v186
	v_pk_mul_f32 v[24:25], v[24:25], v[186:187] op_sel_hi:[1,0]
	v_pk_mul_f32 v[26:27], v[26:27], v[186:187] op_sel_hi:[1,0]
	v_pk_mul_f32 v[28:29], v[28:29], v[186:187] op_sel_hi:[1,0]
	v_pk_mul_f32 v[30:31], v[30:31], v[186:187] op_sel_hi:[1,0]
	v_pk_mul_f32 v[32:33], v[32:33], v[186:187] op_sel_hi:[1,0]
	v_pk_mul_f32 v[34:35], v[34:35], v[186:187] op_sel_hi:[1,0]
	v_pk_mul_f32 v[36:37], v[36:37], v[186:187] op_sel_hi:[1,0]
	v_pk_mul_f32 v[38:39], v[38:39], v[186:187] op_sel_hi:[1,0]
	v_pk_mul_f32 v[46:47], v[46:47], v[186:187] op_sel_hi:[1,0]
	v_pk_mul_f32 v[48:49], v[48:49], v[186:187] op_sel_hi:[1,0]
	v_pk_mul_f32 v[50:51], v[50:51], v[186:187] op_sel_hi:[1,0]
	v_pk_mul_f32 v[52:53], v[52:53], v[186:187] op_sel_hi:[1,0]
	v_pk_mul_f32 v[54:55], v[54:55], v[186:187] op_sel_hi:[1,0]
	v_pk_mul_f32 v[56:57], v[56:57], v[186:187] op_sel_hi:[1,0]
	v_pk_mul_f32 v[58:59], v[58:59], v[186:187] op_sel_hi:[1,0]
	v_pk_mul_f32 v[60:61], v[60:61], v[186:187] op_sel_hi:[1,0]

; #define INP(k) inptr(k)
; #define WSPTR() kptr(224)
; #define OUTPTR() ((float*)kptr(216))
; __device__ __forceinline__ float bflo(unsigned w) { return __uint_as_float(w << 16); }
; __device__ __forceinline__ float bfhi(unsigned w) { return __uint_as_float(w & 0xffff0000u); }
; #define ssq ((float*)(WSPTR() + WS_SSQ))
; __device__ __forceinline__ void final_norm(const Args& a, int G, int vb) {
;     int tid_ = threadIdx.x; asm volatile("" : "+v"(tid_));
;     const int tid = tid_, lane = tid & 63, wave = __builtin_amdgcn_readfirstlane(tid >> 6);
;     const int gw = vb * NWAVES + wave, NGW = G * NWAVES;
;     const float* ssq = (const float*)(WSPTR() + WS_SSQ); const bf16* xb = (const bf16*)(WSPTR() + WS_XB); float* out = OUTPTR();
;     const f32x4* gn = (const f32x4*)INP(26) + 2 * lane;
;     f32x4 gv[2][2];
; #pragma unroll
;     for (int j = 0; j < 2; ++j) { gv[j][0] = gn[128 * j]; gv[j][1] = gn[128 * j + 1]; }
;     for (int mi = gw; mi < NT; mi += NGW) {
;         const int m = XCD_ROW(mi);
;         float s = (lane < 16) ? ssq[((size_t)(lane >> 2) * NT + m) * 4 + (lane & 3)] : 0.f; s = wave_sum(s);
;         const float rs = __builtin_amdgcn_rsqf(s * (1.0f / 1024.0f) + 1e-6f);
;         const u32x4* xr = (const u32x4*)(xb + (size_t)m * DM) + lane; f32x4* orow = (f32x4*)(out + (size_t)m * DM) + 2 * lane;
; #pragma unroll
;         for (int j = 0; j < 2; ++j) { const u32x4 w = xr[64 * j];
;             orow[128 * j] = (f32x4){bflo(w.x), bfhi(w.x), bflo(w.y), bfhi(w.y)} * rs * gv[j][0];
;             orow[128 * j + 1] = (f32x4){bflo(w.z), bfhi(w.z), bflo(w.w), bfhi(w.w)} * rs * gv[j][1]; }
;     }
.LBB0_826:
	v_readlane_b32 s3, v254, 0
	v_readfirstlane_b32 s5, v209
	s_ashr_i32 s4, s5, 6
	s_add_i32 s3, s4, s3
	s_movk_i32 s8, 0xe0
	s_movk_i32 s9, 0xe0
	s_movk_i32 s7, 0xd8
	s_movk_i32 s6, 0xd0
	s_cmpk_gt_i32 s3, 0x7fff
	s_cbranch_scc1 .LBB0_831
	s_ashr_i32 s11, s9, 31
	s_add_u32 s10, s0, s9
	s_addc_u32 s11, s1, s11
	s_ashr_i32 s9, s8, 31
	s_add_u32 s8, s0, s8
	s_addc_u32 s9, s1, s9
	s_ashr_i32 s13, s7, 31
	s_add_u32 s12, s0, s7
	s_addc_u32 s13, s1, s13
	s_ashr_i32 s7, s6, 31
	s_add_u32 s0, s0, s6
	s_addc_u32 s1, s1, s7
	s_load_dwordx2 s[0:1], s[0:1], 0x0
	v_and_b32_e32 v22, 63, v209
	v_lshlrev_b32_e32 v16, 5, v22
	s_waitcnt lgkmcnt(0)
	global_load_dwordx4 v[0:3], v16, s[0:1] offset:16
	global_load_dwordx4 v[4:7], v16, s[0:1]
	global_load_dwordx4 v[8:11], v16, s[0:1] offset:2064
	global_load_dwordx4 v[12:15], v16, s[0:1] offset:2048
	s_load_dwordx2 s[0:1], s[12:13], 0x0
	s_load_dwordx2 s[6:7], s[10:11], 0x0
	s_load_dwordx2 s[14:15], s[8:9], 0x0
	v_mov_b32_e32 v17, 0
	v_and_b32_e32 v20, 3, v209
	v_lshlrev_b32_e32 v20, 2, v20
	v_mov_b32_e32 v21, v17
	v_and_b32_e32 v23, 64, v218
	s_waitcnt lgkmcnt(0)
	v_lshl_add_u64 v[18:19], s[0:1], 0, v[16:17]
	v_lshl_add_u64 v[20:21], s[6:7], 0, v[20:21]
	s_mov_b64 s[0:1], 0x1d200000
	v_add_u32_e32 v23, 64, v23
	v_xor_b32_e32 v24, 1, v218
	v_lshl_add_u64 v[20:21], v[20:21], 0, s[0:1]
	v_cmp_lt_i32_e64 s[0:1], v24, v23
	v_xor_b32_e32 v25, 2, v218
	v_xor_b32_e32 v26, 4, v218
	v_cndmask_b32_e64 v24, v218, v24, s[0:1]
	v_cmp_lt_i32_e64 s[0:1], v25, v23
	v_xor_b32_e32 v27, 8, v218
	v_xor_b32_e32 v28, 16, v218
	v_cndmask_b32_e64 v25, v218, v25, s[0:1]
	v_cmp_lt_i32_e64 s[0:1], v26, v23
	v_xor_b32_e32 v29, 32, v218
	v_cmp_gt_u32_e32 vcc, 16, v22
	v_cndmask_b32_e64 v26, v218, v26, s[0:1]
	v_cmp_lt_i32_e64 s[0:1], v27, v23
	v_lshlrev_b32_e32 v22, 4, v22
	v_lshlrev_b32_e32 v16, 13, v209
	v_cndmask_b32_e64 v27, v218, v27, s[0:1]
	v_cmp_lt_i32_e64 s[0:1], v28, v23
	v_and_b32_e32 v16, 0x18000, v16
	v_lshlrev_b32_e32 v24, 2, v24
	v_cndmask_b32_e64 v28, v218, v28, s[0:1]
	v_cmp_lt_i32_e64 s[0:1], v29, v23
	v_lshlrev_b32_e32 v25, 2, v25
	v_lshlrev_b32_e32 v26, 2, v26
	v_cndmask_b32_e64 v23, v218, v29, s[0:1]
	v_lshlrev_b32_e32 v29, 2, v23
	v_mov_b32_e32 v23, v17
	v_lshl_add_u64 v[22:23], s[14:15], 0, v[22:23]
	s_mov_b64 s[0:1], 0x9800000
	v_lshl_add_u64 v[22:23], v[22:23], 0, s[0:1]
	s_lshl_b32 s0, s33, 12
	s_lshl_b32 s1, s4, 9
	v_lshlrev_b32_e32 v27, 2, v27
	v_lshlrev_b32_e32 v28, 2, v28
	s_bfe_u32 s6, s5, 0x30006
	s_add_i32 s7, s0, s1
	s_lshl_b32 s8, s20, 12
	v_mov_b32_e32 v30, 0x358637bd
	s_cmpk_lg_i32 s2, 0x800
	s_cbranch_scc1 .LBB0_829
	s_ashr_i32 s1, s3, 3
	s_and_b32 s0, s7, 0x7000
	s_and_b32 s1, s1, -8
	s_add_i32 s0, s0, s1
	s_or_b32 s0, s0, s6
	s_ashr_i32 s1, s0, 31
	s_add_i32 s3, s3, s2
	s_add_i32 s7, s7, s8
	v_mov_b32_e32 v31, 0
	s_and_saveexec_b64 s[4:5], vcc
	v_lshl_add_u64 v[54:55], s[0:1], 0, v[16:17]
	v_lshl_add_u64 v[54:55], v[54:55], 4, v[20:21]
	global_load_dword v31, v[54:55], off
	s_or_b64 exec, exec, s[4:5]
	s_lshl_b64 s[4:5], s[0:1], 11
	v_lshl_add_u64 v[54:55], v[22:23], 0, s[4:5]
	global_load_dwordx4 v[32:35], v[54:55], off
	global_load_dwordx4 v[36:39], v[54:55], off offset:1024
	s_lshl_b64 s[4:5], s[0:1], 12
	v_lshl_add_u64 v[40:41], v[18:19], 0, s[4:5]
	s_ashr_i32 s1, s3, 3
	s_and_b32 s0, s7, 0x7000
	s_and_b32 s1, s1, -8
	s_add_i32 s0, s0, s1
	s_or_b32 s0, s0, s6
	s_ashr_i32 s1, s0, 31
	s_add_i32 s3, s3, s2
	s_add_i32 s7, s7, s8
	v_mov_b32_e32 v42, 0
	s_and_saveexec_b64 s[4:5], vcc
	v_lshl_add_u64 v[54:55], s[0:1], 0, v[16:17]
	v_lshl_add_u64 v[54:55], v[54:55], 4, v[20:21]
	global_load_dword v42, v[54:55], off
	s_or_b64 exec, exec, s[4:5]
	s_lshl_b64 s[4:5], s[0:1], 11
	v_lshl_add_u64 v[54:55], v[22:23], 0, s[4:5]
	global_load_dwordx4 v[44:47], v[54:55], off
	global_load_dwordx4 v[48:51], v[54:55], off offset:1024
	s_lshl_b64 s[4:5], s[0:1], 12
	v_lshl_add_u64 v[52:53], v[18:19], 0, s[4:5]
	s_waitcnt vmcnt(3)
	ds_bpermute_b32 v56, v24, v31
	s_waitcnt lgkmcnt(0)
	v_add_f32_e32 v31, v31, v56
	ds_bpermute_b32 v56, v25, v31
	s_waitcnt lgkmcnt(0)
	v_add_f32_e32 v31, v31, v56
	ds_bpermute_b32 v56, v26, v31
	s_waitcnt lgkmcnt(0)
	v_add_f32_e32 v31, v31, v56
	ds_bpermute_b32 v56, v27, v31
	s_waitcnt lgkmcnt(0)
	v_add_f32_e32 v31, v31, v56
	ds_bpermute_b32 v56, v28, v31
	s_waitcnt lgkmcnt(0)
	v_add_f32_e32 v31, v31, v56
	ds_bpermute_b32 v56, v29, v31
	s_waitcnt lgkmcnt(0)
	v_add_f32_e32 v31, v31, v56
	v_fmamk_f32 v31, v31, 0x3a800000, v30
	v_rsq_f32_e32 v80, v31
	v_mov_b32_e32 v81, v17
	v_lshlrev_b32_e32 v56, 16, v32
	v_and_b32_e32 v57, 0xffff0000, v32
	v_lshlrev_b32_e32 v58, 16, v33
	v_and_b32_e32 v59, 0xffff0000, v33
	v_lshlrev_b32_e32 v60, 16, v34
	v_and_b32_e32 v61, 0xffff0000, v34
	v_lshlrev_b32_e32 v62, 16, v35
	v_and_b32_e32 v63, 0xffff0000, v35
	v_pk_mul_f32 v[56:57], v[80:81], v[56:57] op_sel_hi:[0,1]
	v_pk_mul_f32 v[58:59], v[80:81], v[58:59] op_sel_hi:[0,1]
	v_pk_mul_f32 v[60:61], v[80:81], v[60:61] op_sel_hi:[0,1]
	v_pk_mul_f32 v[62:63], v[80:81], v[62:63] op_sel_hi:[0,1]
	v_pk_mul_f32 v[64:65], v[4:5], v[56:57]
	v_pk_mul_f32 v[66:67], v[6:7], v[58:59]
	v_pk_mul_f32 v[68:69], v[0:1], v[60:61]
	v_pk_mul_f32 v[70:71], v[2:3], v[62:63]
	v_lshlrev_b32_e32 v56, 16, v36
	v_and_b32_e32 v57, 0xffff0000, v36
	v_lshlrev_b32_e32 v58, 16, v37
	v_and_b32_e32 v59, 0xffff0000, v37
	v_lshlrev_b32_e32 v60, 16, v38
	v_and_b32_e32 v61, 0xffff0000, v38
	v_lshlrev_b32_e32 v62, 16, v39
	v_and_b32_e32 v63, 0xffff0000, v39
	v_pk_mul_f32 v[56:57], v[80:81], v[56:57] op_sel_hi:[0,1]
	v_pk_mul_f32 v[58:59], v[80:81], v[58:59] op_sel_hi:[0,1]
	v_pk_mul_f32 v[60:61], v[80:81], v[60:61] op_sel_hi:[0,1]
	v_pk_mul_f32 v[62:63], v[80:81], v[62:63] op_sel_hi:[0,1]
	v_pk_mul_f32 v[72:73], v[12:13], v[56:57]
	v_pk_mul_f32 v[74:75], v[14:15], v[58:59]
	v_pk_mul_f32 v[76:77], v[8:9], v[60:61]
	v_pk_mul_f32 v[78:79], v[10:11], v[62:63]
	v_mov_b64_e32 v[82:83], v[40:41]
	s_ashr_i32 s1, s3, 3
	s_and_b32 s0, s7, 0x7000
	s_and_b32 s1, s1, -8
	s_add_i32 s0, s0, s1
	s_or_b32 s0, s0, s6
	s_ashr_i32 s1, s0, 31
	s_add_i32 s3, s3, s2
	s_add_i32 s7, s7, s8
	v_mov_b32_e32 v31, 0
	s_and_saveexec_b64 s[4:5], vcc
	v_lshl_add_u64 v[54:55], s[0:1], 0, v[16:17]
	v_lshl_add_u64 v[54:55], v[54:55], 4, v[20:21]
	global_load_dword v31, v[54:55], off
	s_or_b64 exec, exec, s[4:5]
	s_lshl_b64 s[4:5], s[0:1], 11
	v_lshl_add_u64 v[54:55], v[22:23], 0, s[4:5]
	global_load_dwordx4 v[32:35], v[54:55], off
	global_load_dwordx4 v[36:39], v[54:55], off offset:1024
	s_lshl_b64 s[4:5], s[0:1], 12
	v_lshl_add_u64 v[40:41], v[18:19], 0, s[4:5]
	global_store_dwordx4 v[82:83], v[64:67], off
	global_store_dwordx4 v[82:83], v[68:71], off offset:16
	global_store_dwordx4 v[82:83], v[72:75], off offset:2048
	global_store_dwordx4 v[82:83], v[76:79], off offset:2064
	s_waitcnt vmcnt(3)
; __device__ __forceinline__ float bflo(unsigned w) { return __uint_as_float(w << 16); }
; __device__ __forceinline__ float bfhi(unsigned w) { return __uint_as_float(w & 0xffff0000u); }
; #define ssq ((float*)(WSPTR() + WS_SSQ))
; __device__ __forceinline__ void final_norm(const Args& a, int G, int vb) {
;     ...
;     for (int mi = gw; mi < NT; mi += NGW) {
;         const int m = XCD_ROW(mi);
;         float s = (lane < 16) ? ssq[((size_t)(lane >> 2) * NT + m) * 4 + (lane & 3)] : 0.f; s = wave_sum(s);
;         const float rs = __builtin_amdgcn_rsqf(s * (1.0f / 1024.0f) + 1e-6f);
;         const u32x4* xr = (const u32x4*)(xb + (size_t)m * DM) + lane; f32x4* orow = (f32x4*)(out + (size_t)m * DM) + 2 * lane;
; #pragma unroll
;         for (int j = 0; j < 2; ++j) { const u32x4 w = xr[64 * j];
;             orow[128 * j] = (f32x4){bflo(w.x), bfhi(w.x), bflo(w.y), bfhi(w.y)} * rs * gv[j][0];
;             orow[128 * j + 1] = (f32x4){bflo(w.z), bfhi(w.z), bflo(w.w), bfhi(w.w)} * rs * gv[j][1]; }
;     }
	ds_bpermute_b32 v56, v24, v42
	s_waitcnt lgkmcnt(0)
	v_add_f32_e32 v42, v42, v56
	ds_bpermute_b32 v56, v25, v42
	s_waitcnt lgkmcnt(0)
	v_add_f32_e32 v42, v42, v56
	ds_bpermute_b32 v56, v26, v42
	s_waitcnt lgkmcnt(0)
	v_add_f32_e32 v42, v42, v56
	ds_bpermute_b32 v56, v27, v42
	s_waitcnt lgkmcnt(0)
	v_add_f32_e32 v42, v42, v56
	ds_bpermute_b32 v56, v28, v42
	s_waitcnt lgkmcnt(0)
	v_add_f32_e32 v42, v42, v56
	ds_bpermute_b32 v56, v29, v42
	s_waitcnt lgkmcnt(0)
	v_add_f32_e32 v42, v42, v56
	v_fmamk_f32 v42, v42, 0x3a800000, v30
	v_rsq_f32_e32 v80, v42
	v_mov_b32_e32 v81, v17
	v_lshlrev_b32_e32 v56, 16, v44
	v_and_b32_e32 v57, 0xffff0000, v44
	v_lshlrev_b32_e32 v58, 16, v45
	v_and_b32_e32 v59, 0xffff0000, v45
	v_lshlrev_b32_e32 v60, 16, v46
	v_and_b32_e32 v61, 0xffff0000, v46
	v_lshlrev_b32_e32 v62, 16, v47
	v_and_b32_e32 v63, 0xffff0000, v47
	v_pk_mul_f32 v[56:57], v[80:81], v[56:57] op_sel_hi:[0,1]
	v_pk_mul_f32 v[58:59], v[80:81], v[58:59] op_sel_hi:[0,1]
	v_pk_mul_f32 v[60:61], v[80:81], v[60:61] op_sel_hi:[0,1]
	v_pk_mul_f32 v[62:63], v[80:81], v[62:63] op_sel_hi:[0,1]
	v_pk_mul_f32 v[64:65], v[4:5], v[56:57]
	v_pk_mul_f32 v[66:67], v[6:7], v[58:59]
	v_pk_mul_f32 v[68:69], v[0:1], v[60:61]
	v_pk_mul_f32 v[70:71], v[2:3], v[62:63]
	v_lshlrev_b32_e32 v56, 16, v48
	v_and_b32_e32 v57, 0xffff0000, v48
	v_lshlrev_b32_e32 v58, 16, v49
	v_and_b32_e32 v59, 0xffff0000, v49
	v_lshlrev_b32_e32 v60, 16, v50
	v_and_b32_e32 v61, 0xffff0000, v50
	v_lshlrev_b32_e32 v62, 16, v51
	v_and_b32_e32 v63, 0xffff0000, v51
	v_pk_mul_f32 v[56:57], v[80:81], v[56:57] op_sel_hi:[0,1]
	v_pk_mul_f32 v[58:59], v[80:81], v[58:59] op_sel_hi:[0,1]
	v_pk_mul_f32 v[60:61], v[80:81], v[60:61] op_sel_hi:[0,1]
	v_pk_mul_f32 v[62:63], v[80:81], v[62:63] op_sel_hi:[0,1]
	v_pk_mul_f32 v[72:73], v[12:13], v[56:57]
	v_pk_mul_f32 v[74:75], v[14:15], v[58:59]
	v_pk_mul_f32 v[76:77], v[8:9], v[60:61]
	v_pk_mul_f32 v[78:79], v[10:11], v[62:63]
	v_mov_b64_e32 v[82:83], v[52:53]
	s_ashr_i32 s1, s3, 3
	s_and_b32 s0, s7, 0x7000
	s_and_b32 s1, s1, -8
	s_add_i32 s0, s0, s1
	s_or_b32 s0, s0, s6
	s_ashr_i32 s1, s0, 31
	s_add_i32 s3, s3, s2
	s_add_i32 s7, s7, s8
	v_mov_b32_e32 v42, 0
	s_and_saveexec_b64 s[4:5], vcc
	v_lshl_add_u64 v[54:55], s[0:1], 0, v[16:17]
	v_lshl_add_u64 v[54:55], v[54:55], 4, v[20:21]
	global_load_dword v42, v[54:55], off
	s_or_b64 exec, exec, s[4:5]
	s_lshl_b64 s[4:5], s[0:1], 11
	v_lshl_add_u64 v[54:55], v[22:23], 0, s[4:5]
	global_load_dwordx4 v[44:47], v[54:55], off
	global_load_dwordx4 v[48:51], v[54:55], off offset:1024
	s_lshl_b64 s[4:5], s[0:1], 12
	v_lshl_add_u64 v[52:53], v[18:19], 0, s[4:5]
	global_store_dwordx4 v[82:83], v[64:67], off
	global_store_dwordx4 v[82:83], v[68:71], off offset:16
	global_store_dwordx4 v[82:83], v[72:75], off offset:2048
	global_store_dwordx4 v[82:83], v[76:79], off offset:2064
	s_waitcnt vmcnt(3)
	ds_bpermute_b32 v56, v24, v31
	s_waitcnt lgkmcnt(0)
	v_add_f32_e32 v31, v31, v56
	ds_bpermute_b32 v56, v25, v31
	s_waitcnt lgkmcnt(0)
	v_add_f32_e32 v31, v31, v56
	ds_bpermute_b32 v56, v26, v31
	s_waitcnt lgkmcnt(0)
	v_add_f32_e32 v31, v31, v56
	ds_bpermute_b32 v56, v27, v31
	s_waitcnt lgkmcnt(0)
	v_add_f32_e32 v31, v31, v56
	ds_bpermute_b32 v56, v28, v31
	s_waitcnt lgkmcnt(0)
	v_add_f32_e32 v31, v31, v56
	ds_bpermute_b32 v56, v29, v31
	s_waitcnt lgkmcnt(0)
	v_add_f32_e32 v31, v31, v56
	v_fmamk_f32 v31, v31, 0x3a800000, v30
	v_rsq_f32_e32 v80, v31
	v_mov_b32_e32 v81, v17
	v_lshlrev_b32_e32 v56, 16, v32
	v_and_b32_e32 v57, 0xffff0000, v32
	v_lshlrev_b32_e32 v58, 16, v33
	v_and_b32_e32 v59, 0xffff0000, v33
	v_lshlrev_b32_e32 v60, 16, v34
	v_and_b32_e32 v61, 0xffff0000, v34
	v_lshlrev_b32_e32 v62, 16, v35
	v_and_b32_e32 v63, 0xffff0000, v35
	v_pk_mul_f32 v[56:57], v[80:81], v[56:57] op_sel_hi:[0,1]
	v_pk_mul_f32 v[58:59], v[80:81], v[58:59] op_sel_hi:[0,1]
	v_pk_mul_f32 v[60:61], v[80:81], v[60:61] op_sel_hi:[0,1]
	v_pk_mul_f32 v[62:63], v[80:81], v[62:63] op_sel_hi:[0,1]
	v_pk_mul_f32 v[64:65], v[4:5], v[56:57]
	v_pk_mul_f32 v[66:67], v[6:7], v[58:59]
	v_pk_mul_f32 v[68:69], v[0:1], v[60:61]
	v_pk_mul_f32 v[70:71], v[2:3], v[62:63]
	v_lshlrev_b32_e32 v56, 16, v36
	v_and_b32_e32 v57, 0xffff0000, v36
	v_lshlrev_b32_e32 v58, 16, v37
	v_and_b32_e32 v59, 0xffff0000, v37
	v_lshlrev_b32_e32 v60, 16, v38
	v_and_b32_e32 v61, 0xffff0000, v38
	v_lshlrev_b32_e32 v62, 16, v39
	v_and_b32_e32 v63, 0xffff0000, v39
	v_pk_mul_f32 v[56:57], v[80:81], v[56:57] op_sel_hi:[0,1]
	v_pk_mul_f32 v[58:59], v[80:81], v[58:59] op_sel_hi:[0,1]
	v_pk_mul_f32 v[60:61], v[80:81], v[60:61] op_sel_hi:[0,1]
	v_pk_mul_f32 v[62:63], v[80:81], v[62:63] op_sel_hi:[0,1]
	v_pk_mul_f32 v[72:73], v[12:13], v[56:57]
	v_pk_mul_f32 v[74:75], v[14:15], v[58:59]
	v_pk_mul_f32 v[76:77], v[8:9], v[60:61]
	v_pk_mul_f32 v[78:79], v[10:11], v[62:63]
	v_mov_b64_e32 v[82:83], v[40:41]
	s_ashr_i32 s1, s3, 3
	s_and_b32 s0, s7, 0x7000
	s_and_b32 s1, s1, -8
	s_add_i32 s0, s0, s1
	s_or_b32 s0, s0, s6
	s_ashr_i32 s1, s0, 31
	s_add_i32 s3, s3, s2
	s_add_i32 s7, s7, s8
	v_mov_b32_e32 v31, 0
	s_and_saveexec_b64 s[4:5], vcc
	v_lshl_add_u64 v[54:55], s[0:1], 0, v[16:17]
	v_lshl_add_u64 v[54:55], v[54:55], 4, v[20:21]
	global_load_dword v31, v[54:55], off
	s_or_b64 exec, exec, s[4:5]
	s_lshl_b64 s[4:5], s[0:1], 11
	v_lshl_add_u64 v[54:55], v[22:23], 0, s[4:5]
	global_load_dwordx4 v[32:35], v[54:55], off
	global_load_dwordx4 v[36:39], v[54:55], off offset:1024
	s_lshl_b64 s[4:5], s[0:1], 12
	v_lshl_add_u64 v[40:41], v[18:19], 0, s[4:5]
	global_store_dwordx4 v[82:83], v[64:67], off
	global_store_dwordx4 v[82:83], v[68:71], off offset:16
	global_store_dwordx4 v[82:83], v[72:75], off offset:2048
	global_store_dwordx4 v[82:83], v[76:79], off offset:2064
	s_waitcnt vmcnt(3)
; __device__ __forceinline__ float bflo(unsigned w) { return __uint_as_float(w << 16); }
; __device__ __forceinline__ float bfhi(unsigned w) { return __uint_as_float(w & 0xffff0000u); }
; #define ssq ((float*)(WSPTR() + WS_SSQ))
; __device__ __forceinline__ void final_norm(const Args& a, int G, int vb) {
;     ...
;     for (int mi = gw; mi < NT; mi += NGW) {
;         const int m = XCD_ROW(mi);
;         float s = (lane < 16) ? ssq[((size_t)(lane >> 2) * NT + m) * 4 + (lane & 3)] : 0.f; s = wave_sum(s);
;         const float rs = __builtin_amdgcn_rsqf(s * (1.0f / 1024.0f) + 1e-6f);
;         const u32x4* xr = (const u32x4*)(xb + (size_t)m * DM) + lane; f32x4* orow = (f32x4*)(out + (size_t)m * DM) + 2 * lane;
; #pragma unroll
;         for (int j = 0; j < 2; ++j) { const u32x4 w = xr[64 * j];
;             orow[128 * j] = (f32x4){bflo(w.x), bfhi(w.x), bflo(w.y), bfhi(w.y)} * rs * gv[j][0];
;             orow[128 * j + 1] = (f32x4){bflo(w.z), bfhi(w.z), bflo(w.w), bfhi(w.w)} * rs * gv[j][1]; }
;     }
	ds_bpermute_b32 v56, v24, v42
	s_waitcnt lgkmcnt(0)
	v_add_f32_e32 v42, v42, v56
	ds_bpermute_b32 v56, v25, v42
	s_waitcnt lgkmcnt(0)
	v_add_f32_e32 v42, v42, v56
	ds_bpermute_b32 v56, v26, v42
	s_waitcnt lgkmcnt(0)
	v_add_f32_e32 v42, v42, v56
	ds_bpermute_b32 v56, v27, v42
	s_waitcnt lgkmcnt(0)
	v_add_f32_e32 v42, v42, v56
	ds_bpermute_b32 v56, v28, v42
	s_waitcnt lgkmcnt(0)
	v_add_f32_e32 v42, v42, v56
	ds_bpermute_b32 v56, v29, v42
	s_waitcnt lgkmcnt(0)
	v_add_f32_e32 v42, v42, v56
	v_fmamk_f32 v42, v42, 0x3a800000, v30
	v_rsq_f32_e32 v80, v42
	v_mov_b32_e32 v81, v17
	v_lshlrev_b32_e32 v56, 16, v44
	v_and_b32_e32 v57, 0xffff0000, v44
	v_lshlrev_b32_e32 v58, 16, v45
	v_and_b32_e32 v59, 0xffff0000, v45
	v_lshlrev_b32_e32 v60, 16, v46
	v_and_b32_e32 v61, 0xffff0000, v46
	v_lshlrev_b32_e32 v62, 16, v47
	v_and_b32_e32 v63, 0xffff0000, v47
	v_pk_mul_f32 v[56:57], v[80:81], v[56:57] op_sel_hi:[0,1]
	v_pk_mul_f32 v[58:59], v[80:81], v[58:59] op_sel_hi:[0,1]
	v_pk_mul_f32 v[60:61], v[80:81], v[60:61] op_sel_hi:[0,1]
	v_pk_mul_f32 v[62:63], v[80:81], v[62:63] op_sel_hi:[0,1]
	v_pk_mul_f32 v[64:65], v[4:5], v[56:57]
	v_pk_mul_f32 v[66:67], v[6:7], v[58:59]
	v_pk_mul_f32 v[68:69], v[0:1], v[60:61]
	v_pk_mul_f32 v[70:71], v[2:3], v[62:63]
	v_lshlrev_b32_e32 v56, 16, v48
	v_and_b32_e32 v57, 0xffff0000, v48
	v_lshlrev_b32_e32 v58, 16, v49
	v_and_b32_e32 v59, 0xffff0000, v49
	v_lshlrev_b32_e32 v60, 16, v50
	v_and_b32_e32 v61, 0xffff0000, v50
	v_lshlrev_b32_e32 v62, 16, v51
	v_and_b32_e32 v63, 0xffff0000, v51
	v_pk_mul_f32 v[56:57], v[80:81], v[56:57] op_sel_hi:[0,1]
	v_pk_mul_f32 v[58:59], v[80:81], v[58:59] op_sel_hi:[0,1]
	v_pk_mul_f32 v[60:61], v[80:81], v[60:61] op_sel_hi:[0,1]
	v_pk_mul_f32 v[62:63], v[80:81], v[62:63] op_sel_hi:[0,1]
	v_pk_mul_f32 v[72:73], v[12:13], v[56:57]
	v_pk_mul_f32 v[74:75], v[14:15], v[58:59]
	v_pk_mul_f32 v[76:77], v[8:9], v[60:61]
	v_pk_mul_f32 v[78:79], v[10:11], v[62:63]
	v_mov_b64_e32 v[82:83], v[52:53]
	s_ashr_i32 s1, s3, 3
	s_and_b32 s0, s7, 0x7000
	s_and_b32 s1, s1, -8
	s_add_i32 s0, s0, s1
	s_or_b32 s0, s0, s6
	s_ashr_i32 s1, s0, 31
	s_add_i32 s3, s3, s2
	s_add_i32 s7, s7, s8
	v_mov_b32_e32 v42, 0
	s_and_saveexec_b64 s[4:5], vcc
	v_lshl_add_u64 v[54:55], s[0:1], 0, v[16:17]
	v_lshl_add_u64 v[54:55], v[54:55], 4, v[20:21]
	global_load_dword v42, v[54:55], off
	s_or_b64 exec, exec, s[4:5]
	s_lshl_b64 s[4:5], s[0:1], 11
	v_lshl_add_u64 v[54:55], v[22:23], 0, s[4:5]
	global_load_dwordx4 v[44:47], v[54:55], off
	global_load_dwordx4 v[48:51], v[54:55], off offset:1024
	s_lshl_b64 s[4:5], s[0:1], 12
	v_lshl_add_u64 v[52:53], v[18:19], 0, s[4:5]
	global_store_dwordx4 v[82:83], v[64:67], off
	global_store_dwordx4 v[82:83], v[68:71], off offset:16
	global_store_dwordx4 v[82:83], v[72:75], off offset:2048
	global_store_dwordx4 v[82:83], v[76:79], off offset:2064
	s_waitcnt vmcnt(3)
	ds_bpermute_b32 v56, v24, v31
	s_waitcnt lgkmcnt(0)
	v_add_f32_e32 v31, v31, v56
	ds_bpermute_b32 v56, v25, v31
	s_waitcnt lgkmcnt(0)
	v_add_f32_e32 v31, v31, v56
	ds_bpermute_b32 v56, v26, v31
	s_waitcnt lgkmcnt(0)
	v_add_f32_e32 v31, v31, v56
	ds_bpermute_b32 v56, v27, v31
	s_waitcnt lgkmcnt(0)
	v_add_f32_e32 v31, v31, v56
	ds_bpermute_b32 v56, v28, v31
	s_waitcnt lgkmcnt(0)
	v_add_f32_e32 v31, v31, v56
	ds_bpermute_b32 v56, v29, v31
	s_waitcnt lgkmcnt(0)
	v_add_f32_e32 v31, v31, v56
	v_fmamk_f32 v31, v31, 0x3a800000, v30
	v_rsq_f32_e32 v80, v31
	v_mov_b32_e32 v81, v17
	v_lshlrev_b32_e32 v56, 16, v32
	v_and_b32_e32 v57, 0xffff0000, v32
	v_lshlrev_b32_e32 v58, 16, v33
	v_and_b32_e32 v59, 0xffff0000, v33
	v_lshlrev_b32_e32 v60, 16, v34
	v_and_b32_e32 v61, 0xffff0000, v34
	v_lshlrev_b32_e32 v62, 16, v35
	v_and_b32_e32 v63, 0xffff0000, v35
	v_pk_mul_f32 v[56:57], v[80:81], v[56:57] op_sel_hi:[0,1]
	v_pk_mul_f32 v[58:59], v[80:81], v[58:59] op_sel_hi:[0,1]
	v_pk_mul_f32 v[60:61], v[80:81], v[60:61] op_sel_hi:[0,1]
	v_pk_mul_f32 v[62:63], v[80:81], v[62:63] op_sel_hi:[0,1]
	v_pk_mul_f32 v[64:65], v[4:5], v[56:57]
	v_pk_mul_f32 v[66:67], v[6:7], v[58:59]
	v_pk_mul_f32 v[68:69], v[0:1], v[60:61]
	v_pk_mul_f32 v[70:71], v[2:3], v[62:63]
	v_lshlrev_b32_e32 v56, 16, v36
	v_and_b32_e32 v57, 0xffff0000, v36
	v_lshlrev_b32_e32 v58, 16, v37
	v_and_b32_e32 v59, 0xffff0000, v37
	v_lshlrev_b32_e32 v60, 16, v38
	v_and_b32_e32 v61, 0xffff0000, v38
	v_lshlrev_b32_e32 v62, 16, v39
	v_and_b32_e32 v63, 0xffff0000, v39
	v_pk_mul_f32 v[56:57], v[80:81], v[56:57] op_sel_hi:[0,1]
	v_pk_mul_f32 v[58:59], v[80:81], v[58:59] op_sel_hi:[0,1]
	v_pk_mul_f32 v[60:61], v[80:81], v[60:61] op_sel_hi:[0,1]
	v_pk_mul_f32 v[62:63], v[80:81], v[62:63] op_sel_hi:[0,1]
	v_pk_mul_f32 v[72:73], v[12:13], v[56:57]
	v_pk_mul_f32 v[74:75], v[14:15], v[58:59]
	v_pk_mul_f32 v[76:77], v[8:9], v[60:61]
	v_pk_mul_f32 v[78:79], v[10:11], v[62:63]
	v_mov_b64_e32 v[82:83], v[40:41]
	s_ashr_i32 s1, s3, 3
	s_and_b32 s0, s7, 0x7000
	s_and_b32 s1, s1, -8
	s_add_i32 s0, s0, s1
	s_or_b32 s0, s0, s6
	s_ashr_i32 s1, s0, 31
	s_add_i32 s3, s3, s2
	s_add_i32 s7, s7, s8
	v_mov_b32_e32 v31, 0
	s_and_saveexec_b64 s[4:5], vcc
	v_lshl_add_u64 v[54:55], s[0:1], 0, v[16:17]
	v_lshl_add_u64 v[54:55], v[54:55], 4, v[20:21]
	global_load_dword v31, v[54:55], off
	s_or_b64 exec, exec, s[4:5]
	s_lshl_b64 s[4:5], s[0:1], 11
	v_lshl_add_u64 v[54:55], v[22:23], 0, s[4:5]
	global_load_dwordx4 v[32:35], v[54:55], off
	global_load_dwordx4 v[36:39], v[54:55], off offset:1024
	s_lshl_b64 s[4:5], s[0:1], 12
	v_lshl_add_u64 v[40:41], v[18:19], 0, s[4:5]
	global_store_dwordx4 v[82:83], v[64:67], off
	global_store_dwordx4 v[82:83], v[68:71], off offset:16
	global_store_dwordx4 v[82:83], v[72:75], off offset:2048
	global_store_dwordx4 v[82:83], v[76:79], off offset:2064
	s_waitcnt vmcnt(3)
; __device__ __forceinline__ float bflo(unsigned w) { return __uint_as_float(w << 16); }
; __device__ __forceinline__ float bfhi(unsigned w) { return __uint_as_float(w & 0xffff0000u); }
; #define ssq ((float*)(WSPTR() + WS_SSQ))
; __device__ __forceinline__ void final_norm(const Args& a, int G, int vb) {
;     ...
;     for (int mi = gw; mi < NT; mi += NGW) {
;         const int m = XCD_ROW(mi);
;         float s = (lane < 16) ? ssq[((size_t)(lane >> 2) * NT + m) * 4 + (lane & 3)] : 0.f; s = wave_sum(s);
;         const float rs = __builtin_amdgcn_rsqf(s * (1.0f / 1024.0f) + 1e-6f);
;         const u32x4* xr = (const u32x4*)(xb + (size_t)m * DM) + lane; f32x4* orow = (f32x4*)(out + (size_t)m * DM) + 2 * lane;
; #pragma unroll
;         for (int j = 0; j < 2; ++j) { const u32x4 w = xr[64 * j];
;             orow[128 * j] = (f32x4){bflo(w.x), bfhi(w.x), bflo(w.y), bfhi(w.y)} * rs * gv[j][0];
;             orow[128 * j + 1] = (f32x4){bflo(w.z), bfhi(w.z), bflo(w.w), bfhi(w.w)} * rs * gv[j][1]; }
;     }
	ds_bpermute_b32 v56, v24, v42
	s_waitcnt lgkmcnt(0)
	v_add_f32_e32 v42, v42, v56
	ds_bpermute_b32 v56, v25, v42
	s_waitcnt lgkmcnt(0)
	v_add_f32_e32 v42, v42, v56
	ds_bpermute_b32 v56, v26, v42
	s_waitcnt lgkmcnt(0)
	v_add_f32_e32 v42, v42, v56
	ds_bpermute_b32 v56, v27, v42
	s_waitcnt lgkmcnt(0)
	v_add_f32_e32 v42, v42, v56
	ds_bpermute_b32 v56, v28, v42
	s_waitcnt lgkmcnt(0)
	v_add_f32_e32 v42, v42, v56
	ds_bpermute_b32 v56, v29, v42
	s_waitcnt lgkmcnt(0)
	v_add_f32_e32 v42, v42, v56
	v_fmamk_f32 v42, v42, 0x3a800000, v30
	v_rsq_f32_e32 v80, v42
	v_mov_b32_e32 v81, v17
	v_lshlrev_b32_e32 v56, 16, v44
	v_and_b32_e32 v57, 0xffff0000, v44
	v_lshlrev_b32_e32 v58, 16, v45
	v_and_b32_e32 v59, 0xffff0000, v45
	v_lshlrev_b32_e32 v60, 16, v46
	v_and_b32_e32 v61, 0xffff0000, v46
	v_lshlrev_b32_e32 v62, 16, v47
	v_and_b32_e32 v63, 0xffff0000, v47
	v_pk_mul_f32 v[56:57], v[80:81], v[56:57] op_sel_hi:[0,1]
	v_pk_mul_f32 v[58:59], v[80:81], v[58:59] op_sel_hi:[0,1]
	v_pk_mul_f32 v[60:61], v[80:81], v[60:61] op_sel_hi:[0,1]
	v_pk_mul_f32 v[62:63], v[80:81], v[62:63] op_sel_hi:[0,1]
	v_pk_mul_f32 v[64:65], v[4:5], v[56:57]
	v_pk_mul_f32 v[66:67], v[6:7], v[58:59]
	v_pk_mul_f32 v[68:69], v[0:1], v[60:61]
	v_pk_mul_f32 v[70:71], v[2:3], v[62:63]
	v_lshlrev_b32_e32 v56, 16, v48
	v_and_b32_e32 v57, 0xffff0000, v48
	v_lshlrev_b32_e32 v58, 16, v49
	v_and_b32_e32 v59, 0xffff0000, v49
	v_lshlrev_b32_e32 v60, 16, v50
	v_and_b32_e32 v61, 0xffff0000, v50
	v_lshlrev_b32_e32 v62, 16, v51
	v_and_b32_e32 v63, 0xffff0000, v51
	v_pk_mul_f32 v[56:57], v[80:81], v[56:57] op_sel_hi:[0,1]
	v_pk_mul_f32 v[58:59], v[80:81], v[58:59] op_sel_hi:[0,1]
	v_pk_mul_f32 v[60:61], v[80:81], v[60:61] op_sel_hi:[0,1]
	v_pk_mul_f32 v[62:63], v[80:81], v[62:63] op_sel_hi:[0,1]
	v_pk_mul_f32 v[72:73], v[12:13], v[56:57]
	v_pk_mul_f32 v[74:75], v[14:15], v[58:59]
	v_pk_mul_f32 v[76:77], v[8:9], v[60:61]
	v_pk_mul_f32 v[78:79], v[10:11], v[62:63]
	v_mov_b64_e32 v[82:83], v[52:53]
	s_ashr_i32 s1, s3, 3
	s_and_b32 s0, s7, 0x7000
	s_and_b32 s1, s1, -8
	s_add_i32 s0, s0, s1
	s_or_b32 s0, s0, s6
	s_ashr_i32 s1, s0, 31
	s_add_i32 s3, s3, s2
	s_add_i32 s7, s7, s8
	v_mov_b32_e32 v42, 0
	s_and_saveexec_b64 s[4:5], vcc
	v_lshl_add_u64 v[54:55], s[0:1], 0, v[16:17]
	v_lshl_add_u64 v[54:55], v[54:55], 4, v[20:21]
	global_load_dword v42, v[54:55], off
	s_or_b64 exec, exec, s[4:5]
	s_lshl_b64 s[4:5], s[0:1], 11
	v_lshl_add_u64 v[54:55], v[22:23], 0, s[4:5]
	global_load_dwordx4 v[44:47], v[54:55], off
	global_load_dwordx4 v[48:51], v[54:55], off offset:1024
	s_lshl_b64 s[4:5], s[0:1], 12
	v_lshl_add_u64 v[52:53], v[18:19], 0, s[4:5]
	global_store_dwordx4 v[82:83], v[64:67], off
	global_store_dwordx4 v[82:83], v[68:71], off offset:16
	global_store_dwordx4 v[82:83], v[72:75], off offset:2048
	global_store_dwordx4 v[82:83], v[76:79], off offset:2064
	s_waitcnt vmcnt(3)
	ds_bpermute_b32 v56, v24, v31
	s_waitcnt lgkmcnt(0)
	v_add_f32_e32 v31, v31, v56
	ds_bpermute_b32 v56, v25, v31
	s_waitcnt lgkmcnt(0)
	v_add_f32_e32 v31, v31, v56
	ds_bpermute_b32 v56, v26, v31
	s_waitcnt lgkmcnt(0)
	v_add_f32_e32 v31, v31, v56
	ds_bpermute_b32 v56, v27, v31
	s_waitcnt lgkmcnt(0)
	v_add_f32_e32 v31, v31, v56
	ds_bpermute_b32 v56, v28, v31
	s_waitcnt lgkmcnt(0)
	v_add_f32_e32 v31, v31, v56
	ds_bpermute_b32 v56, v29, v31
	s_waitcnt lgkmcnt(0)
	v_add_f32_e32 v31, v31, v56
	v_fmamk_f32 v31, v31, 0x3a800000, v30
	v_rsq_f32_e32 v80, v31
	v_mov_b32_e32 v81, v17
	v_lshlrev_b32_e32 v56, 16, v32
	v_and_b32_e32 v57, 0xffff0000, v32
	v_lshlrev_b32_e32 v58, 16, v33
	v_and_b32_e32 v59, 0xffff0000, v33
	v_lshlrev_b32_e32 v60, 16, v34
	v_and_b32_e32 v61, 0xffff0000, v34
	v_lshlrev_b32_e32 v62, 16, v35
	v_and_b32_e32 v63, 0xffff0000, v35
	v_pk_mul_f32 v[56:57], v[80:81], v[56:57] op_sel_hi:[0,1]
	v_pk_mul_f32 v[58:59], v[80:81], v[58:59] op_sel_hi:[0,1]
	v_pk_mul_f32 v[60:61], v[80:81], v[60:61] op_sel_hi:[0,1]
	v_pk_mul_f32 v[62:63], v[80:81], v[62:63] op_sel_hi:[0,1]
	v_pk_mul_f32 v[64:65], v[4:5], v[56:57]
	v_pk_mul_f32 v[66:67], v[6:7], v[58:59]
	v_pk_mul_f32 v[68:69], v[0:1], v[60:61]
	v_pk_mul_f32 v[70:71], v[2:3], v[62:63]
	v_lshlrev_b32_e32 v56, 16, v36
	v_and_b32_e32 v57, 0xffff0000, v36
	v_lshlrev_b32_e32 v58, 16, v37
	v_and_b32_e32 v59, 0xffff0000, v37
	v_lshlrev_b32_e32 v60, 16, v38
	v_and_b32_e32 v61, 0xffff0000, v38
	v_lshlrev_b32_e32 v62, 16, v39
	v_and_b32_e32 v63, 0xffff0000, v39
	v_pk_mul_f32 v[56:57], v[80:81], v[56:57] op_sel_hi:[0,1]
	v_pk_mul_f32 v[58:59], v[80:81], v[58:59] op_sel_hi:[0,1]
	v_pk_mul_f32 v[60:61], v[80:81], v[60:61] op_sel_hi:[0,1]
	v_pk_mul_f32 v[62:63], v[80:81], v[62:63] op_sel_hi:[0,1]
	v_pk_mul_f32 v[72:73], v[12:13], v[56:57]
	v_pk_mul_f32 v[74:75], v[14:15], v[58:59]
	v_pk_mul_f32 v[76:77], v[8:9], v[60:61]
	v_pk_mul_f32 v[78:79], v[10:11], v[62:63]
	v_mov_b64_e32 v[82:83], v[40:41]
	s_ashr_i32 s1, s3, 3
	s_and_b32 s0, s7, 0x7000
	s_and_b32 s1, s1, -8
	s_add_i32 s0, s0, s1
	s_or_b32 s0, s0, s6
	s_ashr_i32 s1, s0, 31
	s_add_i32 s3, s3, s2
	s_add_i32 s7, s7, s8
	v_mov_b32_e32 v31, 0
	s_and_saveexec_b64 s[4:5], vcc
	v_lshl_add_u64 v[54:55], s[0:1], 0, v[16:17]
	v_lshl_add_u64 v[54:55], v[54:55], 4, v[20:21]
	global_load_dword v31, v[54:55], off
	s_or_b64 exec, exec, s[4:5]
	s_lshl_b64 s[4:5], s[0:1], 11
	v_lshl_add_u64 v[54:55], v[22:23], 0, s[4:5]
	global_load_dwordx4 v[32:35], v[54:55], off
	global_load_dwordx4 v[36:39], v[54:55], off offset:1024
	s_lshl_b64 s[4:5], s[0:1], 12
	v_lshl_add_u64 v[40:41], v[18:19], 0, s[4:5]
	global_store_dwordx4 v[82:83], v[64:67], off
	global_store_dwordx4 v[82:83], v[68:71], off offset:16
	global_store_dwordx4 v[82:83], v[72:75], off offset:2048
	global_store_dwordx4 v[82:83], v[76:79], off offset:2064
	s_waitcnt vmcnt(3)
; __device__ __forceinline__ float bflo(unsigned w) { return __uint_as_float(w << 16); }
; __device__ __forceinline__ float bfhi(unsigned w) { return __uint_as_float(w & 0xffff0000u); }
; #define ssq ((float*)(WSPTR() + WS_SSQ))
; __device__ __forceinline__ void final_norm(const Args& a, int G, int vb) {
;     ...
;     for (int mi = gw; mi < NT; mi += NGW) {
;         const int m = XCD_ROW(mi);
;         float s = (lane < 16) ? ssq[((size_t)(lane >> 2) * NT + m) * 4 + (lane & 3)] : 0.f; s = wave_sum(s);
;         const float rs = __builtin_amdgcn_rsqf(s * (1.0f / 1024.0f) + 1e-6f);
;         const u32x4* xr = (const u32x4*)(xb + (size_t)m * DM) + lane; f32x4* orow = (f32x4*)(out + (size_t)m * DM) + 2 * lane;
; #pragma unroll
;         for (int j = 0; j < 2; ++j) { const u32x4 w = xr[64 * j];
;             orow[128 * j] = (f32x4){bflo(w.x), bfhi(w.x), bflo(w.y), bfhi(w.y)} * rs * gv[j][0];
;             orow[128 * j + 1] = (f32x4){bflo(w.z), bfhi(w.z), bflo(w.w), bfhi(w.w)} * rs * gv[j][1]; }
;     }
	ds_bpermute_b32 v56, v24, v42
	s_waitcnt lgkmcnt(0)
	v_add_f32_e32 v42, v42, v56
	ds_bpermute_b32 v56, v25, v42
	s_waitcnt lgkmcnt(0)
	v_add_f32_e32 v42, v42, v56
	ds_bpermute_b32 v56, v26, v42
	s_waitcnt lgkmcnt(0)
	v_add_f32_e32 v42, v42, v56
	ds_bpermute_b32 v56, v27, v42
	s_waitcnt lgkmcnt(0)
	v_add_f32_e32 v42, v42, v56
	ds_bpermute_b32 v56, v28, v42
	s_waitcnt lgkmcnt(0)
	v_add_f32_e32 v42, v42, v56
	ds_bpermute_b32 v56, v29, v42
	s_waitcnt lgkmcnt(0)
	v_add_f32_e32 v42, v42, v56
	v_fmamk_f32 v42, v42, 0x3a800000, v30
	v_rsq_f32_e32 v80, v42
	v_mov_b32_e32 v81, v17
	v_lshlrev_b32_e32 v56, 16, v44
	v_and_b32_e32 v57, 0xffff0000, v44
	v_lshlrev_b32_e32 v58, 16, v45
	v_and_b32_e32 v59, 0xffff0000, v45
	v_lshlrev_b32_e32 v60, 16, v46
	v_and_b32_e32 v61, 0xffff0000, v46
	v_lshlrev_b32_e32 v62, 16, v47
	v_and_b32_e32 v63, 0xffff0000, v47
	v_pk_mul_f32 v[56:57], v[80:81], v[56:57] op_sel_hi:[0,1]
	v_pk_mul_f32 v[58:59], v[80:81], v[58:59] op_sel_hi:[0,1]
	v_pk_mul_f32 v[60:61], v[80:81], v[60:61] op_sel_hi:[0,1]
	v_pk_mul_f32 v[62:63], v[80:81], v[62:63] op_sel_hi:[0,1]
	v_pk_mul_f32 v[64:65], v[4:5], v[56:57]
	v_pk_mul_f32 v[66:67], v[6:7], v[58:59]
	v_pk_mul_f32 v[68:69], v[0:1], v[60:61]
	v_pk_mul_f32 v[70:71], v[2:3], v[62:63]
	v_lshlrev_b32_e32 v56, 16, v48
	v_and_b32_e32 v57, 0xffff0000, v48
	v_lshlrev_b32_e32 v58, 16, v49
	v_and_b32_e32 v59, 0xffff0000, v49
	v_lshlrev_b32_e32 v60, 16, v50
	v_and_b32_e32 v61, 0xffff0000, v50
	v_lshlrev_b32_e32 v62, 16, v51
	v_and_b32_e32 v63, 0xffff0000, v51
	v_pk_mul_f32 v[56:57], v[80:81], v[56:57] op_sel_hi:[0,1]
	v_pk_mul_f32 v[58:59], v[80:81], v[58:59] op_sel_hi:[0,1]
	v_pk_mul_f32 v[60:61], v[80:81], v[60:61] op_sel_hi:[0,1]
	v_pk_mul_f32 v[62:63], v[80:81], v[62:63] op_sel_hi:[0,1]
	v_pk_mul_f32 v[72:73], v[12:13], v[56:57]
	v_pk_mul_f32 v[74:75], v[14:15], v[58:59]
	v_pk_mul_f32 v[76:77], v[8:9], v[60:61]
	v_pk_mul_f32 v[78:79], v[10:11], v[62:63]
	v_mov_b64_e32 v[82:83], v[52:53]
	s_ashr_i32 s1, s3, 3
	s_and_b32 s0, s7, 0x7000
	s_and_b32 s1, s1, -8
	s_add_i32 s0, s0, s1
	s_or_b32 s0, s0, s6
	s_ashr_i32 s1, s0, 31
	s_add_i32 s3, s3, s2
	s_add_i32 s7, s7, s8
	v_mov_b32_e32 v42, 0
	s_and_saveexec_b64 s[4:5], vcc
	v_lshl_add_u64 v[54:55], s[0:1], 0, v[16:17]
	v_lshl_add_u64 v[54:55], v[54:55], 4, v[20:21]
	global_load_dword v42, v[54:55], off
	s_or_b64 exec, exec, s[4:5]
	s_lshl_b64 s[4:5], s[0:1], 11
	v_lshl_add_u64 v[54:55], v[22:23], 0, s[4:5]
	global_load_dwordx4 v[44:47], v[54:55], off
	global_load_dwordx4 v[48:51], v[54:55], off offset:1024
	s_lshl_b64 s[4:5], s[0:1], 12
	v_lshl_add_u64 v[52:53], v[18:19], 0, s[4:5]
	global_store_dwordx4 v[82:83], v[64:67], off
	global_store_dwordx4 v[82:83], v[68:71], off offset:16
	global_store_dwordx4 v[82:83], v[72:75], off offset:2048
	global_store_dwordx4 v[82:83], v[76:79], off offset:2064
	s_waitcnt vmcnt(3)
	ds_bpermute_b32 v56, v24, v31
	s_waitcnt lgkmcnt(0)
	v_add_f32_e32 v31, v31, v56
	ds_bpermute_b32 v56, v25, v31
	s_waitcnt lgkmcnt(0)
	v_add_f32_e32 v31, v31, v56
	ds_bpermute_b32 v56, v26, v31
	s_waitcnt lgkmcnt(0)
	v_add_f32_e32 v31, v31, v56
	ds_bpermute_b32 v56, v27, v31
	s_waitcnt lgkmcnt(0)
	v_add_f32_e32 v31, v31, v56
	ds_bpermute_b32 v56, v28, v31
	s_waitcnt lgkmcnt(0)
	v_add_f32_e32 v31, v31, v56
	ds_bpermute_b32 v56, v29, v31
	s_waitcnt lgkmcnt(0)
	v_add_f32_e32 v31, v31, v56
	v_fmamk_f32 v31, v31, 0x3a800000, v30
	v_rsq_f32_e32 v80, v31
	v_mov_b32_e32 v81, v17
	v_lshlrev_b32_e32 v56, 16, v32
	v_and_b32_e32 v57, 0xffff0000, v32
	v_lshlrev_b32_e32 v58, 16, v33
	v_and_b32_e32 v59, 0xffff0000, v33
	v_lshlrev_b32_e32 v60, 16, v34
	v_and_b32_e32 v61, 0xffff0000, v34
	v_lshlrev_b32_e32 v62, 16, v35
	v_and_b32_e32 v63, 0xffff0000, v35
	v_pk_mul_f32 v[56:57], v[80:81], v[56:57] op_sel_hi:[0,1]
	v_pk_mul_f32 v[58:59], v[80:81], v[58:59] op_sel_hi:[0,1]
	v_pk_mul_f32 v[60:61], v[80:81], v[60:61] op_sel_hi:[0,1]
	v_pk_mul_f32 v[62:63], v[80:81], v[62:63] op_sel_hi:[0,1]
	v_pk_mul_f32 v[64:65], v[4:5], v[56:57]
	v_pk_mul_f32 v[66:67], v[6:7], v[58:59]
	v_pk_mul_f32 v[68:69], v[0:1], v[60:61]
	v_pk_mul_f32 v[70:71], v[2:3], v[62:63]
	v_lshlrev_b32_e32 v56, 16, v36
	v_and_b32_e32 v57, 0xffff0000, v36
	v_lshlrev_b32_e32 v58, 16, v37
	v_and_b32_e32 v59, 0xffff0000, v37
	v_lshlrev_b32_e32 v60, 16, v38
	v_and_b32_e32 v61, 0xffff0000, v38
	v_lshlrev_b32_e32 v62, 16, v39
	v_and_b32_e32 v63, 0xffff0000, v39
	v_pk_mul_f32 v[56:57], v[80:81], v[56:57] op_sel_hi:[0,1]
	v_pk_mul_f32 v[58:59], v[80:81], v[58:59] op_sel_hi:[0,1]
	v_pk_mul_f32 v[60:61], v[80:81], v[60:61] op_sel_hi:[0,1]
	v_pk_mul_f32 v[62:63], v[80:81], v[62:63] op_sel_hi:[0,1]
	v_pk_mul_f32 v[72:73], v[12:13], v[56:57]
	v_pk_mul_f32 v[74:75], v[14:15], v[58:59]
	v_pk_mul_f32 v[76:77], v[8:9], v[60:61]
	v_pk_mul_f32 v[78:79], v[10:11], v[62:63]
	v_mov_b64_e32 v[82:83], v[40:41]
	s_ashr_i32 s1, s3, 3
	s_and_b32 s0, s7, 0x7000
	s_and_b32 s1, s1, -8
	s_add_i32 s0, s0, s1
	s_or_b32 s0, s0, s6
	s_ashr_i32 s1, s0, 31
	s_add_i32 s3, s3, s2
	s_add_i32 s7, s7, s8
	v_mov_b32_e32 v31, 0
	s_and_saveexec_b64 s[4:5], vcc
	v_lshl_add_u64 v[54:55], s[0:1], 0, v[16:17]
	v_lshl_add_u64 v[54:55], v[54:55], 4, v[20:21]
	global_load_dword v31, v[54:55], off
	s_or_b64 exec, exec, s[4:5]
	s_lshl_b64 s[4:5], s[0:1], 11
	v_lshl_add_u64 v[54:55], v[22:23], 0, s[4:5]
	global_load_dwordx4 v[32:35], v[54:55], off
	global_load_dwordx4 v[36:39], v[54:55], off offset:1024
	s_lshl_b64 s[4:5], s[0:1], 12
	v_lshl_add_u64 v[40:41], v[18:19], 0, s[4:5]
	global_store_dwordx4 v[82:83], v[64:67], off
	global_store_dwordx4 v[82:83], v[68:71], off offset:16
	global_store_dwordx4 v[82:83], v[72:75], off offset:2048
	global_store_dwordx4 v[82:83], v[76:79], off offset:2064
	s_waitcnt vmcnt(3)
; __device__ __forceinline__ float bflo(unsigned w) { return __uint_as_float(w << 16); }
; __device__ __forceinline__ float bfhi(unsigned w) { return __uint_as_float(w & 0xffff0000u); }
; #define ssq ((float*)(WSPTR() + WS_SSQ))
; __device__ __forceinline__ void final_norm(const Args& a, int G, int vb) {
;     ...
;     for (int mi = gw; mi < NT; mi += NGW) {
;         const int m = XCD_ROW(mi);
;         float s = (lane < 16) ? ssq[((size_t)(lane >> 2) * NT + m) * 4 + (lane & 3)] : 0.f; s = wave_sum(s);
;         const float rs = __builtin_amdgcn_rsqf(s * (1.0f / 1024.0f) + 1e-6f);
;         const u32x4* xr = (const u32x4*)(xb + (size_t)m * DM) + lane; f32x4* orow = (f32x4*)(out + (size_t)m * DM) + 2 * lane;
; #pragma unroll
;         for (int j = 0; j < 2; ++j) { const u32x4 w = xr[64 * j];
;             orow[128 * j] = (f32x4){bflo(w.x), bfhi(w.x), bflo(w.y), bfhi(w.y)} * rs * gv[j][0];
;             orow[128 * j + 1] = (f32x4){bflo(w.z), bfhi(w.z), bflo(w.w), bfhi(w.w)} * rs * gv[j][1]; }
;     }
	ds_bpermute_b32 v56, v24, v42
	s_waitcnt lgkmcnt(0)
	v_add_f32_e32 v42, v42, v56
	ds_bpermute_b32 v56, v25, v42
	s_waitcnt lgkmcnt(0)
	v_add_f32_e32 v42, v42, v56
	ds_bpermute_b32 v56, v26, v42
	s_waitcnt lgkmcnt(0)
	v_add_f32_e32 v42, v42, v56
	ds_bpermute_b32 v56, v27, v42
	s_waitcnt lgkmcnt(0)
	v_add_f32_e32 v42, v42, v56
	ds_bpermute_b32 v56, v28, v42
	s_waitcnt lgkmcnt(0)
	v_add_f32_e32 v42, v42, v56
	ds_bpermute_b32 v56, v29, v42
	s_waitcnt lgkmcnt(0)
	v_add_f32_e32 v42, v42, v56
	v_fmamk_f32 v42, v42, 0x3a800000, v30
	v_rsq_f32_e32 v80, v42
	v_mov_b32_e32 v81, v17
	v_lshlrev_b32_e32 v56, 16, v44
	v_and_b32_e32 v57, 0xffff0000, v44
	v_lshlrev_b32_e32 v58, 16, v45
	v_and_b32_e32 v59, 0xffff0000, v45
	v_lshlrev_b32_e32 v60, 16, v46
	v_and_b32_e32 v61, 0xffff0000, v46
	v_lshlrev_b32_e32 v62, 16, v47
	v_and_b32_e32 v63, 0xffff0000, v47
	v_pk_mul_f32 v[56:57], v[80:81], v[56:57] op_sel_hi:[0,1]
	v_pk_mul_f32 v[58:59], v[80:81], v[58:59] op_sel_hi:[0,1]
	v_pk_mul_f32 v[60:61], v[80:81], v[60:61] op_sel_hi:[0,1]
	v_pk_mul_f32 v[62:63], v[80:81], v[62:63] op_sel_hi:[0,1]
	v_pk_mul_f32 v[64:65], v[4:5], v[56:57]
	v_pk_mul_f32 v[66:67], v[6:7], v[58:59]
	v_pk_mul_f32 v[68:69], v[0:1], v[60:61]
	v_pk_mul_f32 v[70:71], v[2:3], v[62:63]
	v_lshlrev_b32_e32 v56, 16, v48
	v_and_b32_e32 v57, 0xffff0000, v48
	v_lshlrev_b32_e32 v58, 16, v49
	v_and_b32_e32 v59, 0xffff0000, v49
	v_lshlrev_b32_e32 v60, 16, v50
	v_and_b32_e32 v61, 0xffff0000, v50
	v_lshlrev_b32_e32 v62, 16, v51
	v_and_b32_e32 v63, 0xffff0000, v51
	v_pk_mul_f32 v[56:57], v[80:81], v[56:57] op_sel_hi:[0,1]
	v_pk_mul_f32 v[58:59], v[80:81], v[58:59] op_sel_hi:[0,1]
	v_pk_mul_f32 v[60:61], v[80:81], v[60:61] op_sel_hi:[0,1]
	v_pk_mul_f32 v[62:63], v[80:81], v[62:63] op_sel_hi:[0,1]
	v_pk_mul_f32 v[72:73], v[12:13], v[56:57]
	v_pk_mul_f32 v[74:75], v[14:15], v[58:59]
	v_pk_mul_f32 v[76:77], v[8:9], v[60:61]
	v_pk_mul_f32 v[78:79], v[10:11], v[62:63]
	v_mov_b64_e32 v[82:83], v[52:53]
	s_ashr_i32 s1, s3, 3
	s_and_b32 s0, s7, 0x7000
	s_and_b32 s1, s1, -8
	s_add_i32 s0, s0, s1
	s_or_b32 s0, s0, s6
	s_ashr_i32 s1, s0, 31
	s_add_i32 s3, s3, s2
	s_add_i32 s7, s7, s8
	v_mov_b32_e32 v42, 0
	s_and_saveexec_b64 s[4:5], vcc
	v_lshl_add_u64 v[54:55], s[0:1], 0, v[16:17]
	v_lshl_add_u64 v[54:55], v[54:55], 4, v[20:21]
	global_load_dword v42, v[54:55], off
	s_or_b64 exec, exec, s[4:5]
	s_lshl_b64 s[4:5], s[0:1], 11
	v_lshl_add_u64 v[54:55], v[22:23], 0, s[4:5]
	global_load_dwordx4 v[44:47], v[54:55], off
	global_load_dwordx4 v[48:51], v[54:55], off offset:1024
	s_lshl_b64 s[4:5], s[0:1], 12
	v_lshl_add_u64 v[52:53], v[18:19], 0, s[4:5]
	global_store_dwordx4 v[82:83], v[64:67], off
	global_store_dwordx4 v[82:83], v[68:71], off offset:16
	global_store_dwordx4 v[82:83], v[72:75], off offset:2048
	global_store_dwordx4 v[82:83], v[76:79], off offset:2064
	s_waitcnt vmcnt(3)
	ds_bpermute_b32 v56, v24, v31
	s_waitcnt lgkmcnt(0)
	v_add_f32_e32 v31, v31, v56
	ds_bpermute_b32 v56, v25, v31
	s_waitcnt lgkmcnt(0)
	v_add_f32_e32 v31, v31, v56
	ds_bpermute_b32 v56, v26, v31
	s_waitcnt lgkmcnt(0)
	v_add_f32_e32 v31, v31, v56
	ds_bpermute_b32 v56, v27, v31
	s_waitcnt lgkmcnt(0)
	v_add_f32_e32 v31, v31, v56
	ds_bpermute_b32 v56, v28, v31
	s_waitcnt lgkmcnt(0)
	v_add_f32_e32 v31, v31, v56
	ds_bpermute_b32 v56, v29, v31
	s_waitcnt lgkmcnt(0)
	v_add_f32_e32 v31, v31, v56
	v_fmamk_f32 v31, v31, 0x3a800000, v30
	v_rsq_f32_e32 v80, v31
	v_mov_b32_e32 v81, v17
	v_lshlrev_b32_e32 v56, 16, v32
	v_and_b32_e32 v57, 0xffff0000, v32
	v_lshlrev_b32_e32 v58, 16, v33
	v_and_b32_e32 v59, 0xffff0000, v33
	v_lshlrev_b32_e32 v60, 16, v34
	v_and_b32_e32 v61, 0xffff0000, v34
	v_lshlrev_b32_e32 v62, 16, v35
	v_and_b32_e32 v63, 0xffff0000, v35
	v_pk_mul_f32 v[56:57], v[80:81], v[56:57] op_sel_hi:[0,1]
	v_pk_mul_f32 v[58:59], v[80:81], v[58:59] op_sel_hi:[0,1]
	v_pk_mul_f32 v[60:61], v[80:81], v[60:61] op_sel_hi:[0,1]
	v_pk_mul_f32 v[62:63], v[80:81], v[62:63] op_sel_hi:[0,1]
	v_pk_mul_f32 v[64:65], v[4:5], v[56:57]
	v_pk_mul_f32 v[66:67], v[6:7], v[58:59]
	v_pk_mul_f32 v[68:69], v[0:1], v[60:61]
	v_pk_mul_f32 v[70:71], v[2:3], v[62:63]
	v_lshlrev_b32_e32 v56, 16, v36
	v_and_b32_e32 v57, 0xffff0000, v36
	v_lshlrev_b32_e32 v58, 16, v37
	v_and_b32_e32 v59, 0xffff0000, v37
	v_lshlrev_b32_e32 v60, 16, v38
	v_and_b32_e32 v61, 0xffff0000, v38
	v_lshlrev_b32_e32 v62, 16, v39
	v_and_b32_e32 v63, 0xffff0000, v39
	v_pk_mul_f32 v[56:57], v[80:81], v[56:57] op_sel_hi:[0,1]
	v_pk_mul_f32 v[58:59], v[80:81], v[58:59] op_sel_hi:[0,1]
	v_pk_mul_f32 v[60:61], v[80:81], v[60:61] op_sel_hi:[0,1]
	v_pk_mul_f32 v[62:63], v[80:81], v[62:63] op_sel_hi:[0,1]
	v_pk_mul_f32 v[72:73], v[12:13], v[56:57]
	v_pk_mul_f32 v[74:75], v[14:15], v[58:59]
	v_pk_mul_f32 v[76:77], v[8:9], v[60:61]
	v_pk_mul_f32 v[78:79], v[10:11], v[62:63]
	v_mov_b64_e32 v[82:83], v[40:41]
	s_ashr_i32 s1, s3, 3
	s_and_b32 s0, s7, 0x7000
	s_and_b32 s1, s1, -8
	s_add_i32 s0, s0, s1
	s_or_b32 s0, s0, s6
	s_ashr_i32 s1, s0, 31
	s_add_i32 s3, s3, s2
	s_add_i32 s7, s7, s8
	v_mov_b32_e32 v31, 0
	s_and_saveexec_b64 s[4:5], vcc
	v_lshl_add_u64 v[54:55], s[0:1], 0, v[16:17]
	v_lshl_add_u64 v[54:55], v[54:55], 4, v[20:21]
	global_load_dword v31, v[54:55], off
	s_or_b64 exec, exec, s[4:5]
	s_lshl_b64 s[4:5], s[0:1], 11
	v_lshl_add_u64 v[54:55], v[22:23], 0, s[4:5]
	global_load_dwordx4 v[32:35], v[54:55], off
	global_load_dwordx4 v[36:39], v[54:55], off offset:1024
	s_lshl_b64 s[4:5], s[0:1], 12
	v_lshl_add_u64 v[40:41], v[18:19], 0, s[4:5]
	global_store_dwordx4 v[82:83], v[64:67], off
	global_store_dwordx4 v[82:83], v[68:71], off offset:16
	global_store_dwordx4 v[82:83], v[72:75], off offset:2048
	global_store_dwordx4 v[82:83], v[76:79], off offset:2064
	s_waitcnt vmcnt(3)
; __device__ __forceinline__ float bflo(unsigned w) { return __uint_as_float(w << 16); }
; __device__ __forceinline__ float bfhi(unsigned w) { return __uint_as_float(w & 0xffff0000u); }
; #define ssq ((float*)(WSPTR() + WS_SSQ))
; __device__ __forceinline__ void final_norm(const Args& a, int G, int vb) {
;     ...
;     for (int mi = gw; mi < NT; mi += NGW) {
;         const int m = XCD_ROW(mi);
;         float s = (lane < 16) ? ssq[((size_t)(lane >> 2) * NT + m) * 4 + (lane & 3)] : 0.f; s = wave_sum(s);
;         const float rs = __builtin_amdgcn_rsqf(s * (1.0f / 1024.0f) + 1e-6f);
;         const u32x4* xr = (const u32x4*)(xb + (size_t)m * DM) + lane; f32x4* orow = (f32x4*)(out + (size_t)m * DM) + 2 * lane;
; #pragma unroll
;         for (int j = 0; j < 2; ++j) { const u32x4 w = xr[64 * j];
;             orow[128 * j] = (f32x4){bflo(w.x), bfhi(w.x), bflo(w.y), bfhi(w.y)} * rs * gv[j][0];
;             orow[128 * j + 1] = (f32x4){bflo(w.z), bfhi(w.z), bflo(w.w), bfhi(w.w)} * rs * gv[j][1]; }
;     }
	ds_bpermute_b32 v56, v24, v42
	s_waitcnt lgkmcnt(0)
	v_add_f32_e32 v42, v42, v56
	ds_bpermute_b32 v56, v25, v42
	s_waitcnt lgkmcnt(0)
	v_add_f32_e32 v42, v42, v56
	ds_bpermute_b32 v56, v26, v42
	s_waitcnt lgkmcnt(0)
	v_add_f32_e32 v42, v42, v56
	ds_bpermute_b32 v56, v27, v42
	s_waitcnt lgkmcnt(0)
	v_add_f32_e32 v42, v42, v56
	ds_bpermute_b32 v56, v28, v42
	s_waitcnt lgkmcnt(0)
	v_add_f32_e32 v42, v42, v56
	ds_bpermute_b32 v56, v29, v42
	s_waitcnt lgkmcnt(0)
	v_add_f32_e32 v42, v42, v56
	v_fmamk_f32 v42, v42, 0x3a800000, v30
	v_rsq_f32_e32 v80, v42
	v_mov_b32_e32 v81, v17
	v_lshlrev_b32_e32 v56, 16, v44
	v_and_b32_e32 v57, 0xffff0000, v44
	v_lshlrev_b32_e32 v58, 16, v45
	v_and_b32_e32 v59, 0xffff0000, v45
	v_lshlrev_b32_e32 v60, 16, v46
	v_and_b32_e32 v61, 0xffff0000, v46
	v_lshlrev_b32_e32 v62, 16, v47
	v_and_b32_e32 v63, 0xffff0000, v47
	v_pk_mul_f32 v[56:57], v[80:81], v[56:57] op_sel_hi:[0,1]
	v_pk_mul_f32 v[58:59], v[80:81], v[58:59] op_sel_hi:[0,1]
	v_pk_mul_f32 v[60:61], v[80:81], v[60:61] op_sel_hi:[0,1]
	v_pk_mul_f32 v[62:63], v[80:81], v[62:63] op_sel_hi:[0,1]
	v_pk_mul_f32 v[64:65], v[4:5], v[56:57]
	v_pk_mul_f32 v[66:67], v[6:7], v[58:59]
	v_pk_mul_f32 v[68:69], v[0:1], v[60:61]
	v_pk_mul_f32 v[70:71], v[2:3], v[62:63]
	v_lshlrev_b32_e32 v56, 16, v48
	v_and_b32_e32 v57, 0xffff0000, v48
	v_lshlrev_b32_e32 v58, 16, v49
	v_and_b32_e32 v59, 0xffff0000, v49
	v_lshlrev_b32_e32 v60, 16, v50
	v_and_b32_e32 v61, 0xffff0000, v50
	v_lshlrev_b32_e32 v62, 16, v51
	v_and_b32_e32 v63, 0xffff0000, v51
	v_pk_mul_f32 v[56:57], v[80:81], v[56:57] op_sel_hi:[0,1]
	v_pk_mul_f32 v[58:59], v[80:81], v[58:59] op_sel_hi:[0,1]
	v_pk_mul_f32 v[60:61], v[80:81], v[60:61] op_sel_hi:[0,1]
	v_pk_mul_f32 v[62:63], v[80:81], v[62:63] op_sel_hi:[0,1]
	v_pk_mul_f32 v[72:73], v[12:13], v[56:57]
	v_pk_mul_f32 v[74:75], v[14:15], v[58:59]
	v_pk_mul_f32 v[76:77], v[8:9], v[60:61]
	v_pk_mul_f32 v[78:79], v[10:11], v[62:63]
	v_mov_b64_e32 v[82:83], v[52:53]
	s_ashr_i32 s1, s3, 3
	s_and_b32 s0, s7, 0x7000
	s_and_b32 s1, s1, -8
	s_add_i32 s0, s0, s1
	s_or_b32 s0, s0, s6
	s_ashr_i32 s1, s0, 31
	s_add_i32 s3, s3, s2
	s_add_i32 s7, s7, s8
	v_mov_b32_e32 v42, 0
	s_and_saveexec_b64 s[4:5], vcc
	v_lshl_add_u64 v[54:55], s[0:1], 0, v[16:17]
	v_lshl_add_u64 v[54:55], v[54:55], 4, v[20:21]
	global_load_dword v42, v[54:55], off
	s_or_b64 exec, exec, s[4:5]
	s_lshl_b64 s[4:5], s[0:1], 11
	v_lshl_add_u64 v[54:55], v[22:23], 0, s[4:5]
	global_load_dwordx4 v[44:47], v[54:55], off
	global_load_dwordx4 v[48:51], v[54:55], off offset:1024
	s_lshl_b64 s[4:5], s[0:1], 12
	v_lshl_add_u64 v[52:53], v[18:19], 0, s[4:5]
	global_store_dwordx4 v[82:83], v[64:67], off
	global_store_dwordx4 v[82:83], v[68:71], off offset:16
	global_store_dwordx4 v[82:83], v[72:75], off offset:2048
	global_store_dwordx4 v[82:83], v[76:79], off offset:2064
	s_waitcnt vmcnt(3)
	ds_bpermute_b32 v56, v24, v31
	s_waitcnt lgkmcnt(0)
	v_add_f32_e32 v31, v31, v56
	ds_bpermute_b32 v56, v25, v31
	s_waitcnt lgkmcnt(0)
	v_add_f32_e32 v31, v31, v56
	ds_bpermute_b32 v56, v26, v31
	s_waitcnt lgkmcnt(0)
	v_add_f32_e32 v31, v31, v56
	ds_bpermute_b32 v56, v27, v31
	s_waitcnt lgkmcnt(0)
	v_add_f32_e32 v31, v31, v56
	ds_bpermute_b32 v56, v28, v31
	s_waitcnt lgkmcnt(0)
	v_add_f32_e32 v31, v31, v56
	ds_bpermute_b32 v56, v29, v31
	s_waitcnt lgkmcnt(0)
	v_add_f32_e32 v31, v31, v56
	v_fmamk_f32 v31, v31, 0x3a800000, v30
	v_rsq_f32_e32 v80, v31
	v_mov_b32_e32 v81, v17
	v_lshlrev_b32_e32 v56, 16, v32
	v_and_b32_e32 v57, 0xffff0000, v32
	v_lshlrev_b32_e32 v58, 16, v33
	v_and_b32_e32 v59, 0xffff0000, v33
	v_lshlrev_b32_e32 v60, 16, v34
	v_and_b32_e32 v61, 0xffff0000, v34
	v_lshlrev_b32_e32 v62, 16, v35
	v_and_b32_e32 v63, 0xffff0000, v35
	v_pk_mul_f32 v[56:57], v[80:81], v[56:57] op_sel_hi:[0,1]
	v_pk_mul_f32 v[58:59], v[80:81], v[58:59] op_sel_hi:[0,1]
	v_pk_mul_f32 v[60:61], v[80:81], v[60:61] op_sel_hi:[0,1]
	v_pk_mul_f32 v[62:63], v[80:81], v[62:63] op_sel_hi:[0,1]
	v_pk_mul_f32 v[64:65], v[4:5], v[56:57]
	v_pk_mul_f32 v[66:67], v[6:7], v[58:59]
	v_pk_mul_f32 v[68:69], v[0:1], v[60:61]
	v_pk_mul_f32 v[70:71], v[2:3], v[62:63]
	v_lshlrev_b32_e32 v56, 16, v36
	v_and_b32_e32 v57, 0xffff0000, v36
	v_lshlrev_b32_e32 v58, 16, v37
	v_and_b32_e32 v59, 0xffff0000, v37
	v_lshlrev_b32_e32 v60, 16, v38
	v_and_b32_e32 v61, 0xffff0000, v38
	v_lshlrev_b32_e32 v62, 16, v39
	v_and_b32_e32 v63, 0xffff0000, v39
	v_pk_mul_f32 v[56:57], v[80:81], v[56:57] op_sel_hi:[0,1]
	v_pk_mul_f32 v[58:59], v[80:81], v[58:59] op_sel_hi:[0,1]
	v_pk_mul_f32 v[60:61], v[80:81], v[60:61] op_sel_hi:[0,1]
	v_pk_mul_f32 v[62:63], v[80:81], v[62:63] op_sel_hi:[0,1]
	v_pk_mul_f32 v[72:73], v[12:13], v[56:57]
	v_pk_mul_f32 v[74:75], v[14:15], v[58:59]
	v_pk_mul_f32 v[76:77], v[8:9], v[60:61]
	v_pk_mul_f32 v[78:79], v[10:11], v[62:63]
	v_mov_b64_e32 v[82:83], v[40:41]
	s_ashr_i32 s1, s3, 3
	s_and_b32 s0, s7, 0x7000
	s_and_b32 s1, s1, -8
	s_add_i32 s0, s0, s1
	s_or_b32 s0, s0, s6
	s_ashr_i32 s1, s0, 31
	s_add_i32 s3, s3, s2
	s_add_i32 s7, s7, s8
	v_mov_b32_e32 v31, 0
	s_and_saveexec_b64 s[4:5], vcc
	v_lshl_add_u64 v[54:55], s[0:1], 0, v[16:17]
	v_lshl_add_u64 v[54:55], v[54:55], 4, v[20:21]
	global_load_dword v31, v[54:55], off
	s_or_b64 exec, exec, s[4:5]
	s_lshl_b64 s[4:5], s[0:1], 11
	v_lshl_add_u64 v[54:55], v[22:23], 0, s[4:5]
	global_load_dwordx4 v[32:35], v[54:55], off
	global_load_dwordx4 v[36:39], v[54:55], off offset:1024
	s_lshl_b64 s[4:5], s[0:1], 12
	v_lshl_add_u64 v[40:41], v[18:19], 0, s[4:5]
	global_store_dwordx4 v[82:83], v[64:67], off
	global_store_dwordx4 v[82:83], v[68:71], off offset:16
	global_store_dwordx4 v[82:83], v[72:75], off offset:2048
	global_store_dwordx4 v[82:83], v[76:79], off offset:2064
	s_waitcnt vmcnt(3)
; __device__ __forceinline__ float bflo(unsigned w) { return __uint_as_float(w << 16); }
; __device__ __forceinline__ float bfhi(unsigned w) { return __uint_as_float(w & 0xffff0000u); }
; #define ssq ((float*)(WSPTR() + WS_SSQ))
; __device__ __forceinline__ void final_norm(const Args& a, int G, int vb) {
;     ...
;     for (int mi = gw; mi < NT; mi += NGW) {
;         const int m = XCD_ROW(mi);
;         float s = (lane < 16) ? ssq[((size_t)(lane >> 2) * NT + m) * 4 + (lane & 3)] : 0.f; s = wave_sum(s);
;         const float rs = __builtin_amdgcn_rsqf(s * (1.0f / 1024.0f) + 1e-6f);
;         const u32x4* xr = (const u32x4*)(xb + (size_t)m * DM) + lane; f32x4* orow = (f32x4*)(out + (size_t)m * DM) + 2 * lane;
; #pragma unroll
;         for (int j = 0; j < 2; ++j) { const u32x4 w = xr[64 * j];
;             orow[128 * j] = (f32x4){bflo(w.x), bfhi(w.x), bflo(w.y), bfhi(w.y)} * rs * gv[j][0];
;             orow[128 * j + 1] = (f32x4){bflo(w.z), bfhi(w.z), bflo(w.w), bfhi(w.w)} * rs * gv[j][1]; }
;     }
	ds_bpermute_b32 v56, v24, v42
	s_waitcnt lgkmcnt(0)
	v_add_f32_e32 v42, v42, v56
	ds_bpermute_b32 v56, v25, v42
	s_waitcnt lgkmcnt(0)
	v_add_f32_e32 v42, v42, v56
	ds_bpermute_b32 v56, v26, v42
	s_waitcnt lgkmcnt(0)
	v_add_f32_e32 v42, v42, v56
	ds_bpermute_b32 v56, v27, v42
	s_waitcnt lgkmcnt(0)
	v_add_f32_e32 v42, v42, v56
	ds_bpermute_b32 v56, v28, v42
	s_waitcnt lgkmcnt(0)
	v_add_f32_e32 v42, v42, v56
	ds_bpermute_b32 v56, v29, v42
	s_waitcnt lgkmcnt(0)
	v_add_f32_e32 v42, v42, v56
	v_fmamk_f32 v42, v42, 0x3a800000, v30
	v_rsq_f32_e32 v80, v42
	v_mov_b32_e32 v81, v17
	v_lshlrev_b32_e32 v56, 16, v44
	v_and_b32_e32 v57, 0xffff0000, v44
	v_lshlrev_b32_e32 v58, 16, v45
	v_and_b32_e32 v59, 0xffff0000, v45
	v_lshlrev_b32_e32 v60, 16, v46
	v_and_b32_e32 v61, 0xffff0000, v46
	v_lshlrev_b32_e32 v62, 16, v47
	v_and_b32_e32 v63, 0xffff0000, v47
	v_pk_mul_f32 v[56:57], v[80:81], v[56:57] op_sel_hi:[0,1]
	v_pk_mul_f32 v[58:59], v[80:81], v[58:59] op_sel_hi:[0,1]
	v_pk_mul_f32 v[60:61], v[80:81], v[60:61] op_sel_hi:[0,1]
	v_pk_mul_f32 v[62:63], v[80:81], v[62:63] op_sel_hi:[0,1]
	v_pk_mul_f32 v[64:65], v[4:5], v[56:57]
	v_pk_mul_f32 v[66:67], v[6:7], v[58:59]
	v_pk_mul_f32 v[68:69], v[0:1], v[60:61]
	v_pk_mul_f32 v[70:71], v[2:3], v[62:63]
	v_lshlrev_b32_e32 v56, 16, v48
	v_and_b32_e32 v57, 0xffff0000, v48
	v_lshlrev_b32_e32 v58, 16, v49
	v_and_b32_e32 v59, 0xffff0000, v49
	v_lshlrev_b32_e32 v60, 16, v50
	v_and_b32_e32 v61, 0xffff0000, v50
	v_lshlrev_b32_e32 v62, 16, v51
	v_and_b32_e32 v63, 0xffff0000, v51
	v_pk_mul_f32 v[56:57], v[80:81], v[56:57] op_sel_hi:[0,1]
	v_pk_mul_f32 v[58:59], v[80:81], v[58:59] op_sel_hi:[0,1]
	v_pk_mul_f32 v[60:61], v[80:81], v[60:61] op_sel_hi:[0,1]
	v_pk_mul_f32 v[62:63], v[80:81], v[62:63] op_sel_hi:[0,1]
	v_pk_mul_f32 v[72:73], v[12:13], v[56:57]
	v_pk_mul_f32 v[74:75], v[14:15], v[58:59]
	v_pk_mul_f32 v[76:77], v[8:9], v[60:61]
	v_pk_mul_f32 v[78:79], v[10:11], v[62:63]
	v_mov_b64_e32 v[82:83], v[52:53]
	s_ashr_i32 s1, s3, 3
	s_and_b32 s0, s7, 0x7000
	s_and_b32 s1, s1, -8
	s_add_i32 s0, s0, s1
	s_or_b32 s0, s0, s6
	s_ashr_i32 s1, s0, 31
	s_add_i32 s3, s3, s2
	s_add_i32 s7, s7, s8
	v_mov_b32_e32 v42, 0
	s_and_saveexec_b64 s[4:5], vcc
	v_lshl_add_u64 v[54:55], s[0:1], 0, v[16:17]
	v_lshl_add_u64 v[54:55], v[54:55], 4, v[20:21]
	global_load_dword v42, v[54:55], off
	s_or_b64 exec, exec, s[4:5]
	s_lshl_b64 s[4:5], s[0:1], 11
	v_lshl_add_u64 v[54:55], v[22:23], 0, s[4:5]
	global_load_dwordx4 v[44:47], v[54:55], off
	global_load_dwordx4 v[48:51], v[54:55], off offset:1024
	s_lshl_b64 s[4:5], s[0:1], 12
	v_lshl_add_u64 v[52:53], v[18:19], 0, s[4:5]
	global_store_dwordx4 v[82:83], v[64:67], off
	global_store_dwordx4 v[82:83], v[68:71], off offset:16
	global_store_dwordx4 v[82:83], v[72:75], off offset:2048
	global_store_dwordx4 v[82:83], v[76:79], off offset:2064
	s_waitcnt vmcnt(3)
	ds_bpermute_b32 v56, v24, v31
	s_waitcnt lgkmcnt(0)
	v_add_f32_e32 v31, v31, v56
	ds_bpermute_b32 v56, v25, v31
	s_waitcnt lgkmcnt(0)
	v_add_f32_e32 v31, v31, v56
	ds_bpermute_b32 v56, v26, v31
	s_waitcnt lgkmcnt(0)
	v_add_f32_e32 v31, v31, v56
	ds_bpermute_b32 v56, v27, v31
	s_waitcnt lgkmcnt(0)
	v_add_f32_e32 v31, v31, v56
	ds_bpermute_b32 v56, v28, v31
	s_waitcnt lgkmcnt(0)
	v_add_f32_e32 v31, v31, v56
	ds_bpermute_b32 v56, v29, v31
	s_waitcnt lgkmcnt(0)
; __device__ __forceinline__ float bflo(unsigned w) { return __uint_as_float(w << 16); }
; __device__ __forceinline__ float bfhi(unsigned w) { return __uint_as_float(w & 0xffff0000u); }
; #define ssq ((float*)(WSPTR() + WS_SSQ))
; __device__ __forceinline__ void final_norm(const Args& a, int G, int vb) {
;     ...
;     for (int mi = gw; mi < NT; mi += NGW) {
;         const int m = XCD_ROW(mi);
;         float s = (lane < 16) ? ssq[((size_t)(lane >> 2) * NT + m) * 4 + (lane & 3)] : 0.f; s = wave_sum(s);
;         const float rs = __builtin_amdgcn_rsqf(s * (1.0f / 1024.0f) + 1e-6f);
;         const u32x4* xr = (const u32x4*)(xb + (size_t)m * DM) + lane; f32x4* orow = (f32x4*)(out + (size_t)m * DM) + 2 * lane;
; #pragma unroll
;         for (int j = 0; j < 2; ++j) { const u32x4 w = xr[64 * j];
;             orow[128 * j] = (f32x4){bflo(w.x), bfhi(w.x), bflo(w.y), bfhi(w.y)} * rs * gv[j][0];
;             orow[128 * j + 1] = (f32x4){bflo(w.z), bfhi(w.z), bflo(w.w), bfhi(w.w)} * rs * gv[j][1]; }
;     }
	v_add_f32_e32 v31, v31, v56
	v_fmamk_f32 v31, v31, 0x3a800000, v30
	v_rsq_f32_e32 v80, v31
	v_mov_b32_e32 v81, v17
	v_lshlrev_b32_e32 v56, 16, v32
	v_and_b32_e32 v57, 0xffff0000, v32
	v_lshlrev_b32_e32 v58, 16, v33
	v_and_b32_e32 v59, 0xffff0000, v33
	v_lshlrev_b32_e32 v60, 16, v34
	v_and_b32_e32 v61, 0xffff0000, v34
	v_lshlrev_b32_e32 v62, 16, v35
	v_and_b32_e32 v63, 0xffff0000, v35
	v_pk_mul_f32 v[56:57], v[80:81], v[56:57] op_sel_hi:[0,1]
	v_pk_mul_f32 v[58:59], v[80:81], v[58:59] op_sel_hi:[0,1]
	v_pk_mul_f32 v[60:61], v[80:81], v[60:61] op_sel_hi:[0,1]
	v_pk_mul_f32 v[62:63], v[80:81], v[62:63] op_sel_hi:[0,1]
	v_pk_mul_f32 v[64:65], v[4:5], v[56:57]
	v_pk_mul_f32 v[66:67], v[6:7], v[58:59]
	v_pk_mul_f32 v[68:69], v[0:1], v[60:61]
	v_pk_mul_f32 v[70:71], v[2:3], v[62:63]
	v_lshlrev_b32_e32 v56, 16, v36
	v_and_b32_e32 v57, 0xffff0000, v36
	v_lshlrev_b32_e32 v58, 16, v37
	v_and_b32_e32 v59, 0xffff0000, v37
	v_lshlrev_b32_e32 v60, 16, v38
	v_and_b32_e32 v61, 0xffff0000, v38
	v_lshlrev_b32_e32 v62, 16, v39
	v_and_b32_e32 v63, 0xffff0000, v39
	v_pk_mul_f32 v[56:57], v[80:81], v[56:57] op_sel_hi:[0,1]
	v_pk_mul_f32 v[58:59], v[80:81], v[58:59] op_sel_hi:[0,1]
	v_pk_mul_f32 v[60:61], v[80:81], v[60:61] op_sel_hi:[0,1]
	v_pk_mul_f32 v[62:63], v[80:81], v[62:63] op_sel_hi:[0,1]
	v_pk_mul_f32 v[72:73], v[12:13], v[56:57]
	v_pk_mul_f32 v[74:75], v[14:15], v[58:59]
	v_pk_mul_f32 v[76:77], v[8:9], v[60:61]
	v_pk_mul_f32 v[78:79], v[10:11], v[62:63]
	v_mov_b64_e32 v[82:83], v[40:41]
	global_store_dwordx4 v[82:83], v[64:67], off
	global_store_dwordx4 v[82:83], v[68:71], off offset:16
	global_store_dwordx4 v[82:83], v[72:75], off offset:2048
	global_store_dwordx4 v[82:83], v[76:79], off offset:2064
	s_waitcnt vmcnt(0)
	ds_bpermute_b32 v56, v24, v42
	s_waitcnt lgkmcnt(0)
	v_add_f32_e32 v42, v42, v56
	ds_bpermute_b32 v56, v25, v42
	s_waitcnt lgkmcnt(0)
	v_add_f32_e32 v42, v42, v56
	ds_bpermute_b32 v56, v26, v42
	s_waitcnt lgkmcnt(0)
	v_add_f32_e32 v42, v42, v56
	ds_bpermute_b32 v56, v27, v42
	s_waitcnt lgkmcnt(0)
	v_add_f32_e32 v42, v42, v56
	ds_bpermute_b32 v56, v28, v42
	s_waitcnt lgkmcnt(0)
	v_add_f32_e32 v42, v42, v56
	ds_bpermute_b32 v56, v29, v42
	s_waitcnt lgkmcnt(0)
	v_add_f32_e32 v42, v42, v56
	v_fmamk_f32 v42, v42, 0x3a800000, v30
	v_rsq_f32_e32 v80, v42
	v_mov_b32_e32 v81, v17
	v_lshlrev_b32_e32 v56, 16, v44
	v_and_b32_e32 v57, 0xffff0000, v44
	v_lshlrev_b32_e32 v58, 16, v45
	v_and_b32_e32 v59, 0xffff0000, v45
	v_lshlrev_b32_e32 v60, 16, v46
	v_and_b32_e32 v61, 0xffff0000, v46
	v_lshlrev_b32_e32 v62, 16, v47
	v_and_b32_e32 v63, 0xffff0000, v47
	v_pk_mul_f32 v[56:57], v[80:81], v[56:57] op_sel_hi:[0,1]
	v_pk_mul_f32 v[58:59], v[80:81], v[58:59] op_sel_hi:[0,1]
	v_pk_mul_f32 v[60:61], v[80:81], v[60:61] op_sel_hi:[0,1]
	v_pk_mul_f32 v[62:63], v[80:81], v[62:63] op_sel_hi:[0,1]
	v_pk_mul_f32 v[64:65], v[4:5], v[56:57]
	v_pk_mul_f32 v[66:67], v[6:7], v[58:59]
	v_pk_mul_f32 v[68:69], v[0:1], v[60:61]
	v_pk_mul_f32 v[70:71], v[2:3], v[62:63]
	v_lshlrev_b32_e32 v56, 16, v48
	v_and_b32_e32 v57, 0xffff0000, v48
	v_lshlrev_b32_e32 v58, 16, v49
	v_and_b32_e32 v59, 0xffff0000, v49
	v_lshlrev_b32_e32 v60, 16, v50
	v_and_b32_e32 v61, 0xffff0000, v50
	v_lshlrev_b32_e32 v62, 16, v51
	v_and_b32_e32 v63, 0xffff0000, v51
	v_pk_mul_f32 v[56:57], v[80:81], v[56:57] op_sel_hi:[0,1]
	v_pk_mul_f32 v[58:59], v[80:81], v[58:59] op_sel_hi:[0,1]
	v_pk_mul_f32 v[60:61], v[80:81], v[60:61] op_sel_hi:[0,1]
	v_pk_mul_f32 v[62:63], v[80:81], v[62:63] op_sel_hi:[0,1]
	v_pk_mul_f32 v[72:73], v[12:13], v[56:57]
	v_pk_mul_f32 v[74:75], v[14:15], v[58:59]
	v_pk_mul_f32 v[76:77], v[8:9], v[60:61]
	v_pk_mul_f32 v[78:79], v[10:11], v[62:63]
	v_mov_b64_e32 v[82:83], v[52:53]
	global_store_dwordx4 v[82:83], v[64:67], off
	global_store_dwordx4 v[82:83], v[68:71], off offset:16
	global_store_dwordx4 v[82:83], v[72:75], off offset:2048
	global_store_dwordx4 v[82:83], v[76:79], off offset:2064
	s_branch .LBB0_831
	s_branch .LBB0_829
